# v15 + SwiGLU epilogues re-emitted with packed f32 VALU (v_pk_mul/v_pk_add in place in the accumulator quads, same operations and rounding)
# speedup vs baseline: 1.0032x; 1.0032x over previous
.LBB0_274:
	ds_read_b128 v[146:149], v153
	ds_read_b128 v[156:159], v153 offset:1024
	ds_read_b128 v[160:163], v153 offset:2048
	ds_read_b128 v[164:167], v153 offset:3072
	ds_read_b128 v[168:171], v154
	ds_read_b128 v[172:175], v154 offset:1024
	ds_read_b128 v[176:179], v154 offset:2048
	ds_read_b128 v[180:183], v154 offset:3072
	s_add_u32 s34, s76, 0xfff80080
	s_addc_u32 s35, s77, -1
	s_cmp_eq_u32 s85, 28
	s_cselect_b32 s79, s0, s35
	s_cselect_b32 s78, s1, s34
	s_cselect_b32 s35, s67, s84
	s_cselect_b32 s34, s69, s83
	v_lshl_add_u64 v[218:219], s[76:77], 0, v[138:139]
	s_add_i32 m0, s54, 0xc000
	ds_read_b128 v[184:187], v155
	ds_read_b128 v[188:191], v155 offset:1024
	ds_read_b128 v[192:195], v155 offset:2048
	ds_read_b128 v[196:199], v155 offset:3072
	ds_read_b128 v[200:203], v155 offset:4096
	ds_read_b128 v[204:207], v155 offset:5120
	ds_read_b128 v[208:211], v155 offset:6144
	ds_read_b128 v[212:215], v155 offset:7168
	global_load_lds_dwordx4 v[218:219], off
	v_lshl_add_u64 v[218:219], s[76:77], 0, v[140:141]
	s_add_i32 m0, s54, 0xe000
	s_nop 0
	global_load_lds_dwordx4 v[218:219], off
	s_waitcnt vmcnt(8)
	s_waitcnt lgkmcnt(0)
	s_barrier
	s_setprio 1
	s_waitcnt lgkmcnt(0)
	v_mfma_f32_16x16x32_bf16 v[126:129], v[146:149], v[184:187], v[126:129]
	v_mfma_f32_16x16x32_bf16 v[118:121], v[160:163], v[184:187], v[118:121]
	v_mfma_f32_16x16x32_bf16 v[110:113], v[146:149], v[192:195], v[110:113]
	v_mfma_f32_16x16x32_bf16 v[102:105], v[160:163], v[192:195], v[102:105]
	v_mfma_f32_16x16x32_bf16 v[94:97], v[146:149], v[200:203], v[94:97]
	v_mfma_f32_16x16x32_bf16 v[86:89], v[160:163], v[200:203], v[86:89]
	v_mfma_f32_16x16x32_bf16 v[78:81], v[146:149], v[208:211], v[78:81]
	v_mfma_f32_16x16x32_bf16 v[70:73], v[160:163], v[208:211], v[70:73]
	v_mfma_f32_16x16x32_bf16 v[126:129], v[156:159], v[188:191], v[126:129]
	v_mfma_f32_16x16x32_bf16 v[118:121], v[164:167], v[188:191], v[118:121]
	v_mfma_f32_16x16x32_bf16 v[110:113], v[156:159], v[196:199], v[110:113]
	v_mfma_f32_16x16x32_bf16 v[102:105], v[164:167], v[196:199], v[102:105]
	v_mfma_f32_16x16x32_bf16 v[94:97], v[156:159], v[204:207], v[94:97]
	v_mfma_f32_16x16x32_bf16 v[86:89], v[164:167], v[204:207], v[86:89]
	v_mfma_f32_16x16x32_bf16 v[78:81], v[156:159], v[212:215], v[78:81]
	v_mfma_f32_16x16x32_bf16 v[70:73], v[164:167], v[212:215], v[70:73]
	s_setprio 0
	s_setprio 1
	v_mfma_f32_16x16x32_bf16 v[122:125], v[168:171], v[184:187], v[122:125]
	v_mfma_f32_16x16x32_bf16 v[114:117], v[176:179], v[184:187], v[114:117]
	v_mfma_f32_16x16x32_bf16 v[106:109], v[168:171], v[192:195], v[106:109]
	v_mfma_f32_16x16x32_bf16 v[98:101], v[176:179], v[192:195], v[98:101]
	v_mfma_f32_16x16x32_bf16 v[90:93], v[168:171], v[200:203], v[90:93]
	v_mfma_f32_16x16x32_bf16 v[82:85], v[176:179], v[200:203], v[82:85]
	v_mfma_f32_16x16x32_bf16 v[74:77], v[168:171], v[208:211], v[74:77]
	v_mfma_f32_16x16x32_bf16 v[66:69], v[176:179], v[208:211], v[66:69]
	v_mfma_f32_16x16x32_bf16 v[122:125], v[172:175], v[188:191], v[122:125]
	v_mfma_f32_16x16x32_bf16 v[114:117], v[180:183], v[188:191], v[114:117]
	v_mfma_f32_16x16x32_bf16 v[106:109], v[172:175], v[196:199], v[106:109]
	v_mfma_f32_16x16x32_bf16 v[98:101], v[180:183], v[196:199], v[98:101]
	v_mfma_f32_16x16x32_bf16 v[90:93], v[172:175], v[204:207], v[90:93]
	v_mfma_f32_16x16x32_bf16 v[82:85], v[180:183], v[204:207], v[82:85]
	v_mfma_f32_16x16x32_bf16 v[74:77], v[172:175], v[212:215], v[74:77]
	v_mfma_f32_16x16x32_bf16 v[66:69], v[180:183], v[212:215], v[66:69]
	s_setprio 0
	s_barrier
	s_add_i32 s62, s75, s33
	v_lshl_add_u64 v[218:219], s[34:35], 0, v[134:135]
	s_mov_b32 m0, s62
	ds_read_b128 v[184:187], v155 offset:16384
	ds_read_b128 v[188:191], v155 offset:17408
	ds_read_b128 v[192:195], v155 offset:18432
	ds_read_b128 v[196:199], v155 offset:19456
	ds_read_b128 v[200:203], v155 offset:20480
	ds_read_b128 v[204:207], v155 offset:21504
	ds_read_b128 v[208:211], v155 offset:22528
	ds_read_b128 v[212:215], v155 offset:23552
	global_load_lds_dwordx4 v[218:219], off
	s_add_i32 m0, s62, 0x2000
	s_add_u32 s62, s34, 0x80000
	v_lshl_add_u64 v[220:221], s[34:35], 0, v[130:131]
	s_addc_u32 s63, s35, 0
	s_add_i32 s86, s80, s33
	global_load_lds_dwordx4 v[220:221], off
	v_lshl_add_u64 v[222:223], s[62:63], 0, v[134:135]
	s_mov_b32 m0, s86
	v_lshl_add_u64 v[224:225], s[78:79], 0, v[132:133]
	global_load_lds_dwordx4 v[222:223], off
	v_lshl_add_u64 v[222:223], s[62:63], 0, v[130:131]
	s_add_i32 m0, s86, 0x2000
	s_nop 0
	global_load_lds_dwordx4 v[222:223], off
	v_lshl_add_u64 v[222:223], s[78:79], 0, v[136:137]
	s_mov_b32 m0, s54
	s_nop 0
	global_load_lds_dwordx4 v[222:223], off
	s_mov_b32 m0, s55
	s_nop 0
	global_load_lds_dwordx4 v[224:225], off
	s_waitcnt vmcnt(8)
	s_waitcnt lgkmcnt(0)
	s_barrier
	s_setprio 1
	s_waitcnt lgkmcnt(0)
	v_mfma_f32_16x16x32_bf16 v[62:65], v[146:149], v[184:187], v[62:65]
	v_mfma_f32_16x16x32_bf16 v[54:57], v[160:163], v[184:187], v[54:57]
	v_mfma_f32_16x16x32_bf16 v[46:49], v[146:149], v[192:195], v[46:49]
	v_mfma_f32_16x16x32_bf16 v[38:41], v[160:163], v[192:195], v[38:41]
	v_mfma_f32_16x16x32_bf16 v[30:33], v[146:149], v[200:203], v[30:33]
	v_mfma_f32_16x16x32_bf16 v[22:25], v[160:163], v[200:203], v[22:25]
	v_mfma_f32_16x16x32_bf16 v[14:17], v[146:149], v[208:211], v[14:17]
	v_mfma_f32_16x16x32_bf16 v[6:9], v[160:163], v[208:211], v[6:9]
	v_mfma_f32_16x16x32_bf16 v[62:65], v[156:159], v[188:191], v[62:65]
	v_mfma_f32_16x16x32_bf16 v[54:57], v[164:167], v[188:191], v[54:57]
	v_mfma_f32_16x16x32_bf16 v[46:49], v[156:159], v[196:199], v[46:49]
	v_mfma_f32_16x16x32_bf16 v[38:41], v[164:167], v[196:199], v[38:41]
	v_mfma_f32_16x16x32_bf16 v[30:33], v[156:159], v[204:207], v[30:33]
	v_mfma_f32_16x16x32_bf16 v[22:25], v[164:167], v[204:207], v[22:25]
	v_mfma_f32_16x16x32_bf16 v[14:17], v[156:159], v[212:215], v[14:17]
	v_mfma_f32_16x16x32_bf16 v[6:9], v[164:167], v[212:215], v[6:9]
	s_setprio 0
	s_setprio 1
	v_mfma_f32_16x16x32_bf16 v[58:61], v[168:171], v[184:187], v[58:61]
	v_mfma_f32_16x16x32_bf16 v[50:53], v[176:179], v[184:187], v[50:53]
	v_mfma_f32_16x16x32_bf16 v[42:45], v[168:171], v[192:195], v[42:45]
	v_mfma_f32_16x16x32_bf16 v[34:37], v[176:179], v[192:195], v[34:37]
	v_mfma_f32_16x16x32_bf16 v[26:29], v[168:171], v[200:203], v[26:29]
	v_mfma_f32_16x16x32_bf16 v[18:21], v[176:179], v[200:203], v[18:21]
	v_mfma_f32_16x16x32_bf16 v[10:13], v[168:171], v[208:211], v[10:13]
	v_mfma_f32_16x16x32_bf16 v[2:5], v[176:179], v[208:211], v[2:5]
	v_mfma_f32_16x16x32_bf16 v[58:61], v[172:175], v[188:191], v[58:61]
	v_mfma_f32_16x16x32_bf16 v[50:53], v[180:183], v[188:191], v[50:53]
	v_mfma_f32_16x16x32_bf16 v[42:45], v[172:175], v[196:199], v[42:45]
	v_mfma_f32_16x16x32_bf16 v[34:37], v[180:183], v[196:199], v[34:37]
	v_mfma_f32_16x16x32_bf16 v[26:29], v[172:175], v[204:207], v[26:29]
	v_mfma_f32_16x16x32_bf16 v[18:21], v[180:183], v[204:207], v[18:21]
	v_mfma_f32_16x16x32_bf16 v[10:13], v[172:175], v[212:215], v[10:13]
	v_mfma_f32_16x16x32_bf16 v[2:5], v[180:183], v[212:215], v[2:5]
	s_setprio 0
	s_barrier
	s_add_i32 s86, 0, 0x18000
	s_add_i32 s87, 0, 0x1c000
	v_add_u32_e32 v164, s86, v151
	v_add_u32_e32 v180, s87, v151
	ds_read_b128 v[146:149], v164
	ds_read_b128 v[156:159], v164 offset:1024
	ds_read_b128 v[160:163], v164 offset:2048
	ds_read_b128 v[164:167], v164 offset:3072
	ds_read_b128 v[168:171], v180
	ds_read_b128 v[172:175], v180 offset:1024
	ds_read_b128 v[176:179], v180 offset:2048
	ds_read_b128 v[180:183], v180 offset:3072
	s_add_u32 s62, s78, 0x80000
	s_addc_u32 s63, s79, 0
	s_mov_b32 m0, s56
	v_lshl_add_u64 v[226:227], s[62:63], 0, v[136:137]
	ds_read_b128 v[184:187], v155 offset:32768
	ds_read_b128 v[188:191], v155 offset:33792
	ds_read_b128 v[192:195], v155 offset:34816
	ds_read_b128 v[196:199], v155 offset:35840
	ds_read_b128 v[200:203], v155 offset:36864
	ds_read_b128 v[204:207], v155 offset:37888
	ds_read_b128 v[208:211], v155 offset:38912
	ds_read_b128 v[212:215], v155 offset:39936
	global_load_lds_dwordx4 v[226:227], off
	v_lshl_add_u64 v[226:227], s[62:63], 0, v[132:133]
	s_mov_b32 m0, s57
	s_nop 0
	global_load_lds_dwordx4 v[226:227], off
	s_waitcnt vmcnt(8)
	s_waitcnt lgkmcnt(0)
	s_barrier
	s_setprio 1
	s_waitcnt lgkmcnt(0)
	v_mfma_f32_16x16x32_bf16 v[126:129], v[146:149], v[184:187], v[126:129]
	v_mfma_f32_16x16x32_bf16 v[118:121], v[160:163], v[184:187], v[118:121]
	v_mfma_f32_16x16x32_bf16 v[110:113], v[146:149], v[192:195], v[110:113]
	v_mfma_f32_16x16x32_bf16 v[102:105], v[160:163], v[192:195], v[102:105]
	v_mfma_f32_16x16x32_bf16 v[94:97], v[146:149], v[200:203], v[94:97]
	v_mfma_f32_16x16x32_bf16 v[86:89], v[160:163], v[200:203], v[86:89]
	v_mfma_f32_16x16x32_bf16 v[78:81], v[146:149], v[208:211], v[78:81]
	v_mfma_f32_16x16x32_bf16 v[70:73], v[160:163], v[208:211], v[70:73]
	v_mfma_f32_16x16x32_bf16 v[126:129], v[156:159], v[188:191], v[126:129]
	v_mfma_f32_16x16x32_bf16 v[118:121], v[164:167], v[188:191], v[118:121]
	v_mfma_f32_16x16x32_bf16 v[110:113], v[156:159], v[196:199], v[110:113]
	v_mfma_f32_16x16x32_bf16 v[102:105], v[164:167], v[196:199], v[102:105]
	v_mfma_f32_16x16x32_bf16 v[94:97], v[156:159], v[204:207], v[94:97]
	v_mfma_f32_16x16x32_bf16 v[86:89], v[164:167], v[204:207], v[86:89]
	v_mfma_f32_16x16x32_bf16 v[78:81], v[156:159], v[212:215], v[78:81]
	v_mfma_f32_16x16x32_bf16 v[70:73], v[164:167], v[212:215], v[70:73]
	s_setprio 0
	s_setprio 1
	v_mfma_f32_16x16x32_bf16 v[122:125], v[168:171], v[184:187], v[122:125]
	v_mfma_f32_16x16x32_bf16 v[114:117], v[176:179], v[184:187], v[114:117]
	v_mfma_f32_16x16x32_bf16 v[106:109], v[168:171], v[192:195], v[106:109]
	v_mfma_f32_16x16x32_bf16 v[98:101], v[176:179], v[192:195], v[98:101]
	v_mfma_f32_16x16x32_bf16 v[90:93], v[168:171], v[200:203], v[90:93]
	v_mfma_f32_16x16x32_bf16 v[82:85], v[176:179], v[200:203], v[82:85]
	v_mfma_f32_16x16x32_bf16 v[74:77], v[168:171], v[208:211], v[74:77]
	v_mfma_f32_16x16x32_bf16 v[66:69], v[176:179], v[208:211], v[66:69]
	v_mfma_f32_16x16x32_bf16 v[122:125], v[172:175], v[188:191], v[122:125]
	v_mfma_f32_16x16x32_bf16 v[114:117], v[180:183], v[188:191], v[114:117]
	v_mfma_f32_16x16x32_bf16 v[106:109], v[172:175], v[196:199], v[106:109]
	v_mfma_f32_16x16x32_bf16 v[98:101], v[180:183], v[196:199], v[98:101]
	v_mfma_f32_16x16x32_bf16 v[90:93], v[172:175], v[204:207], v[90:93]
	v_mfma_f32_16x16x32_bf16 v[82:85], v[180:183], v[204:207], v[82:85]
	v_mfma_f32_16x16x32_bf16 v[74:77], v[172:175], v[212:215], v[74:77]
	v_mfma_f32_16x16x32_bf16 v[66:69], v[180:183], v[212:215], v[66:69]
	s_setprio 0
	s_barrier
	s_add_i32 s62, s86, s33
	v_lshl_add_u64 v[218:219], v[218:219], 0, s[8:9]
	s_mov_b32 m0, s62
	ds_read_b128 v[184:187], v155 offset:49152
	ds_read_b128 v[188:191], v155 offset:50176
	ds_read_b128 v[192:195], v155 offset:51200
	ds_read_b128 v[196:199], v155 offset:52224
	ds_read_b128 v[200:203], v155 offset:53248
	ds_read_b128 v[204:207], v155 offset:54272
	ds_read_b128 v[208:211], v155 offset:55296
	ds_read_b128 v[212:215], v155 offset:56320
	global_load_lds_dwordx4 v[218:219], off
	s_add_i32 m0, s62, 0x2000
	s_add_u32 s34, s34, 0x80080
	v_lshl_add_u64 v[218:219], v[220:221], 0, s[8:9]
	s_addc_u32 s35, s35, 0
	s_add_i32 s62, s87, s33
	global_load_lds_dwordx4 v[218:219], off
	v_lshl_add_u64 v[218:219], s[34:35], 0, v[134:135]
	s_mov_b32 m0, s62
	s_nop 0
	global_load_lds_dwordx4 v[218:219], off
	v_lshl_add_u64 v[218:219], s[34:35], 0, v[130:131]
	s_add_i32 m0, s62, 0x2000
	s_nop 0
	global_load_lds_dwordx4 v[218:219], off
	v_lshl_add_u64 v[218:219], v[222:223], 0, s[8:9]
	s_mov_b32 m0, s59
	s_nop 0
	global_load_lds_dwordx4 v[218:219], off
	v_lshl_add_u64 v[218:219], v[224:225], 0, s[8:9]
	s_mov_b32 m0, s60
	s_nop 0
	global_load_lds_dwordx4 v[218:219], off
	s_waitcnt vmcnt(8)
	s_waitcnt lgkmcnt(0)
	s_barrier
	s_setprio 1
	s_waitcnt lgkmcnt(0)
	v_mfma_f32_16x16x32_bf16 v[62:65], v[146:149], v[184:187], v[62:65]
	v_mfma_f32_16x16x32_bf16 v[54:57], v[160:163], v[184:187], v[54:57]
	v_mfma_f32_16x16x32_bf16 v[46:49], v[146:149], v[192:195], v[46:49]
	v_mfma_f32_16x16x32_bf16 v[38:41], v[160:163], v[192:195], v[38:41]
	v_mfma_f32_16x16x32_bf16 v[30:33], v[146:149], v[200:203], v[30:33]
	v_mfma_f32_16x16x32_bf16 v[22:25], v[160:163], v[200:203], v[22:25]
	v_mfma_f32_16x16x32_bf16 v[14:17], v[146:149], v[208:211], v[14:17]
	v_mfma_f32_16x16x32_bf16 v[6:9], v[160:163], v[208:211], v[6:9]
	v_mfma_f32_16x16x32_bf16 v[62:65], v[156:159], v[188:191], v[62:65]
	v_mfma_f32_16x16x32_bf16 v[54:57], v[164:167], v[188:191], v[54:57]
	v_mfma_f32_16x16x32_bf16 v[46:49], v[156:159], v[196:199], v[46:49]
	v_mfma_f32_16x16x32_bf16 v[38:41], v[164:167], v[196:199], v[38:41]
	v_mfma_f32_16x16x32_bf16 v[30:33], v[156:159], v[204:207], v[30:33]
	v_mfma_f32_16x16x32_bf16 v[22:25], v[164:167], v[204:207], v[22:25]
	v_mfma_f32_16x16x32_bf16 v[14:17], v[156:159], v[212:215], v[14:17]
	v_mfma_f32_16x16x32_bf16 v[6:9], v[164:167], v[212:215], v[6:9]
	s_setprio 0
	s_setprio 1
	v_mfma_f32_16x16x32_bf16 v[58:61], v[168:171], v[184:187], v[58:61]
	v_mfma_f32_16x16x32_bf16 v[50:53], v[176:179], v[184:187], v[50:53]
	v_mfma_f32_16x16x32_bf16 v[42:45], v[168:171], v[192:195], v[42:45]
	v_mfma_f32_16x16x32_bf16 v[34:37], v[176:179], v[192:195], v[34:37]
	v_mfma_f32_16x16x32_bf16 v[26:29], v[168:171], v[200:203], v[26:29]
	v_mfma_f32_16x16x32_bf16 v[18:21], v[176:179], v[200:203], v[18:21]
	v_mfma_f32_16x16x32_bf16 v[10:13], v[168:171], v[208:211], v[10:13]
	v_mfma_f32_16x16x32_bf16 v[2:5], v[176:179], v[208:211], v[2:5]
	v_mfma_f32_16x16x32_bf16 v[58:61], v[172:175], v[188:191], v[58:61]
	v_mfma_f32_16x16x32_bf16 v[50:53], v[180:183], v[188:191], v[50:53]
	v_mfma_f32_16x16x32_bf16 v[42:45], v[172:175], v[196:199], v[42:45]
	v_mfma_f32_16x16x32_bf16 v[34:37], v[180:183], v[196:199], v[34:37]
	v_mfma_f32_16x16x32_bf16 v[26:29], v[172:175], v[204:207], v[26:29]
	v_mfma_f32_16x16x32_bf16 v[18:21], v[180:183], v[204:207], v[18:21]
	v_mfma_f32_16x16x32_bf16 v[10:13], v[172:175], v[212:215], v[10:13]
	v_mfma_f32_16x16x32_bf16 v[2:5], v[180:183], v[212:215], v[2:5]
	s_setprio 0
	s_barrier
	s_add_i32 s85, s85, 2
	s_add_u32 s76, s76, 0x100
	s_addc_u32 s77, s77, 0
	s_add_u32 s83, s83, 0x100
	s_addc_u32 s84, s84, 0
	s_cmp_gt_u32 s85, 29
	s_cbranch_scc0 .LBB0_274
	v_mov_b32_e32 v160, 0xbfb8aa3b
	s_and_b64 vcc, exec, s[64:65]
	s_cbranch_vccz .LBB0_277
	s_barrier
.LBB0_277:
	v_readlane_b32 s0, v247, 31
	v_lshl_or_b32 v146, s82, 7, v152
	v_readlane_b32 s1, v247, 32
	v_lshl_add_u32 v156, s74, 8, v1
	v_ashrrev_i32_e32 v147, 31, v146
	v_mov_b64_e32 v[148:149], s[0:1]
	v_mad_i64_i32 v[158:159], s[0:1], v156, s81, v[148:149]
	v_lshlrev_b64 v[146:147], 1, v[146:147]
	v_lshl_add_u64 v[158:159], v[158:159], 0, v[146:147]
	v_pk_mul_f32 v[122:123], v[126:127], v[122:123]
	v_pk_mul_f32 v[124:125], v[128:129], v[124:125]
	v_pk_mul_f32 v[114:115], v[118:119], v[114:115]
	v_pk_mul_f32 v[116:117], v[120:121], v[116:117]
	v_pk_mul_f32 v[126:127], v[126:127], v[160:161] op_sel_hi:[1,0]
	v_pk_mul_f32 v[128:129], v[128:129], v[160:161] op_sel_hi:[1,0]
	v_pk_mul_f32 v[118:119], v[118:119], v[160:161] op_sel_hi:[1,0]
	v_pk_mul_f32 v[120:121], v[120:121], v[160:161] op_sel_hi:[1,0]
	v_exp_f32_e32 v126, v126
	v_exp_f32_e32 v127, v127
	v_exp_f32_e32 v128, v128
	v_exp_f32_e32 v129, v129
	v_exp_f32_e32 v118, v118
	v_exp_f32_e32 v119, v119
	v_exp_f32_e32 v120, v120
	v_exp_f32_e32 v121, v121
	v_pk_add_f32 v[126:127], v[126:127], 1.0 op_sel_hi:[1,0]
	v_pk_add_f32 v[128:129], v[128:129], 1.0 op_sel_hi:[1,0]
	v_pk_add_f32 v[118:119], v[118:119], 1.0 op_sel_hi:[1,0]
	v_pk_add_f32 v[120:121], v[120:121], 1.0 op_sel_hi:[1,0]
	v_rcp_f32_e32 v126, v126
	v_rcp_f32_e32 v127, v127
	v_rcp_f32_e32 v128, v128
	v_rcp_f32_e32 v129, v129
	v_rcp_f32_e32 v118, v118
	v_rcp_f32_e32 v119, v119
	v_rcp_f32_e32 v120, v120
	v_rcp_f32_e32 v121, v121
	v_pk_mul_f32 v[122:123], v[126:127], v[122:123]
	v_pk_mul_f32 v[124:125], v[128:129], v[124:125]
	v_pk_mul_f32 v[114:115], v[118:119], v[114:115]
	v_pk_mul_f32 v[116:117], v[120:121], v[116:117]
	v_cvt_pk_bf16_f32 v122, v122, v123
	v_cvt_pk_bf16_f32 v123, v124, v125
	v_cvt_pk_bf16_f32 v124, v114, v115
	v_cvt_pk_bf16_f32 v125, v116, v117
	global_store_dwordx4 v[158:159], v[122:125], off
	v_or_b32_e32 v114, 16, v156
	v_mad_i64_i32 v[114:115], s[0:1], v114, s81, v[148:149]
	v_lshl_add_u64 v[114:115], v[114:115], 0, v[146:147]
	v_pk_mul_f32 v[106:107], v[110:111], v[106:107]
	v_pk_mul_f32 v[108:109], v[112:113], v[108:109]
	v_pk_mul_f32 v[98:99], v[102:103], v[98:99]
	v_pk_mul_f32 v[100:101], v[104:105], v[100:101]
	v_pk_mul_f32 v[110:111], v[110:111], v[160:161] op_sel_hi:[1,0]
	v_pk_mul_f32 v[112:113], v[112:113], v[160:161] op_sel_hi:[1,0]
	v_pk_mul_f32 v[102:103], v[102:103], v[160:161] op_sel_hi:[1,0]
	v_pk_mul_f32 v[104:105], v[104:105], v[160:161] op_sel_hi:[1,0]
	v_exp_f32_e32 v110, v110
	v_exp_f32_e32 v111, v111
	v_exp_f32_e32 v112, v112
	v_exp_f32_e32 v113, v113
	v_exp_f32_e32 v102, v102
	v_exp_f32_e32 v103, v103
	v_exp_f32_e32 v104, v104
	v_exp_f32_e32 v105, v105
	v_pk_add_f32 v[110:111], v[110:111], 1.0 op_sel_hi:[1,0]
	v_pk_add_f32 v[112:113], v[112:113], 1.0 op_sel_hi:[1,0]
	v_pk_add_f32 v[102:103], v[102:103], 1.0 op_sel_hi:[1,0]
	v_pk_add_f32 v[104:105], v[104:105], 1.0 op_sel_hi:[1,0]
	v_rcp_f32_e32 v110, v110
	v_rcp_f32_e32 v111, v111
	v_rcp_f32_e32 v112, v112
	v_rcp_f32_e32 v113, v113
	v_rcp_f32_e32 v102, v102
	v_rcp_f32_e32 v103, v103
	v_rcp_f32_e32 v104, v104
	v_rcp_f32_e32 v105, v105
	v_pk_mul_f32 v[106:107], v[110:111], v[106:107]
	v_pk_mul_f32 v[108:109], v[112:113], v[108:109]
	v_pk_mul_f32 v[98:99], v[102:103], v[98:99]
	v_pk_mul_f32 v[100:101], v[104:105], v[100:101]
	v_cvt_pk_bf16_f32 v106, v106, v107
	v_cvt_pk_bf16_f32 v107, v108, v109
	v_cvt_pk_bf16_f32 v108, v98, v99
	v_cvt_pk_bf16_f32 v109, v100, v101
	global_store_dwordx4 v[114:115], v[106:109], off
	v_or_b32_e32 v98, 32, v156
	v_mad_i64_i32 v[98:99], s[0:1], v98, s81, v[148:149]
	v_lshl_add_u64 v[98:99], v[98:99], 0, v[146:147]
	v_pk_mul_f32 v[90:91], v[94:95], v[90:91]
	v_pk_mul_f32 v[92:93], v[96:97], v[92:93]
	v_pk_mul_f32 v[82:83], v[86:87], v[82:83]
	v_pk_mul_f32 v[84:85], v[88:89], v[84:85]
	v_pk_mul_f32 v[94:95], v[94:95], v[160:161] op_sel_hi:[1,0]
	v_pk_mul_f32 v[96:97], v[96:97], v[160:161] op_sel_hi:[1,0]
	v_pk_mul_f32 v[86:87], v[86:87], v[160:161] op_sel_hi:[1,0]
	v_pk_mul_f32 v[88:89], v[88:89], v[160:161] op_sel_hi:[1,0]
	v_exp_f32_e32 v94, v94
	v_exp_f32_e32 v95, v95
	v_exp_f32_e32 v96, v96
	v_exp_f32_e32 v97, v97
	v_exp_f32_e32 v86, v86
	v_exp_f32_e32 v87, v87
	v_exp_f32_e32 v88, v88
	v_exp_f32_e32 v89, v89
	v_pk_add_f32 v[94:95], v[94:95], 1.0 op_sel_hi:[1,0]
	v_pk_add_f32 v[96:97], v[96:97], 1.0 op_sel_hi:[1,0]
	v_pk_add_f32 v[86:87], v[86:87], 1.0 op_sel_hi:[1,0]
	v_pk_add_f32 v[88:89], v[88:89], 1.0 op_sel_hi:[1,0]
	v_rcp_f32_e32 v94, v94
	v_rcp_f32_e32 v95, v95
	v_rcp_f32_e32 v96, v96
	v_rcp_f32_e32 v97, v97
	v_rcp_f32_e32 v86, v86
	v_rcp_f32_e32 v87, v87
	v_rcp_f32_e32 v88, v88
	v_rcp_f32_e32 v89, v89
	v_pk_mul_f32 v[90:91], v[94:95], v[90:91]
	v_pk_mul_f32 v[92:93], v[96:97], v[92:93]
	v_pk_mul_f32 v[82:83], v[86:87], v[82:83]
	v_pk_mul_f32 v[84:85], v[88:89], v[84:85]
	v_cvt_pk_bf16_f32 v90, v90, v91
	v_cvt_pk_bf16_f32 v91, v92, v93
	v_cvt_pk_bf16_f32 v92, v82, v83
	v_cvt_pk_bf16_f32 v93, v84, v85
	global_store_dwordx4 v[98:99], v[90:93], off
	v_or_b32_e32 v82, 48, v156
	v_mad_i64_i32 v[82:83], s[0:1], v82, s81, v[148:149]
	v_lshl_add_u64 v[82:83], v[82:83], 0, v[146:147]
	v_pk_mul_f32 v[74:75], v[78:79], v[74:75]
	v_pk_mul_f32 v[76:77], v[80:81], v[76:77]
	v_pk_mul_f32 v[66:67], v[70:71], v[66:67]
	v_pk_mul_f32 v[68:69], v[72:73], v[68:69]
	v_pk_mul_f32 v[78:79], v[78:79], v[160:161] op_sel_hi:[1,0]
	v_pk_mul_f32 v[80:81], v[80:81], v[160:161] op_sel_hi:[1,0]
	v_pk_mul_f32 v[70:71], v[70:71], v[160:161] op_sel_hi:[1,0]
	v_pk_mul_f32 v[72:73], v[72:73], v[160:161] op_sel_hi:[1,0]
	v_exp_f32_e32 v78, v78
	v_exp_f32_e32 v79, v79
	v_exp_f32_e32 v80, v80
	v_exp_f32_e32 v81, v81
	v_exp_f32_e32 v70, v70
	v_exp_f32_e32 v71, v71
	v_exp_f32_e32 v72, v72
	v_exp_f32_e32 v73, v73
	v_pk_add_f32 v[78:79], v[78:79], 1.0 op_sel_hi:[1,0]
	v_pk_add_f32 v[80:81], v[80:81], 1.0 op_sel_hi:[1,0]
	v_pk_add_f32 v[70:71], v[70:71], 1.0 op_sel_hi:[1,0]
	v_pk_add_f32 v[72:73], v[72:73], 1.0 op_sel_hi:[1,0]
	v_rcp_f32_e32 v78, v78
	v_rcp_f32_e32 v79, v79
	v_rcp_f32_e32 v80, v80
	v_rcp_f32_e32 v81, v81
	v_rcp_f32_e32 v70, v70
	v_rcp_f32_e32 v71, v71
	v_rcp_f32_e32 v72, v72
	v_rcp_f32_e32 v73, v73
	v_pk_mul_f32 v[74:75], v[78:79], v[74:75]
	v_pk_mul_f32 v[76:77], v[80:81], v[76:77]
	v_pk_mul_f32 v[66:67], v[70:71], v[66:67]
	v_pk_mul_f32 v[68:69], v[72:73], v[68:69]
	v_cvt_pk_bf16_f32 v74, v74, v75
	v_cvt_pk_bf16_f32 v75, v76, v77
	v_cvt_pk_bf16_f32 v76, v66, v67
	v_cvt_pk_bf16_f32 v77, v68, v69
	global_store_dwordx4 v[82:83], v[74:77], off
	v_add_u32_e32 v66, 0x80, v156
	v_mad_i64_i32 v[66:67], s[0:1], v66, s81, v[148:149]
	v_lshl_add_u64 v[66:67], v[66:67], 0, v[146:147]
	v_pk_mul_f32 v[58:59], v[62:63], v[58:59]
	v_pk_mul_f32 v[60:61], v[64:65], v[60:61]
	v_pk_mul_f32 v[50:51], v[54:55], v[50:51]
	v_pk_mul_f32 v[52:53], v[56:57], v[52:53]
	v_pk_mul_f32 v[62:63], v[62:63], v[160:161] op_sel_hi:[1,0]
	v_pk_mul_f32 v[64:65], v[64:65], v[160:161] op_sel_hi:[1,0]
	v_pk_mul_f32 v[54:55], v[54:55], v[160:161] op_sel_hi:[1,0]
	v_pk_mul_f32 v[56:57], v[56:57], v[160:161] op_sel_hi:[1,0]
	v_exp_f32_e32 v62, v62
	v_exp_f32_e32 v63, v63
	v_exp_f32_e32 v64, v64
	v_exp_f32_e32 v65, v65
	v_exp_f32_e32 v54, v54
	v_exp_f32_e32 v55, v55
	v_exp_f32_e32 v56, v56
	v_exp_f32_e32 v57, v57
	v_pk_add_f32 v[62:63], v[62:63], 1.0 op_sel_hi:[1,0]
	v_pk_add_f32 v[64:65], v[64:65], 1.0 op_sel_hi:[1,0]
	v_pk_add_f32 v[54:55], v[54:55], 1.0 op_sel_hi:[1,0]
	v_pk_add_f32 v[56:57], v[56:57], 1.0 op_sel_hi:[1,0]
	v_rcp_f32_e32 v62, v62
	v_rcp_f32_e32 v63, v63
	v_rcp_f32_e32 v64, v64
	v_rcp_f32_e32 v65, v65
	v_rcp_f32_e32 v54, v54
	v_rcp_f32_e32 v55, v55
	v_rcp_f32_e32 v56, v56
	v_rcp_f32_e32 v57, v57
	v_pk_mul_f32 v[58:59], v[62:63], v[58:59]
	v_pk_mul_f32 v[60:61], v[64:65], v[60:61]
	v_pk_mul_f32 v[50:51], v[54:55], v[50:51]
	v_pk_mul_f32 v[52:53], v[56:57], v[52:53]
	v_cvt_pk_bf16_f32 v58, v58, v59
	v_cvt_pk_bf16_f32 v59, v60, v61
	v_cvt_pk_bf16_f32 v60, v50, v51
	v_cvt_pk_bf16_f32 v61, v52, v53
	global_store_dwordx4 v[66:67], v[58:61], off
	v_add_u32_e32 v50, 0x90, v156
	v_mad_i64_i32 v[50:51], s[0:1], v50, s81, v[148:149]
	v_lshl_add_u64 v[50:51], v[50:51], 0, v[146:147]
	v_pk_mul_f32 v[42:43], v[46:47], v[42:43]
	v_pk_mul_f32 v[44:45], v[48:49], v[44:45]
	v_pk_mul_f32 v[34:35], v[38:39], v[34:35]
	v_pk_mul_f32 v[36:37], v[40:41], v[36:37]
	v_pk_mul_f32 v[46:47], v[46:47], v[160:161] op_sel_hi:[1,0]
	v_pk_mul_f32 v[48:49], v[48:49], v[160:161] op_sel_hi:[1,0]
	v_pk_mul_f32 v[38:39], v[38:39], v[160:161] op_sel_hi:[1,0]
	v_pk_mul_f32 v[40:41], v[40:41], v[160:161] op_sel_hi:[1,0]
	v_exp_f32_e32 v46, v46
	v_exp_f32_e32 v47, v47
	v_exp_f32_e32 v48, v48
	v_exp_f32_e32 v49, v49
	v_exp_f32_e32 v38, v38
	v_exp_f32_e32 v39, v39
	v_exp_f32_e32 v40, v40
	v_exp_f32_e32 v41, v41
	v_pk_add_f32 v[46:47], v[46:47], 1.0 op_sel_hi:[1,0]
	v_pk_add_f32 v[48:49], v[48:49], 1.0 op_sel_hi:[1,0]
	v_pk_add_f32 v[38:39], v[38:39], 1.0 op_sel_hi:[1,0]
	v_pk_add_f32 v[40:41], v[40:41], 1.0 op_sel_hi:[1,0]
	v_rcp_f32_e32 v46, v46
	v_rcp_f32_e32 v47, v47
	v_rcp_f32_e32 v48, v48
	v_rcp_f32_e32 v49, v49
	v_rcp_f32_e32 v38, v38
	v_rcp_f32_e32 v39, v39
	v_rcp_f32_e32 v40, v40
	v_rcp_f32_e32 v41, v41
	v_pk_mul_f32 v[42:43], v[46:47], v[42:43]
	v_pk_mul_f32 v[44:45], v[48:49], v[44:45]
	v_pk_mul_f32 v[34:35], v[38:39], v[34:35]
	v_pk_mul_f32 v[36:37], v[40:41], v[36:37]
	v_cvt_pk_bf16_f32 v42, v42, v43
	v_cvt_pk_bf16_f32 v43, v44, v45
	v_cvt_pk_bf16_f32 v44, v34, v35
	v_cvt_pk_bf16_f32 v45, v36, v37
	global_store_dwordx4 v[50:51], v[42:45], off
	v_add_u32_e32 v34, 0xa0, v156
	v_mad_i64_i32 v[34:35], s[0:1], v34, s81, v[148:149]
	v_lshl_add_u64 v[34:35], v[34:35], 0, v[146:147]
	v_pk_mul_f32 v[26:27], v[30:31], v[26:27]
	v_pk_mul_f32 v[28:29], v[32:33], v[28:29]
	v_pk_mul_f32 v[18:19], v[22:23], v[18:19]
	v_pk_mul_f32 v[20:21], v[24:25], v[20:21]
	v_pk_mul_f32 v[30:31], v[30:31], v[160:161] op_sel_hi:[1,0]
	v_pk_mul_f32 v[32:33], v[32:33], v[160:161] op_sel_hi:[1,0]
	v_pk_mul_f32 v[22:23], v[22:23], v[160:161] op_sel_hi:[1,0]
	v_pk_mul_f32 v[24:25], v[24:25], v[160:161] op_sel_hi:[1,0]
	v_exp_f32_e32 v30, v30
	v_exp_f32_e32 v31, v31
	v_exp_f32_e32 v32, v32
	v_exp_f32_e32 v33, v33
	v_exp_f32_e32 v22, v22
	v_exp_f32_e32 v23, v23
	v_exp_f32_e32 v24, v24
	v_exp_f32_e32 v25, v25
	v_pk_add_f32 v[30:31], v[30:31], 1.0 op_sel_hi:[1,0]
	v_pk_add_f32 v[32:33], v[32:33], 1.0 op_sel_hi:[1,0]
	v_pk_add_f32 v[22:23], v[22:23], 1.0 op_sel_hi:[1,0]
	v_pk_add_f32 v[24:25], v[24:25], 1.0 op_sel_hi:[1,0]
	v_rcp_f32_e32 v30, v30
	v_rcp_f32_e32 v31, v31
	v_rcp_f32_e32 v32, v32
	v_rcp_f32_e32 v33, v33
	v_rcp_f32_e32 v22, v22
	v_rcp_f32_e32 v23, v23
	v_rcp_f32_e32 v24, v24
	v_rcp_f32_e32 v25, v25
	v_pk_mul_f32 v[26:27], v[30:31], v[26:27]
	v_pk_mul_f32 v[28:29], v[32:33], v[28:29]
	v_pk_mul_f32 v[18:19], v[22:23], v[18:19]
	v_pk_mul_f32 v[20:21], v[24:25], v[20:21]
	v_cvt_pk_bf16_f32 v26, v26, v27
	v_cvt_pk_bf16_f32 v27, v28, v29
	v_cvt_pk_bf16_f32 v28, v18, v19
	v_cvt_pk_bf16_f32 v29, v20, v21
	global_store_dwordx4 v[34:35], v[26:29], off
	v_add_u32_e32 v18, 0xb0, v156
	v_mad_i64_i32 v[18:19], s[0:1], v18, s81, v[148:149]
	v_lshl_add_u64 v[18:19], v[18:19], 0, v[146:147]
	s_andn2_b64 vcc, exec, s[2:3]
	s_mov_b64 s[0:1], -1
	v_pk_mul_f32 v[10:11], v[14:15], v[10:11]
	v_pk_mul_f32 v[12:13], v[16:17], v[12:13]
	v_pk_mul_f32 v[2:3], v[6:7], v[2:3]
	v_pk_mul_f32 v[4:5], v[8:9], v[4:5]
	v_pk_mul_f32 v[14:15], v[14:15], v[160:161] op_sel_hi:[1,0]
	v_pk_mul_f32 v[16:17], v[16:17], v[160:161] op_sel_hi:[1,0]
	v_pk_mul_f32 v[6:7], v[6:7], v[160:161] op_sel_hi:[1,0]
	v_pk_mul_f32 v[8:9], v[8:9], v[160:161] op_sel_hi:[1,0]
	v_exp_f32_e32 v14, v14
	v_exp_f32_e32 v15, v15
	v_exp_f32_e32 v16, v16
	v_exp_f32_e32 v17, v17
	v_exp_f32_e32 v6, v6
	v_exp_f32_e32 v7, v7
	v_exp_f32_e32 v8, v8
	v_exp_f32_e32 v9, v9
	v_pk_add_f32 v[14:15], v[14:15], 1.0 op_sel_hi:[1,0]
	v_pk_add_f32 v[16:17], v[16:17], 1.0 op_sel_hi:[1,0]
	v_pk_add_f32 v[6:7], v[6:7], 1.0 op_sel_hi:[1,0]
	v_pk_add_f32 v[8:9], v[8:9], 1.0 op_sel_hi:[1,0]
	v_rcp_f32_e32 v14, v14
	v_rcp_f32_e32 v15, v15
	v_rcp_f32_e32 v16, v16
	v_rcp_f32_e32 v17, v17
	v_rcp_f32_e32 v6, v6
	v_rcp_f32_e32 v7, v7
	v_rcp_f32_e32 v8, v8
	v_rcp_f32_e32 v9, v9
	v_pk_mul_f32 v[10:11], v[14:15], v[10:11]
	v_pk_mul_f32 v[12:13], v[16:17], v[12:13]
	v_pk_mul_f32 v[2:3], v[6:7], v[2:3]
	v_pk_mul_f32 v[4:5], v[8:9], v[4:5]
	v_cvt_pk_bf16_f32 v10, v10, v11
	v_cvt_pk_bf16_f32 v11, v12, v13
	v_cvt_pk_bf16_f32 v12, v2, v3
	v_cvt_pk_bf16_f32 v13, v4, v5
	global_store_dwordx4 v[18:19], v[10:13], off
	s_cbranch_vccnz .LBB0_270
	s_andn2_b64 vcc, exec, s[6:7]
	s_cbranch_vccnz .LBB0_269
	s_barrier
	s_branch .LBB0_269

.LBB0_1124:
	ds_read_b128 v[146:149], v153
	ds_read_b128 v[156:159], v153 offset:1024
	ds_read_b128 v[160:163], v153 offset:2048
	ds_read_b128 v[164:167], v153 offset:3072
	ds_read_b128 v[168:171], v154
	ds_read_b128 v[172:175], v154 offset:1024
	ds_read_b128 v[176:179], v154 offset:2048
	ds_read_b128 v[180:183], v154 offset:3072
	s_add_u32 s34, s88, 0xfff80080
	s_addc_u32 s35, s89, -1
	s_cmp_eq_u32 s92, 28
	s_cselect_b32 s91, s0, s35
	s_cselect_b32 s90, s1, s34
	s_cselect_b32 s35, s52, s83
	s_cselect_b32 s34, s77, s81
	v_lshl_add_u64 v[218:219], s[88:89], 0, v[138:139]
	s_add_i32 m0, s56, 0xc000
	ds_read_b128 v[184:187], v155
	ds_read_b128 v[188:191], v155 offset:1024
	ds_read_b128 v[192:195], v155 offset:2048
	ds_read_b128 v[196:199], v155 offset:3072
	ds_read_b128 v[200:203], v155 offset:4096
	ds_read_b128 v[204:207], v155 offset:5120
	ds_read_b128 v[208:211], v155 offset:6144
	ds_read_b128 v[212:215], v155 offset:7168
	global_load_lds_dwordx4 v[218:219], off
	v_lshl_add_u64 v[218:219], s[88:89], 0, v[140:141]
	s_add_i32 m0, s56, 0xe000
	s_nop 0
	global_load_lds_dwordx4 v[218:219], off
	s_waitcnt vmcnt(8)
	s_waitcnt lgkmcnt(0)
	s_barrier
	s_setprio 1
	s_waitcnt lgkmcnt(0)
	v_mfma_f32_16x16x32_bf16 v[126:129], v[146:149], v[184:187], v[126:129]
	v_mfma_f32_16x16x32_bf16 v[118:121], v[160:163], v[184:187], v[118:121]
	v_mfma_f32_16x16x32_bf16 v[110:113], v[146:149], v[192:195], v[110:113]
	v_mfma_f32_16x16x32_bf16 v[102:105], v[160:163], v[192:195], v[102:105]
	v_mfma_f32_16x16x32_bf16 v[94:97], v[146:149], v[200:203], v[94:97]
	v_mfma_f32_16x16x32_bf16 v[86:89], v[160:163], v[200:203], v[86:89]
	v_mfma_f32_16x16x32_bf16 v[78:81], v[146:149], v[208:211], v[78:81]
	v_mfma_f32_16x16x32_bf16 v[70:73], v[160:163], v[208:211], v[70:73]
	v_mfma_f32_16x16x32_bf16 v[126:129], v[156:159], v[188:191], v[126:129]
	v_mfma_f32_16x16x32_bf16 v[118:121], v[164:167], v[188:191], v[118:121]
	v_mfma_f32_16x16x32_bf16 v[110:113], v[156:159], v[196:199], v[110:113]
	v_mfma_f32_16x16x32_bf16 v[102:105], v[164:167], v[196:199], v[102:105]
	v_mfma_f32_16x16x32_bf16 v[94:97], v[156:159], v[204:207], v[94:97]
	v_mfma_f32_16x16x32_bf16 v[86:89], v[164:167], v[204:207], v[86:89]
	v_mfma_f32_16x16x32_bf16 v[78:81], v[156:159], v[212:215], v[78:81]
	v_mfma_f32_16x16x32_bf16 v[70:73], v[164:167], v[212:215], v[70:73]
	s_setprio 0
	s_setprio 1
	v_mfma_f32_16x16x32_bf16 v[122:125], v[168:171], v[184:187], v[122:125]
	v_mfma_f32_16x16x32_bf16 v[114:117], v[176:179], v[184:187], v[114:117]
	v_mfma_f32_16x16x32_bf16 v[106:109], v[168:171], v[192:195], v[106:109]
	v_mfma_f32_16x16x32_bf16 v[98:101], v[176:179], v[192:195], v[98:101]
	v_mfma_f32_16x16x32_bf16 v[90:93], v[168:171], v[200:203], v[90:93]
	v_mfma_f32_16x16x32_bf16 v[82:85], v[176:179], v[200:203], v[82:85]
	v_mfma_f32_16x16x32_bf16 v[74:77], v[168:171], v[208:211], v[74:77]
	v_mfma_f32_16x16x32_bf16 v[66:69], v[176:179], v[208:211], v[66:69]
	v_mfma_f32_16x16x32_bf16 v[122:125], v[172:175], v[188:191], v[122:125]
	v_mfma_f32_16x16x32_bf16 v[114:117], v[180:183], v[188:191], v[114:117]
	v_mfma_f32_16x16x32_bf16 v[106:109], v[172:175], v[196:199], v[106:109]
	v_mfma_f32_16x16x32_bf16 v[98:101], v[180:183], v[196:199], v[98:101]
	v_mfma_f32_16x16x32_bf16 v[90:93], v[172:175], v[204:207], v[90:93]
	v_mfma_f32_16x16x32_bf16 v[82:85], v[180:183], v[204:207], v[82:85]
	v_mfma_f32_16x16x32_bf16 v[74:77], v[172:175], v[212:215], v[74:77]
	v_mfma_f32_16x16x32_bf16 v[66:69], v[180:183], v[212:215], v[66:69]
	s_setprio 0
	s_barrier
	s_add_i32 s53, s72, s30
	v_lshl_add_u64 v[218:219], s[34:35], 0, v[134:135]
	s_mov_b32 m0, s53
	ds_read_b128 v[184:187], v155 offset:16384
	ds_read_b128 v[188:191], v155 offset:17408
	ds_read_b128 v[192:195], v155 offset:18432
	ds_read_b128 v[196:199], v155 offset:19456
	ds_read_b128 v[200:203], v155 offset:20480
	ds_read_b128 v[204:207], v155 offset:21504
	ds_read_b128 v[208:211], v155 offset:22528
	ds_read_b128 v[212:215], v155 offset:23552
	global_load_lds_dwordx4 v[218:219], off
	s_add_i32 m0, s53, 0x2000
	s_add_u32 s54, s34, 0x80000
	v_lshl_add_u64 v[220:221], s[34:35], 0, v[130:131]
	s_addc_u32 s55, s35, 0
	s_add_i32 s53, s73, s30
	global_load_lds_dwordx4 v[220:221], off
	v_lshl_add_u64 v[222:223], s[54:55], 0, v[134:135]
	s_mov_b32 m0, s53
	v_lshl_add_u64 v[224:225], s[90:91], 0, v[132:133]
	global_load_lds_dwordx4 v[222:223], off
	v_lshl_add_u64 v[222:223], s[54:55], 0, v[130:131]
	s_add_i32 m0, s53, 0x2000
	s_nop 0
	global_load_lds_dwordx4 v[222:223], off
	v_lshl_add_u64 v[222:223], s[90:91], 0, v[136:137]
	s_mov_b32 m0, s56
	s_nop 0
	global_load_lds_dwordx4 v[222:223], off
	s_mov_b32 m0, s57
	s_nop 0
	global_load_lds_dwordx4 v[224:225], off
	s_waitcnt vmcnt(8)
	s_waitcnt lgkmcnt(0)
	s_barrier
	s_setprio 1
	s_waitcnt lgkmcnt(0)
	v_mfma_f32_16x16x32_bf16 v[62:65], v[146:149], v[184:187], v[62:65]
	v_mfma_f32_16x16x32_bf16 v[54:57], v[160:163], v[184:187], v[54:57]
	v_mfma_f32_16x16x32_bf16 v[46:49], v[146:149], v[192:195], v[46:49]
	v_mfma_f32_16x16x32_bf16 v[38:41], v[160:163], v[192:195], v[38:41]
	v_mfma_f32_16x16x32_bf16 v[30:33], v[146:149], v[200:203], v[30:33]
	v_mfma_f32_16x16x32_bf16 v[22:25], v[160:163], v[200:203], v[22:25]
	v_mfma_f32_16x16x32_bf16 v[14:17], v[146:149], v[208:211], v[14:17]
	v_mfma_f32_16x16x32_bf16 v[6:9], v[160:163], v[208:211], v[6:9]
	v_mfma_f32_16x16x32_bf16 v[62:65], v[156:159], v[188:191], v[62:65]
	v_mfma_f32_16x16x32_bf16 v[54:57], v[164:167], v[188:191], v[54:57]
	v_mfma_f32_16x16x32_bf16 v[46:49], v[156:159], v[196:199], v[46:49]
	v_mfma_f32_16x16x32_bf16 v[38:41], v[164:167], v[196:199], v[38:41]
	v_mfma_f32_16x16x32_bf16 v[30:33], v[156:159], v[204:207], v[30:33]
	v_mfma_f32_16x16x32_bf16 v[22:25], v[164:167], v[204:207], v[22:25]
	v_mfma_f32_16x16x32_bf16 v[14:17], v[156:159], v[212:215], v[14:17]
	v_mfma_f32_16x16x32_bf16 v[6:9], v[164:167], v[212:215], v[6:9]
	s_setprio 0
	s_setprio 1
	v_mfma_f32_16x16x32_bf16 v[58:61], v[168:171], v[184:187], v[58:61]
	v_mfma_f32_16x16x32_bf16 v[50:53], v[176:179], v[184:187], v[50:53]
	v_mfma_f32_16x16x32_bf16 v[42:45], v[168:171], v[192:195], v[42:45]
	v_mfma_f32_16x16x32_bf16 v[34:37], v[176:179], v[192:195], v[34:37]
	v_mfma_f32_16x16x32_bf16 v[26:29], v[168:171], v[200:203], v[26:29]
	v_mfma_f32_16x16x32_bf16 v[18:21], v[176:179], v[200:203], v[18:21]
	v_mfma_f32_16x16x32_bf16 v[10:13], v[168:171], v[208:211], v[10:13]
	v_mfma_f32_16x16x32_bf16 v[2:5], v[176:179], v[208:211], v[2:5]
	v_mfma_f32_16x16x32_bf16 v[58:61], v[172:175], v[188:191], v[58:61]
	v_mfma_f32_16x16x32_bf16 v[50:53], v[180:183], v[188:191], v[50:53]
	v_mfma_f32_16x16x32_bf16 v[42:45], v[172:175], v[196:199], v[42:45]
	v_mfma_f32_16x16x32_bf16 v[34:37], v[180:183], v[196:199], v[34:37]
	v_mfma_f32_16x16x32_bf16 v[26:29], v[172:175], v[204:207], v[26:29]
	v_mfma_f32_16x16x32_bf16 v[18:21], v[180:183], v[204:207], v[18:21]
	v_mfma_f32_16x16x32_bf16 v[10:13], v[172:175], v[212:215], v[10:13]
	v_mfma_f32_16x16x32_bf16 v[2:5], v[180:183], v[212:215], v[2:5]
	s_setprio 0
	s_barrier
	s_add_i32 s53, 0, 0x18000
	s_add_i32 s62, 0, 0x1c000
	v_add_u32_e32 v164, s53, v151
	v_add_u32_e32 v180, s62, v151
	ds_read_b128 v[146:149], v164
	ds_read_b128 v[156:159], v164 offset:1024
	ds_read_b128 v[160:163], v164 offset:2048
	ds_read_b128 v[164:167], v164 offset:3072
	ds_read_b128 v[168:171], v180
	ds_read_b128 v[172:175], v180 offset:1024
	ds_read_b128 v[176:179], v180 offset:2048
	ds_read_b128 v[180:183], v180 offset:3072
	s_add_u32 s54, s90, 0x80000
	s_addc_u32 s55, s91, 0
	s_mov_b32 m0, s58
	v_lshl_add_u64 v[226:227], s[54:55], 0, v[136:137]
	ds_read_b128 v[184:187], v155 offset:32768
	ds_read_b128 v[188:191], v155 offset:33792
	ds_read_b128 v[192:195], v155 offset:34816
	ds_read_b128 v[196:199], v155 offset:35840
	ds_read_b128 v[200:203], v155 offset:36864
	ds_read_b128 v[204:207], v155 offset:37888
	ds_read_b128 v[208:211], v155 offset:38912
	ds_read_b128 v[212:215], v155 offset:39936
	global_load_lds_dwordx4 v[226:227], off
	v_lshl_add_u64 v[226:227], s[54:55], 0, v[132:133]
	s_mov_b32 m0, s59
	s_nop 0
	global_load_lds_dwordx4 v[226:227], off
	s_waitcnt vmcnt(8)
	s_waitcnt lgkmcnt(0)
	s_barrier
	s_setprio 1
	s_waitcnt lgkmcnt(0)
	v_mfma_f32_16x16x32_bf16 v[126:129], v[146:149], v[184:187], v[126:129]
	v_mfma_f32_16x16x32_bf16 v[118:121], v[160:163], v[184:187], v[118:121]
	v_mfma_f32_16x16x32_bf16 v[110:113], v[146:149], v[192:195], v[110:113]
	v_mfma_f32_16x16x32_bf16 v[102:105], v[160:163], v[192:195], v[102:105]
	v_mfma_f32_16x16x32_bf16 v[94:97], v[146:149], v[200:203], v[94:97]
	v_mfma_f32_16x16x32_bf16 v[86:89], v[160:163], v[200:203], v[86:89]
	v_mfma_f32_16x16x32_bf16 v[78:81], v[146:149], v[208:211], v[78:81]
	v_mfma_f32_16x16x32_bf16 v[70:73], v[160:163], v[208:211], v[70:73]
	v_mfma_f32_16x16x32_bf16 v[126:129], v[156:159], v[188:191], v[126:129]
	v_mfma_f32_16x16x32_bf16 v[118:121], v[164:167], v[188:191], v[118:121]
	v_mfma_f32_16x16x32_bf16 v[110:113], v[156:159], v[196:199], v[110:113]
	v_mfma_f32_16x16x32_bf16 v[102:105], v[164:167], v[196:199], v[102:105]
	v_mfma_f32_16x16x32_bf16 v[94:97], v[156:159], v[204:207], v[94:97]
	v_mfma_f32_16x16x32_bf16 v[86:89], v[164:167], v[204:207], v[86:89]
	v_mfma_f32_16x16x32_bf16 v[78:81], v[156:159], v[212:215], v[78:81]
	v_mfma_f32_16x16x32_bf16 v[70:73], v[164:167], v[212:215], v[70:73]
	s_setprio 0
	s_setprio 1
	v_mfma_f32_16x16x32_bf16 v[122:125], v[168:171], v[184:187], v[122:125]
	v_mfma_f32_16x16x32_bf16 v[114:117], v[176:179], v[184:187], v[114:117]
	v_mfma_f32_16x16x32_bf16 v[106:109], v[168:171], v[192:195], v[106:109]
	v_mfma_f32_16x16x32_bf16 v[98:101], v[176:179], v[192:195], v[98:101]
	v_mfma_f32_16x16x32_bf16 v[90:93], v[168:171], v[200:203], v[90:93]
	v_mfma_f32_16x16x32_bf16 v[82:85], v[176:179], v[200:203], v[82:85]
	v_mfma_f32_16x16x32_bf16 v[74:77], v[168:171], v[208:211], v[74:77]
	v_mfma_f32_16x16x32_bf16 v[66:69], v[176:179], v[208:211], v[66:69]
	v_mfma_f32_16x16x32_bf16 v[122:125], v[172:175], v[188:191], v[122:125]
	v_mfma_f32_16x16x32_bf16 v[114:117], v[180:183], v[188:191], v[114:117]
	v_mfma_f32_16x16x32_bf16 v[106:109], v[172:175], v[196:199], v[106:109]
	v_mfma_f32_16x16x32_bf16 v[98:101], v[180:183], v[196:199], v[98:101]
	v_mfma_f32_16x16x32_bf16 v[90:93], v[172:175], v[204:207], v[90:93]
	v_mfma_f32_16x16x32_bf16 v[82:85], v[180:183], v[204:207], v[82:85]
	v_mfma_f32_16x16x32_bf16 v[74:77], v[172:175], v[212:215], v[74:77]
	v_mfma_f32_16x16x32_bf16 v[66:69], v[180:183], v[212:215], v[66:69]
	s_setprio 0
	s_barrier
	s_add_i32 s53, s53, s30
	v_lshl_add_u64 v[218:219], v[218:219], 0, s[8:9]
	s_mov_b32 m0, s53
	ds_read_b128 v[184:187], v155 offset:49152
	ds_read_b128 v[188:191], v155 offset:50176
	ds_read_b128 v[192:195], v155 offset:51200
	ds_read_b128 v[196:199], v155 offset:52224
	ds_read_b128 v[200:203], v155 offset:53248
	ds_read_b128 v[204:207], v155 offset:54272
	ds_read_b128 v[208:211], v155 offset:55296
	ds_read_b128 v[212:215], v155 offset:56320
	global_load_lds_dwordx4 v[218:219], off
	s_add_i32 m0, s53, 0x2000
	s_add_u32 s34, s34, 0x80080
	v_lshl_add_u64 v[218:219], v[220:221], 0, s[8:9]
	s_addc_u32 s35, s35, 0
	s_add_i32 s53, s62, s30
	global_load_lds_dwordx4 v[218:219], off
	v_lshl_add_u64 v[218:219], s[34:35], 0, v[134:135]
	s_mov_b32 m0, s53
	s_nop 0
	global_load_lds_dwordx4 v[218:219], off
	v_lshl_add_u64 v[218:219], s[34:35], 0, v[130:131]
	s_add_i32 m0, s53, 0x2000
	s_nop 0
	global_load_lds_dwordx4 v[218:219], off
	v_lshl_add_u64 v[218:219], v[222:223], 0, s[8:9]
	s_mov_b32 m0, s61
	s_nop 0
	global_load_lds_dwordx4 v[218:219], off
	v_lshl_add_u64 v[218:219], v[224:225], 0, s[8:9]
	s_mov_b32 m0, s70
	s_nop 0
	global_load_lds_dwordx4 v[218:219], off
	s_waitcnt vmcnt(8)
	s_waitcnt lgkmcnt(0)
	s_barrier
	s_setprio 1
	s_waitcnt lgkmcnt(0)
	v_mfma_f32_16x16x32_bf16 v[62:65], v[146:149], v[184:187], v[62:65]
	v_mfma_f32_16x16x32_bf16 v[54:57], v[160:163], v[184:187], v[54:57]
	v_mfma_f32_16x16x32_bf16 v[46:49], v[146:149], v[192:195], v[46:49]
	v_mfma_f32_16x16x32_bf16 v[38:41], v[160:163], v[192:195], v[38:41]
	v_mfma_f32_16x16x32_bf16 v[30:33], v[146:149], v[200:203], v[30:33]
	v_mfma_f32_16x16x32_bf16 v[22:25], v[160:163], v[200:203], v[22:25]
	v_mfma_f32_16x16x32_bf16 v[14:17], v[146:149], v[208:211], v[14:17]
	v_mfma_f32_16x16x32_bf16 v[6:9], v[160:163], v[208:211], v[6:9]
	v_mfma_f32_16x16x32_bf16 v[62:65], v[156:159], v[188:191], v[62:65]
	v_mfma_f32_16x16x32_bf16 v[54:57], v[164:167], v[188:191], v[54:57]
	v_mfma_f32_16x16x32_bf16 v[46:49], v[156:159], v[196:199], v[46:49]
	v_mfma_f32_16x16x32_bf16 v[38:41], v[164:167], v[196:199], v[38:41]
	v_mfma_f32_16x16x32_bf16 v[30:33], v[156:159], v[204:207], v[30:33]
	v_mfma_f32_16x16x32_bf16 v[22:25], v[164:167], v[204:207], v[22:25]
	v_mfma_f32_16x16x32_bf16 v[14:17], v[156:159], v[212:215], v[14:17]
	v_mfma_f32_16x16x32_bf16 v[6:9], v[164:167], v[212:215], v[6:9]
	s_setprio 0
	s_setprio 1
	v_mfma_f32_16x16x32_bf16 v[58:61], v[168:171], v[184:187], v[58:61]
	v_mfma_f32_16x16x32_bf16 v[50:53], v[176:179], v[184:187], v[50:53]
	v_mfma_f32_16x16x32_bf16 v[42:45], v[168:171], v[192:195], v[42:45]
	v_mfma_f32_16x16x32_bf16 v[34:37], v[176:179], v[192:195], v[34:37]
	v_mfma_f32_16x16x32_bf16 v[26:29], v[168:171], v[200:203], v[26:29]
	v_mfma_f32_16x16x32_bf16 v[18:21], v[176:179], v[200:203], v[18:21]
	v_mfma_f32_16x16x32_bf16 v[10:13], v[168:171], v[208:211], v[10:13]
	v_mfma_f32_16x16x32_bf16 v[2:5], v[176:179], v[208:211], v[2:5]
	v_mfma_f32_16x16x32_bf16 v[58:61], v[172:175], v[188:191], v[58:61]
	v_mfma_f32_16x16x32_bf16 v[50:53], v[180:183], v[188:191], v[50:53]
	v_mfma_f32_16x16x32_bf16 v[42:45], v[172:175], v[196:199], v[42:45]
	v_mfma_f32_16x16x32_bf16 v[34:37], v[180:183], v[196:199], v[34:37]
	v_mfma_f32_16x16x32_bf16 v[26:29], v[172:175], v[204:207], v[26:29]
	v_mfma_f32_16x16x32_bf16 v[18:21], v[180:183], v[204:207], v[18:21]
	v_mfma_f32_16x16x32_bf16 v[10:13], v[172:175], v[212:215], v[10:13]
	v_mfma_f32_16x16x32_bf16 v[2:5], v[180:183], v[212:215], v[2:5]
	s_setprio 0
	s_barrier
	s_add_i32 s92, s92, 2
	s_add_u32 s88, s88, 0x100
	s_addc_u32 s89, s89, 0
	s_add_u32 s81, s81, 0x100
	s_addc_u32 s83, s83, 0
	s_cmp_gt_u32 s92, 29
	s_cbranch_scc0 .LBB0_1124
	v_mov_b32_e32 v157, 0xbfb8aa3b
	s_and_b64 vcc, exec, s[78:79]
	s_cbranch_vccz .LBB0_1127
	s_barrier
.LBB0_1127:
	v_readlane_b32 s0, v247, 31
	v_lshl_or_b32 v148, s75, 7, v152
	v_readlane_b32 s1, v247, 32
	v_lshl_add_u32 v156, s76, 8, v1
	v_ashrrev_i32_e32 v149, 31, v148
	v_mov_b64_e32 v[146:147], s[0:1]
	v_mad_i64_i32 v[158:159], s[0:1], v156, s74, v[146:147]
	v_lshlrev_b64 v[148:149], 1, v[148:149]
	v_lshl_add_u64 v[158:159], v[158:159], 0, v[148:149]
	v_pk_mul_f32 v[122:123], v[126:127], v[122:123]
	v_pk_mul_f32 v[124:125], v[128:129], v[124:125]
	v_pk_mul_f32 v[114:115], v[118:119], v[114:115]
	v_pk_mul_f32 v[116:117], v[120:121], v[116:117]
	v_pk_mul_f32 v[126:127], v[126:127], v[156:157] op_sel:[0,1]
	v_pk_mul_f32 v[128:129], v[128:129], v[156:157] op_sel:[0,1]
	v_pk_mul_f32 v[118:119], v[118:119], v[156:157] op_sel:[0,1]
	v_pk_mul_f32 v[120:121], v[120:121], v[156:157] op_sel:[0,1]
	v_exp_f32_e32 v126, v126
	v_exp_f32_e32 v127, v127
	v_exp_f32_e32 v128, v128
	v_exp_f32_e32 v129, v129
	v_exp_f32_e32 v118, v118
	v_exp_f32_e32 v119, v119
	v_exp_f32_e32 v120, v120
	v_exp_f32_e32 v121, v121
	v_pk_add_f32 v[126:127], v[126:127], 1.0 op_sel_hi:[1,0]
	v_pk_add_f32 v[128:129], v[128:129], 1.0 op_sel_hi:[1,0]
	v_pk_add_f32 v[118:119], v[118:119], 1.0 op_sel_hi:[1,0]
	v_pk_add_f32 v[120:121], v[120:121], 1.0 op_sel_hi:[1,0]
	v_rcp_f32_e32 v126, v126
	v_rcp_f32_e32 v127, v127
	v_rcp_f32_e32 v128, v128
	v_rcp_f32_e32 v129, v129
	v_rcp_f32_e32 v118, v118
	v_rcp_f32_e32 v119, v119
	v_rcp_f32_e32 v120, v120
	v_rcp_f32_e32 v121, v121
	v_pk_mul_f32 v[122:123], v[126:127], v[122:123]
	v_pk_mul_f32 v[124:125], v[128:129], v[124:125]
	v_pk_mul_f32 v[114:115], v[118:119], v[114:115]
	v_pk_mul_f32 v[116:117], v[120:121], v[116:117]
	v_cvt_pk_bf16_f32 v122, v122, v123
	v_cvt_pk_bf16_f32 v123, v124, v125
	v_cvt_pk_bf16_f32 v124, v114, v115
	v_cvt_pk_bf16_f32 v125, v116, v117
	global_store_dwordx4 v[158:159], v[122:125], off
	v_or_b32_e32 v114, 16, v156
	v_mad_i64_i32 v[114:115], s[0:1], v114, s74, v[146:147]
	v_lshl_add_u64 v[114:115], v[114:115], 0, v[148:149]
	s_andn2_b64 vcc, exec, s[2:3]
	s_nop 0
	s_nop 0
	s_nop 0
	s_nop 0
	s_nop 0
	s_nop 0
	s_nop 0
	s_nop 0
	v_pk_mul_f32 v[106:107], v[110:111], v[106:107]
	v_pk_mul_f32 v[108:109], v[112:113], v[108:109]
	v_pk_mul_f32 v[98:99], v[102:103], v[98:99]
	v_pk_mul_f32 v[100:101], v[104:105], v[100:101]
	v_pk_mul_f32 v[110:111], v[110:111], v[156:157] op_sel:[0,1]
	v_pk_mul_f32 v[112:113], v[112:113], v[156:157] op_sel:[0,1]
	v_pk_mul_f32 v[102:103], v[102:103], v[156:157] op_sel:[0,1]
	v_pk_mul_f32 v[104:105], v[104:105], v[156:157] op_sel:[0,1]
	v_exp_f32_e32 v110, v110
	v_exp_f32_e32 v111, v111
	v_exp_f32_e32 v112, v112
	v_exp_f32_e32 v113, v113
	v_exp_f32_e32 v102, v102
	v_exp_f32_e32 v103, v103
	v_exp_f32_e32 v104, v104
	v_exp_f32_e32 v105, v105
	v_pk_add_f32 v[110:111], v[110:111], 1.0 op_sel_hi:[1,0]
	v_pk_add_f32 v[112:113], v[112:113], 1.0 op_sel_hi:[1,0]
	v_pk_add_f32 v[102:103], v[102:103], 1.0 op_sel_hi:[1,0]
	v_pk_add_f32 v[104:105], v[104:105], 1.0 op_sel_hi:[1,0]
	v_rcp_f32_e32 v110, v110
	v_rcp_f32_e32 v111, v111
	v_rcp_f32_e32 v112, v112
	v_rcp_f32_e32 v113, v113
	v_rcp_f32_e32 v102, v102
	v_rcp_f32_e32 v103, v103
	v_rcp_f32_e32 v104, v104
	v_rcp_f32_e32 v105, v105
	v_pk_mul_f32 v[106:107], v[110:111], v[106:107]
	v_pk_mul_f32 v[108:109], v[112:113], v[108:109]
	v_pk_mul_f32 v[98:99], v[102:103], v[98:99]
	v_pk_mul_f32 v[100:101], v[104:105], v[100:101]
	v_cvt_pk_bf16_f32 v106, v106, v107
	v_cvt_pk_bf16_f32 v107, v108, v109
	v_cvt_pk_bf16_f32 v108, v98, v99
	v_cvt_pk_bf16_f32 v109, v100, v101
	global_store_dwordx4 v[114:115], v[106:109], off
	v_or_b32_e32 v98, 32, v156
	v_mad_i64_i32 v[98:99], s[0:1], v98, s74, v[146:147]
	v_lshl_add_u64 v[98:99], v[98:99], 0, v[148:149]
	s_nop 0
	s_nop 0
	s_nop 0
	s_nop 0
	s_nop 0
	s_nop 0
	s_nop 0
	s_nop 0
	s_nop 0
	s_nop 0
	s_nop 0
	s_nop 0
	s_nop 0
	v_pk_mul_f32 v[90:91], v[94:95], v[90:91]
	v_pk_mul_f32 v[92:93], v[96:97], v[92:93]
	v_pk_mul_f32 v[82:83], v[86:87], v[82:83]
	v_pk_mul_f32 v[84:85], v[88:89], v[84:85]
	v_pk_mul_f32 v[94:95], v[94:95], v[156:157] op_sel:[0,1]
	v_pk_mul_f32 v[96:97], v[96:97], v[156:157] op_sel:[0,1]
	v_pk_mul_f32 v[86:87], v[86:87], v[156:157] op_sel:[0,1]
	v_pk_mul_f32 v[88:89], v[88:89], v[156:157] op_sel:[0,1]
	v_exp_f32_e32 v94, v94
	v_exp_f32_e32 v95, v95
	v_exp_f32_e32 v96, v96
	v_exp_f32_e32 v97, v97
	v_exp_f32_e32 v86, v86
	v_exp_f32_e32 v87, v87
	v_exp_f32_e32 v88, v88
	v_exp_f32_e32 v89, v89
	v_pk_add_f32 v[94:95], v[94:95], 1.0 op_sel_hi:[1,0]
	v_pk_add_f32 v[96:97], v[96:97], 1.0 op_sel_hi:[1,0]
	v_pk_add_f32 v[86:87], v[86:87], 1.0 op_sel_hi:[1,0]
	v_pk_add_f32 v[88:89], v[88:89], 1.0 op_sel_hi:[1,0]
	v_rcp_f32_e32 v94, v94
	v_rcp_f32_e32 v95, v95
	v_rcp_f32_e32 v96, v96
	v_rcp_f32_e32 v97, v97
	v_rcp_f32_e32 v86, v86
	v_rcp_f32_e32 v87, v87
	v_rcp_f32_e32 v88, v88
	v_rcp_f32_e32 v89, v89
	v_pk_mul_f32 v[90:91], v[94:95], v[90:91]
	v_pk_mul_f32 v[92:93], v[96:97], v[92:93]
	v_pk_mul_f32 v[82:83], v[86:87], v[82:83]
	v_pk_mul_f32 v[84:85], v[88:89], v[84:85]
	v_cvt_pk_bf16_f32 v90, v90, v91
	v_cvt_pk_bf16_f32 v91, v92, v93
	v_cvt_pk_bf16_f32 v92, v82, v83
	v_cvt_pk_bf16_f32 v93, v84, v85
	global_store_dwordx4 v[98:99], v[90:93], off
	v_or_b32_e32 v82, 48, v156
	v_mad_i64_i32 v[82:83], s[0:1], v82, s74, v[146:147]
	v_lshl_add_u64 v[82:83], v[82:83], 0, v[148:149]
	s_nop 0
	s_nop 0
	s_nop 0
	s_nop 0
	s_nop 0
	s_nop 0
	s_nop 0
	s_nop 0
	s_nop 0
	s_nop 0
	s_nop 0
	s_nop 0
	s_nop 0
	v_pk_mul_f32 v[74:75], v[78:79], v[74:75]
	v_pk_mul_f32 v[76:77], v[80:81], v[76:77]
	v_pk_mul_f32 v[66:67], v[70:71], v[66:67]
	v_pk_mul_f32 v[68:69], v[72:73], v[68:69]
	v_pk_mul_f32 v[78:79], v[78:79], v[156:157] op_sel:[0,1]
	v_pk_mul_f32 v[80:81], v[80:81], v[156:157] op_sel:[0,1]
	v_pk_mul_f32 v[70:71], v[70:71], v[156:157] op_sel:[0,1]
	v_pk_mul_f32 v[72:73], v[72:73], v[156:157] op_sel:[0,1]
	v_exp_f32_e32 v78, v78
	v_exp_f32_e32 v79, v79
	v_exp_f32_e32 v80, v80
	v_exp_f32_e32 v81, v81
	v_exp_f32_e32 v70, v70
	v_exp_f32_e32 v71, v71
	v_exp_f32_e32 v72, v72
	v_exp_f32_e32 v73, v73
	v_pk_add_f32 v[78:79], v[78:79], 1.0 op_sel_hi:[1,0]
	v_pk_add_f32 v[80:81], v[80:81], 1.0 op_sel_hi:[1,0]
	v_pk_add_f32 v[70:71], v[70:71], 1.0 op_sel_hi:[1,0]
	v_pk_add_f32 v[72:73], v[72:73], 1.0 op_sel_hi:[1,0]
	v_rcp_f32_e32 v78, v78
	v_rcp_f32_e32 v79, v79
	v_rcp_f32_e32 v80, v80
	v_rcp_f32_e32 v81, v81
	v_rcp_f32_e32 v70, v70
	v_rcp_f32_e32 v71, v71
	v_rcp_f32_e32 v72, v72
	v_rcp_f32_e32 v73, v73
	v_pk_mul_f32 v[74:75], v[78:79], v[74:75]
	v_pk_mul_f32 v[76:77], v[80:81], v[76:77]
	v_pk_mul_f32 v[66:67], v[70:71], v[66:67]
	v_pk_mul_f32 v[68:69], v[72:73], v[68:69]
	v_cvt_pk_bf16_f32 v74, v74, v75
	v_cvt_pk_bf16_f32 v75, v76, v77
	v_cvt_pk_bf16_f32 v76, v66, v67
	v_cvt_pk_bf16_f32 v77, v68, v69
	global_store_dwordx4 v[82:83], v[74:77], off
	v_add_u32_e32 v66, 0x80, v156
	v_mad_i64_i32 v[66:67], s[0:1], v66, s74, v[146:147]
	v_lshl_add_u64 v[66:67], v[66:67], 0, v[148:149]
	s_nop 0
	s_nop 0
	s_nop 0
	s_nop 0
	s_nop 0
	s_nop 0
	s_nop 0
	s_nop 0
	s_nop 0
	s_nop 0
	s_nop 0
	s_nop 0
	s_nop 0
	v_pk_mul_f32 v[58:59], v[62:63], v[58:59]
	v_pk_mul_f32 v[60:61], v[64:65], v[60:61]
	v_pk_mul_f32 v[50:51], v[54:55], v[50:51]
	v_pk_mul_f32 v[52:53], v[56:57], v[52:53]
	v_pk_mul_f32 v[62:63], v[62:63], v[156:157] op_sel:[0,1]
	v_pk_mul_f32 v[64:65], v[64:65], v[156:157] op_sel:[0,1]
	v_pk_mul_f32 v[54:55], v[54:55], v[156:157] op_sel:[0,1]
	v_pk_mul_f32 v[56:57], v[56:57], v[156:157] op_sel:[0,1]
	v_exp_f32_e32 v62, v62
	v_exp_f32_e32 v63, v63
	v_exp_f32_e32 v64, v64
	v_exp_f32_e32 v65, v65
	v_exp_f32_e32 v54, v54
	v_exp_f32_e32 v55, v55
	v_exp_f32_e32 v56, v56
	v_exp_f32_e32 v57, v57
	v_pk_add_f32 v[62:63], v[62:63], 1.0 op_sel_hi:[1,0]
	v_pk_add_f32 v[64:65], v[64:65], 1.0 op_sel_hi:[1,0]
	v_pk_add_f32 v[54:55], v[54:55], 1.0 op_sel_hi:[1,0]
	v_pk_add_f32 v[56:57], v[56:57], 1.0 op_sel_hi:[1,0]
	v_rcp_f32_e32 v62, v62
	v_rcp_f32_e32 v63, v63
	v_rcp_f32_e32 v64, v64
	v_rcp_f32_e32 v65, v65
	v_rcp_f32_e32 v54, v54
	v_rcp_f32_e32 v55, v55
	v_rcp_f32_e32 v56, v56
	v_rcp_f32_e32 v57, v57
	v_pk_mul_f32 v[58:59], v[62:63], v[58:59]
	v_pk_mul_f32 v[60:61], v[64:65], v[60:61]
	v_pk_mul_f32 v[50:51], v[54:55], v[50:51]
	v_pk_mul_f32 v[52:53], v[56:57], v[52:53]
	v_cvt_pk_bf16_f32 v58, v58, v59
	v_cvt_pk_bf16_f32 v59, v60, v61
	v_cvt_pk_bf16_f32 v60, v50, v51
	v_cvt_pk_bf16_f32 v61, v52, v53
	global_store_dwordx4 v[66:67], v[58:61], off
	v_add_u32_e32 v50, 0x90, v156
	v_mad_i64_i32 v[50:51], s[0:1], v50, s74, v[146:147]
	v_lshl_add_u64 v[50:51], v[50:51], 0, v[148:149]
	s_nop 0
	s_nop 0
	s_nop 0
	s_nop 0
	s_nop 0
	s_nop 0
	s_nop 0
	s_nop 0
	s_nop 0
	s_nop 0
	s_nop 0
	s_nop 0
	s_nop 0
	v_pk_mul_f32 v[42:43], v[46:47], v[42:43]
	v_pk_mul_f32 v[44:45], v[48:49], v[44:45]
	v_pk_mul_f32 v[34:35], v[38:39], v[34:35]
	v_pk_mul_f32 v[36:37], v[40:41], v[36:37]
	v_pk_mul_f32 v[46:47], v[46:47], v[156:157] op_sel:[0,1]
	v_pk_mul_f32 v[48:49], v[48:49], v[156:157] op_sel:[0,1]
	v_pk_mul_f32 v[38:39], v[38:39], v[156:157] op_sel:[0,1]
	v_pk_mul_f32 v[40:41], v[40:41], v[156:157] op_sel:[0,1]
	v_exp_f32_e32 v46, v46
	v_exp_f32_e32 v47, v47
	v_exp_f32_e32 v48, v48
	v_exp_f32_e32 v49, v49
	v_exp_f32_e32 v38, v38
	v_exp_f32_e32 v39, v39
	v_exp_f32_e32 v40, v40
	v_exp_f32_e32 v41, v41
	v_pk_add_f32 v[46:47], v[46:47], 1.0 op_sel_hi:[1,0]
	v_pk_add_f32 v[48:49], v[48:49], 1.0 op_sel_hi:[1,0]
	v_pk_add_f32 v[38:39], v[38:39], 1.0 op_sel_hi:[1,0]
	v_pk_add_f32 v[40:41], v[40:41], 1.0 op_sel_hi:[1,0]
	v_rcp_f32_e32 v46, v46
	v_rcp_f32_e32 v47, v47
	v_rcp_f32_e32 v48, v48
	v_rcp_f32_e32 v49, v49
	v_rcp_f32_e32 v38, v38
	v_rcp_f32_e32 v39, v39
	v_rcp_f32_e32 v40, v40
	v_rcp_f32_e32 v41, v41
	v_pk_mul_f32 v[42:43], v[46:47], v[42:43]
	v_pk_mul_f32 v[44:45], v[48:49], v[44:45]
	v_pk_mul_f32 v[34:35], v[38:39], v[34:35]
	v_pk_mul_f32 v[36:37], v[40:41], v[36:37]
	v_cvt_pk_bf16_f32 v42, v42, v43
	v_cvt_pk_bf16_f32 v43, v44, v45
	v_cvt_pk_bf16_f32 v44, v34, v35
	v_cvt_pk_bf16_f32 v45, v36, v37
	global_store_dwordx4 v[50:51], v[42:45], off
	v_add_u32_e32 v34, 0xa0, v156
	v_mad_i64_i32 v[34:35], s[0:1], v34, s74, v[146:147]
	v_lshl_add_u64 v[34:35], v[34:35], 0, v[148:149]
	s_nop 0
	s_nop 0
	s_nop 0
	s_nop 0
	s_nop 0
	s_nop 0
	s_nop 0
	s_nop 0
	s_nop 0
	s_nop 0
	s_nop 0
	s_nop 0
	s_nop 0
	v_pk_mul_f32 v[26:27], v[30:31], v[26:27]
	v_pk_mul_f32 v[28:29], v[32:33], v[28:29]
	v_pk_mul_f32 v[18:19], v[22:23], v[18:19]
	v_pk_mul_f32 v[20:21], v[24:25], v[20:21]
	v_pk_mul_f32 v[30:31], v[30:31], v[156:157] op_sel:[0,1]
	v_pk_mul_f32 v[32:33], v[32:33], v[156:157] op_sel:[0,1]
	v_pk_mul_f32 v[22:23], v[22:23], v[156:157] op_sel:[0,1]
	v_pk_mul_f32 v[24:25], v[24:25], v[156:157] op_sel:[0,1]
	v_exp_f32_e32 v30, v30
	v_exp_f32_e32 v31, v31
	v_exp_f32_e32 v32, v32
	v_exp_f32_e32 v33, v33
	v_exp_f32_e32 v22, v22
	v_exp_f32_e32 v23, v23
	v_exp_f32_e32 v24, v24
	v_exp_f32_e32 v25, v25
	v_pk_add_f32 v[30:31], v[30:31], 1.0 op_sel_hi:[1,0]
	v_pk_add_f32 v[32:33], v[32:33], 1.0 op_sel_hi:[1,0]
	v_pk_add_f32 v[22:23], v[22:23], 1.0 op_sel_hi:[1,0]
	v_pk_add_f32 v[24:25], v[24:25], 1.0 op_sel_hi:[1,0]
	v_rcp_f32_e32 v30, v30
	v_rcp_f32_e32 v31, v31
	v_rcp_f32_e32 v32, v32
	v_rcp_f32_e32 v33, v33
	v_rcp_f32_e32 v22, v22
	v_rcp_f32_e32 v23, v23
	v_rcp_f32_e32 v24, v24
	v_rcp_f32_e32 v25, v25
	v_pk_mul_f32 v[26:27], v[30:31], v[26:27]
	v_pk_mul_f32 v[28:29], v[32:33], v[28:29]
	v_pk_mul_f32 v[18:19], v[22:23], v[18:19]
	v_pk_mul_f32 v[20:21], v[24:25], v[20:21]
	v_cvt_pk_bf16_f32 v26, v26, v27
	v_cvt_pk_bf16_f32 v27, v28, v29
	v_cvt_pk_bf16_f32 v28, v18, v19
	v_cvt_pk_bf16_f32 v29, v20, v21
	global_store_dwordx4 v[34:35], v[26:29], off
	v_add_u32_e32 v18, 0xb0, v156
	v_mad_i64_i32 v[18:19], s[0:1], v18, s74, v[146:147]
	v_lshl_add_u64 v[18:19], v[18:19], 0, v[148:149]
	s_mov_b64 s[0:1], -1
	s_nop 0
	s_nop 0
	s_nop 0
	s_nop 0
	s_nop 0
	s_nop 0
	s_nop 0
	s_nop 0
	s_nop 0
	s_nop 0
	s_nop 0
	s_nop 0
	v_pk_mul_f32 v[10:11], v[14:15], v[10:11]
	v_pk_mul_f32 v[12:13], v[16:17], v[12:13]
	v_pk_mul_f32 v[2:3], v[6:7], v[2:3]
	v_pk_mul_f32 v[4:5], v[8:9], v[4:5]
	v_pk_mul_f32 v[14:15], v[14:15], v[156:157] op_sel:[0,1]
	v_pk_mul_f32 v[16:17], v[16:17], v[156:157] op_sel:[0,1]
	v_pk_mul_f32 v[6:7], v[6:7], v[156:157] op_sel:[0,1]
	v_pk_mul_f32 v[8:9], v[8:9], v[156:157] op_sel:[0,1]
	v_exp_f32_e32 v14, v14
	v_exp_f32_e32 v15, v15
	v_exp_f32_e32 v16, v16
	v_exp_f32_e32 v17, v17
	v_exp_f32_e32 v6, v6
	v_exp_f32_e32 v7, v7
	v_exp_f32_e32 v8, v8
	v_exp_f32_e32 v9, v9
	v_pk_add_f32 v[14:15], v[14:15], 1.0 op_sel_hi:[1,0]
	v_pk_add_f32 v[16:17], v[16:17], 1.0 op_sel_hi:[1,0]
	v_pk_add_f32 v[6:7], v[6:7], 1.0 op_sel_hi:[1,0]
	v_pk_add_f32 v[8:9], v[8:9], 1.0 op_sel_hi:[1,0]
	v_rcp_f32_e32 v14, v14
	v_rcp_f32_e32 v15, v15
	v_rcp_f32_e32 v16, v16
	v_rcp_f32_e32 v17, v17
	v_rcp_f32_e32 v6, v6
	v_rcp_f32_e32 v7, v7
	v_rcp_f32_e32 v8, v8
	v_rcp_f32_e32 v9, v9
	v_pk_mul_f32 v[10:11], v[14:15], v[10:11]
	v_pk_mul_f32 v[12:13], v[16:17], v[12:13]
	v_pk_mul_f32 v[2:3], v[6:7], v[2:3]
	v_pk_mul_f32 v[4:5], v[8:9], v[4:5]
	v_cvt_pk_bf16_f32 v10, v10, v11
	v_cvt_pk_bf16_f32 v11, v12, v13
	v_cvt_pk_bf16_f32 v12, v2, v3
	v_cvt_pk_bf16_f32 v13, v4, v5
	global_store_dwordx4 v[18:19], v[10:13], off
	s_cbranch_vccnz .LBB0_1120
	s_andn2_b64 vcc, exec, s[6:7]
	s_cbranch_vccnz .LBB0_1119
	s_barrier
	s_branch .LBB0_1119

.LBB0_2218:
	ds_read_b128 v[146:149], v153
	ds_read_b128 v[156:159], v153 offset:1024
	ds_read_b128 v[160:163], v153 offset:2048
	ds_read_b128 v[164:167], v153 offset:3072
	ds_read_b128 v[168:171], v154
	ds_read_b128 v[172:175], v154 offset:1024
	ds_read_b128 v[176:179], v154 offset:2048
	ds_read_b128 v[180:183], v154 offset:3072
	s_add_u32 s34, s76, 0xfff80080
	s_addc_u32 s35, s77, -1
	s_cmp_eq_u32 s80, 28
	s_cselect_b32 s79, s0, s35
	s_cselect_b32 s78, s1, s34
	s_cselect_b32 s35, s27, s75
	s_cselect_b32 s34, s37, s52
	v_lshl_add_u64 v[218:219], s[76:77], 0, v[138:139]
	s_add_i32 m0, s47, 0xc000
	ds_read_b128 v[184:187], v155
	ds_read_b128 v[188:191], v155 offset:1024
	ds_read_b128 v[192:195], v155 offset:2048
	ds_read_b128 v[196:199], v155 offset:3072
	ds_read_b128 v[200:203], v155 offset:4096
	ds_read_b128 v[204:207], v155 offset:5120
	ds_read_b128 v[208:211], v155 offset:6144
	ds_read_b128 v[212:215], v155 offset:7168
	global_load_lds_dwordx4 v[218:219], off
	v_lshl_add_u64 v[218:219], s[76:77], 0, v[140:141]
	s_add_i32 m0, s47, 0xe000
	s_nop 0
	global_load_lds_dwordx4 v[218:219], off
	s_waitcnt vmcnt(8)
	s_waitcnt lgkmcnt(0)
	s_barrier
	s_setprio 1
	s_waitcnt lgkmcnt(0)
	v_mfma_f32_16x16x32_bf16 v[126:129], v[146:149], v[184:187], v[126:129]
	v_mfma_f32_16x16x32_bf16 v[118:121], v[160:163], v[184:187], v[118:121]
	v_mfma_f32_16x16x32_bf16 v[110:113], v[146:149], v[192:195], v[110:113]
	v_mfma_f32_16x16x32_bf16 v[102:105], v[160:163], v[192:195], v[102:105]
	v_mfma_f32_16x16x32_bf16 v[94:97], v[146:149], v[200:203], v[94:97]
	v_mfma_f32_16x16x32_bf16 v[86:89], v[160:163], v[200:203], v[86:89]
	v_mfma_f32_16x16x32_bf16 v[78:81], v[146:149], v[208:211], v[78:81]
	v_mfma_f32_16x16x32_bf16 v[70:73], v[160:163], v[208:211], v[70:73]
	v_mfma_f32_16x16x32_bf16 v[126:129], v[156:159], v[188:191], v[126:129]
	v_mfma_f32_16x16x32_bf16 v[118:121], v[164:167], v[188:191], v[118:121]
	v_mfma_f32_16x16x32_bf16 v[110:113], v[156:159], v[196:199], v[110:113]
	v_mfma_f32_16x16x32_bf16 v[102:105], v[164:167], v[196:199], v[102:105]
	v_mfma_f32_16x16x32_bf16 v[94:97], v[156:159], v[204:207], v[94:97]
	v_mfma_f32_16x16x32_bf16 v[86:89], v[164:167], v[204:207], v[86:89]
	v_mfma_f32_16x16x32_bf16 v[78:81], v[156:159], v[212:215], v[78:81]
	v_mfma_f32_16x16x32_bf16 v[70:73], v[164:167], v[212:215], v[70:73]
	s_setprio 0
	s_setprio 1
	v_mfma_f32_16x16x32_bf16 v[122:125], v[168:171], v[184:187], v[122:125]
	v_mfma_f32_16x16x32_bf16 v[114:117], v[176:179], v[184:187], v[114:117]
	v_mfma_f32_16x16x32_bf16 v[106:109], v[168:171], v[192:195], v[106:109]
	v_mfma_f32_16x16x32_bf16 v[98:101], v[176:179], v[192:195], v[98:101]
	v_mfma_f32_16x16x32_bf16 v[90:93], v[168:171], v[200:203], v[90:93]
	v_mfma_f32_16x16x32_bf16 v[82:85], v[176:179], v[200:203], v[82:85]
	v_mfma_f32_16x16x32_bf16 v[74:77], v[168:171], v[208:211], v[74:77]
	v_mfma_f32_16x16x32_bf16 v[66:69], v[176:179], v[208:211], v[66:69]
	v_mfma_f32_16x16x32_bf16 v[122:125], v[172:175], v[188:191], v[122:125]
	v_mfma_f32_16x16x32_bf16 v[114:117], v[180:183], v[188:191], v[114:117]
	v_mfma_f32_16x16x32_bf16 v[106:109], v[172:175], v[196:199], v[106:109]
	v_mfma_f32_16x16x32_bf16 v[98:101], v[180:183], v[196:199], v[98:101]
	v_mfma_f32_16x16x32_bf16 v[90:93], v[172:175], v[204:207], v[90:93]
	v_mfma_f32_16x16x32_bf16 v[82:85], v[180:183], v[204:207], v[82:85]
	v_mfma_f32_16x16x32_bf16 v[74:77], v[172:175], v[212:215], v[74:77]
	v_mfma_f32_16x16x32_bf16 v[66:69], v[180:183], v[212:215], v[66:69]
	s_setprio 0
	s_barrier
	s_add_i32 s53, s71, s30
	v_lshl_add_u64 v[218:219], s[34:35], 0, v[134:135]
	s_mov_b32 m0, s53
	ds_read_b128 v[184:187], v155 offset:16384
	ds_read_b128 v[188:191], v155 offset:17408
	ds_read_b128 v[192:195], v155 offset:18432
	ds_read_b128 v[196:199], v155 offset:19456
	ds_read_b128 v[200:203], v155 offset:20480
	ds_read_b128 v[204:207], v155 offset:21504
	ds_read_b128 v[208:211], v155 offset:22528
	ds_read_b128 v[212:215], v155 offset:23552
	global_load_lds_dwordx4 v[218:219], off
	s_add_i32 m0, s53, 0x2000
	s_add_u32 s54, s34, 0x80000
	v_lshl_add_u64 v[220:221], s[34:35], 0, v[130:131]
	s_addc_u32 s55, s35, 0
	s_add_i32 s53, s72, s30
	global_load_lds_dwordx4 v[220:221], off
	v_lshl_add_u64 v[222:223], s[54:55], 0, v[134:135]
	s_mov_b32 m0, s53
	v_lshl_add_u64 v[224:225], s[78:79], 0, v[132:133]
	global_load_lds_dwordx4 v[222:223], off
	v_lshl_add_u64 v[222:223], s[54:55], 0, v[130:131]
	s_add_i32 m0, s53, 0x2000
	s_nop 0
	global_load_lds_dwordx4 v[222:223], off
	v_lshl_add_u64 v[222:223], s[78:79], 0, v[136:137]
	s_mov_b32 m0, s47
	s_nop 0
	global_load_lds_dwordx4 v[222:223], off
	s_mov_b32 m0, s56
	s_nop 0
	global_load_lds_dwordx4 v[224:225], off
	s_waitcnt vmcnt(8)
	s_waitcnt lgkmcnt(0)
	s_barrier
	s_setprio 1
	s_waitcnt lgkmcnt(0)
	v_mfma_f32_16x16x32_bf16 v[62:65], v[146:149], v[184:187], v[62:65]
	v_mfma_f32_16x16x32_bf16 v[54:57], v[160:163], v[184:187], v[54:57]
	v_mfma_f32_16x16x32_bf16 v[46:49], v[146:149], v[192:195], v[46:49]
	v_mfma_f32_16x16x32_bf16 v[38:41], v[160:163], v[192:195], v[38:41]
	v_mfma_f32_16x16x32_bf16 v[30:33], v[146:149], v[200:203], v[30:33]
	v_mfma_f32_16x16x32_bf16 v[22:25], v[160:163], v[200:203], v[22:25]
	v_mfma_f32_16x16x32_bf16 v[14:17], v[146:149], v[208:211], v[14:17]
	v_mfma_f32_16x16x32_bf16 v[6:9], v[160:163], v[208:211], v[6:9]
	v_mfma_f32_16x16x32_bf16 v[62:65], v[156:159], v[188:191], v[62:65]
	v_mfma_f32_16x16x32_bf16 v[54:57], v[164:167], v[188:191], v[54:57]
	v_mfma_f32_16x16x32_bf16 v[46:49], v[156:159], v[196:199], v[46:49]
	v_mfma_f32_16x16x32_bf16 v[38:41], v[164:167], v[196:199], v[38:41]
	v_mfma_f32_16x16x32_bf16 v[30:33], v[156:159], v[204:207], v[30:33]
	v_mfma_f32_16x16x32_bf16 v[22:25], v[164:167], v[204:207], v[22:25]
	v_mfma_f32_16x16x32_bf16 v[14:17], v[156:159], v[212:215], v[14:17]
	v_mfma_f32_16x16x32_bf16 v[6:9], v[164:167], v[212:215], v[6:9]
	s_setprio 0
	s_setprio 1
	v_mfma_f32_16x16x32_bf16 v[58:61], v[168:171], v[184:187], v[58:61]
	v_mfma_f32_16x16x32_bf16 v[50:53], v[176:179], v[184:187], v[50:53]
	v_mfma_f32_16x16x32_bf16 v[42:45], v[168:171], v[192:195], v[42:45]
	v_mfma_f32_16x16x32_bf16 v[34:37], v[176:179], v[192:195], v[34:37]
	v_mfma_f32_16x16x32_bf16 v[26:29], v[168:171], v[200:203], v[26:29]
	v_mfma_f32_16x16x32_bf16 v[18:21], v[176:179], v[200:203], v[18:21]
	v_mfma_f32_16x16x32_bf16 v[10:13], v[168:171], v[208:211], v[10:13]
	v_mfma_f32_16x16x32_bf16 v[2:5], v[176:179], v[208:211], v[2:5]
	v_mfma_f32_16x16x32_bf16 v[58:61], v[172:175], v[188:191], v[58:61]
	v_mfma_f32_16x16x32_bf16 v[50:53], v[180:183], v[188:191], v[50:53]
	v_mfma_f32_16x16x32_bf16 v[42:45], v[172:175], v[196:199], v[42:45]
	v_mfma_f32_16x16x32_bf16 v[34:37], v[180:183], v[196:199], v[34:37]
	v_mfma_f32_16x16x32_bf16 v[26:29], v[172:175], v[204:207], v[26:29]
	v_mfma_f32_16x16x32_bf16 v[18:21], v[180:183], v[204:207], v[18:21]
	v_mfma_f32_16x16x32_bf16 v[10:13], v[172:175], v[212:215], v[10:13]
	v_mfma_f32_16x16x32_bf16 v[2:5], v[180:183], v[212:215], v[2:5]
	s_setprio 0
	s_barrier
	s_add_i32 s53, 0, 0x18000
	s_add_i32 s62, 0, 0x1c000
	v_add_u32_e32 v164, s53, v151
	v_add_u32_e32 v180, s62, v151
	ds_read_b128 v[146:149], v164
	ds_read_b128 v[156:159], v164 offset:1024
	ds_read_b128 v[160:163], v164 offset:2048
	ds_read_b128 v[164:167], v164 offset:3072
	ds_read_b128 v[168:171], v180
	ds_read_b128 v[172:175], v180 offset:1024
	ds_read_b128 v[176:179], v180 offset:2048
	ds_read_b128 v[180:183], v180 offset:3072
	s_add_u32 s54, s78, 0x80000
	s_addc_u32 s55, s79, 0
	s_mov_b32 m0, s57
	v_lshl_add_u64 v[226:227], s[54:55], 0, v[136:137]
	ds_read_b128 v[184:187], v155 offset:32768
	ds_read_b128 v[188:191], v155 offset:33792
	ds_read_b128 v[192:195], v155 offset:34816
	ds_read_b128 v[196:199], v155 offset:35840
	ds_read_b128 v[200:203], v155 offset:36864
	ds_read_b128 v[204:207], v155 offset:37888
	ds_read_b128 v[208:211], v155 offset:38912
	ds_read_b128 v[212:215], v155 offset:39936
	global_load_lds_dwordx4 v[226:227], off
	v_lshl_add_u64 v[226:227], s[54:55], 0, v[132:133]
	s_mov_b32 m0, s58
	s_nop 0
	global_load_lds_dwordx4 v[226:227], off
	s_waitcnt vmcnt(8)
	s_waitcnt lgkmcnt(0)
	s_barrier
	s_setprio 1
	s_waitcnt lgkmcnt(0)
	v_mfma_f32_16x16x32_bf16 v[126:129], v[146:149], v[184:187], v[126:129]
	v_mfma_f32_16x16x32_bf16 v[118:121], v[160:163], v[184:187], v[118:121]
	v_mfma_f32_16x16x32_bf16 v[110:113], v[146:149], v[192:195], v[110:113]
	v_mfma_f32_16x16x32_bf16 v[102:105], v[160:163], v[192:195], v[102:105]
	v_mfma_f32_16x16x32_bf16 v[94:97], v[146:149], v[200:203], v[94:97]
	v_mfma_f32_16x16x32_bf16 v[86:89], v[160:163], v[200:203], v[86:89]
	v_mfma_f32_16x16x32_bf16 v[78:81], v[146:149], v[208:211], v[78:81]
	v_mfma_f32_16x16x32_bf16 v[70:73], v[160:163], v[208:211], v[70:73]
	v_mfma_f32_16x16x32_bf16 v[126:129], v[156:159], v[188:191], v[126:129]
	v_mfma_f32_16x16x32_bf16 v[118:121], v[164:167], v[188:191], v[118:121]
	v_mfma_f32_16x16x32_bf16 v[110:113], v[156:159], v[196:199], v[110:113]
	v_mfma_f32_16x16x32_bf16 v[102:105], v[164:167], v[196:199], v[102:105]
	v_mfma_f32_16x16x32_bf16 v[94:97], v[156:159], v[204:207], v[94:97]
	v_mfma_f32_16x16x32_bf16 v[86:89], v[164:167], v[204:207], v[86:89]
	v_mfma_f32_16x16x32_bf16 v[78:81], v[156:159], v[212:215], v[78:81]
	v_mfma_f32_16x16x32_bf16 v[70:73], v[164:167], v[212:215], v[70:73]
	s_setprio 0
	s_setprio 1
	v_mfma_f32_16x16x32_bf16 v[122:125], v[168:171], v[184:187], v[122:125]
	v_mfma_f32_16x16x32_bf16 v[114:117], v[176:179], v[184:187], v[114:117]
	v_mfma_f32_16x16x32_bf16 v[106:109], v[168:171], v[192:195], v[106:109]
	v_mfma_f32_16x16x32_bf16 v[98:101], v[176:179], v[192:195], v[98:101]
	v_mfma_f32_16x16x32_bf16 v[90:93], v[168:171], v[200:203], v[90:93]
	v_mfma_f32_16x16x32_bf16 v[82:85], v[176:179], v[200:203], v[82:85]
	v_mfma_f32_16x16x32_bf16 v[74:77], v[168:171], v[208:211], v[74:77]
	v_mfma_f32_16x16x32_bf16 v[66:69], v[176:179], v[208:211], v[66:69]
	v_mfma_f32_16x16x32_bf16 v[122:125], v[172:175], v[188:191], v[122:125]
	v_mfma_f32_16x16x32_bf16 v[114:117], v[180:183], v[188:191], v[114:117]
	v_mfma_f32_16x16x32_bf16 v[106:109], v[172:175], v[196:199], v[106:109]
	v_mfma_f32_16x16x32_bf16 v[98:101], v[180:183], v[196:199], v[98:101]
	v_mfma_f32_16x16x32_bf16 v[90:93], v[172:175], v[204:207], v[90:93]
	v_mfma_f32_16x16x32_bf16 v[82:85], v[180:183], v[204:207], v[82:85]
	v_mfma_f32_16x16x32_bf16 v[74:77], v[172:175], v[212:215], v[74:77]
	v_mfma_f32_16x16x32_bf16 v[66:69], v[180:183], v[212:215], v[66:69]
	s_setprio 0
	s_barrier
	s_add_i32 s53, s53, s30
	v_lshl_add_u64 v[218:219], v[218:219], 0, s[8:9]
	s_mov_b32 m0, s53
	ds_read_b128 v[184:187], v155 offset:49152
	ds_read_b128 v[188:191], v155 offset:50176
	ds_read_b128 v[192:195], v155 offset:51200
	ds_read_b128 v[196:199], v155 offset:52224
	ds_read_b128 v[200:203], v155 offset:53248
	ds_read_b128 v[204:207], v155 offset:54272
	ds_read_b128 v[208:211], v155 offset:55296
	ds_read_b128 v[212:215], v155 offset:56320
	global_load_lds_dwordx4 v[218:219], off
	s_add_i32 m0, s53, 0x2000
	s_add_u32 s34, s34, 0x80080
	v_lshl_add_u64 v[218:219], v[220:221], 0, s[8:9]
	s_addc_u32 s35, s35, 0
	s_add_i32 s53, s62, s30
	global_load_lds_dwordx4 v[218:219], off
	v_lshl_add_u64 v[218:219], s[34:35], 0, v[134:135]
	s_mov_b32 m0, s53
	s_nop 0
	global_load_lds_dwordx4 v[218:219], off
	v_lshl_add_u64 v[218:219], s[34:35], 0, v[130:131]
	s_add_i32 m0, s53, 0x2000
	s_nop 0
	global_load_lds_dwordx4 v[218:219], off
	v_lshl_add_u64 v[218:219], v[222:223], 0, s[8:9]
	s_mov_b32 m0, s60
	s_nop 0
	global_load_lds_dwordx4 v[218:219], off
	v_lshl_add_u64 v[218:219], v[224:225], 0, s[8:9]
	s_mov_b32 m0, s61
	s_nop 0
	global_load_lds_dwordx4 v[218:219], off
	s_waitcnt vmcnt(8)
	s_waitcnt lgkmcnt(0)
	s_barrier
	s_setprio 1
	s_waitcnt lgkmcnt(0)
	v_mfma_f32_16x16x32_bf16 v[62:65], v[146:149], v[184:187], v[62:65]
	v_mfma_f32_16x16x32_bf16 v[54:57], v[160:163], v[184:187], v[54:57]
	v_mfma_f32_16x16x32_bf16 v[46:49], v[146:149], v[192:195], v[46:49]
	v_mfma_f32_16x16x32_bf16 v[38:41], v[160:163], v[192:195], v[38:41]
	v_mfma_f32_16x16x32_bf16 v[30:33], v[146:149], v[200:203], v[30:33]
	v_mfma_f32_16x16x32_bf16 v[22:25], v[160:163], v[200:203], v[22:25]
	v_mfma_f32_16x16x32_bf16 v[14:17], v[146:149], v[208:211], v[14:17]
	v_mfma_f32_16x16x32_bf16 v[6:9], v[160:163], v[208:211], v[6:9]
	v_mfma_f32_16x16x32_bf16 v[62:65], v[156:159], v[188:191], v[62:65]
	v_mfma_f32_16x16x32_bf16 v[54:57], v[164:167], v[188:191], v[54:57]
	v_mfma_f32_16x16x32_bf16 v[46:49], v[156:159], v[196:199], v[46:49]
	v_mfma_f32_16x16x32_bf16 v[38:41], v[164:167], v[196:199], v[38:41]
	v_mfma_f32_16x16x32_bf16 v[30:33], v[156:159], v[204:207], v[30:33]
	v_mfma_f32_16x16x32_bf16 v[22:25], v[164:167], v[204:207], v[22:25]
	v_mfma_f32_16x16x32_bf16 v[14:17], v[156:159], v[212:215], v[14:17]
	v_mfma_f32_16x16x32_bf16 v[6:9], v[164:167], v[212:215], v[6:9]
	s_setprio 0
	s_setprio 1
	v_mfma_f32_16x16x32_bf16 v[58:61], v[168:171], v[184:187], v[58:61]
	v_mfma_f32_16x16x32_bf16 v[50:53], v[176:179], v[184:187], v[50:53]
	v_mfma_f32_16x16x32_bf16 v[42:45], v[168:171], v[192:195], v[42:45]
	v_mfma_f32_16x16x32_bf16 v[34:37], v[176:179], v[192:195], v[34:37]
	v_mfma_f32_16x16x32_bf16 v[26:29], v[168:171], v[200:203], v[26:29]
	v_mfma_f32_16x16x32_bf16 v[18:21], v[176:179], v[200:203], v[18:21]
	v_mfma_f32_16x16x32_bf16 v[10:13], v[168:171], v[208:211], v[10:13]
	v_mfma_f32_16x16x32_bf16 v[2:5], v[176:179], v[208:211], v[2:5]
	v_mfma_f32_16x16x32_bf16 v[58:61], v[172:175], v[188:191], v[58:61]
	v_mfma_f32_16x16x32_bf16 v[50:53], v[180:183], v[188:191], v[50:53]
	v_mfma_f32_16x16x32_bf16 v[42:45], v[172:175], v[196:199], v[42:45]
	v_mfma_f32_16x16x32_bf16 v[34:37], v[180:183], v[196:199], v[34:37]
	v_mfma_f32_16x16x32_bf16 v[26:29], v[172:175], v[204:207], v[26:29]
	v_mfma_f32_16x16x32_bf16 v[18:21], v[180:183], v[204:207], v[18:21]
	v_mfma_f32_16x16x32_bf16 v[10:13], v[172:175], v[212:215], v[10:13]
	v_mfma_f32_16x16x32_bf16 v[2:5], v[180:183], v[212:215], v[2:5]
	s_setprio 0
	s_barrier
	s_add_i32 s80, s80, 2
	s_add_u32 s76, s76, 0x100
	s_addc_u32 s77, s77, 0
	s_add_u32 s52, s52, 0x100
	s_addc_u32 s75, s75, 0
	s_cmp_gt_u32 s80, 29
	s_cbranch_scc0 .LBB0_2218
	v_mov_b32_e32 v160, 0xbfb8aa3b
	s_and_b64 vcc, exec, s[24:25]
	s_cbranch_vccz .LBB0_2221
	s_barrier
.LBB0_2221:
	v_readlane_b32 s0, v247, 31
	v_lshl_or_b32 v146, s74, 7, v152
	v_readlane_b32 s1, v247, 32
	v_lshl_add_u32 v156, s46, 8, v1
	v_ashrrev_i32_e32 v147, 31, v146
	v_mov_b64_e32 v[148:149], s[0:1]
	v_mad_i64_i32 v[158:159], s[0:1], v156, s73, v[148:149]
	v_lshlrev_b64 v[146:147], 1, v[146:147]
	v_lshl_add_u64 v[158:159], v[158:159], 0, v[146:147]
	v_pk_mul_f32 v[122:123], v[126:127], v[122:123]
	v_pk_mul_f32 v[124:125], v[128:129], v[124:125]
	v_pk_mul_f32 v[114:115], v[118:119], v[114:115]
	v_pk_mul_f32 v[116:117], v[120:121], v[116:117]
	v_pk_mul_f32 v[126:127], v[126:127], v[160:161] op_sel_hi:[1,0]
	v_pk_mul_f32 v[128:129], v[128:129], v[160:161] op_sel_hi:[1,0]
	v_pk_mul_f32 v[118:119], v[118:119], v[160:161] op_sel_hi:[1,0]
	v_pk_mul_f32 v[120:121], v[120:121], v[160:161] op_sel_hi:[1,0]
	v_exp_f32_e32 v126, v126
	v_exp_f32_e32 v127, v127
	v_exp_f32_e32 v128, v128
	v_exp_f32_e32 v129, v129
	v_exp_f32_e32 v118, v118
	v_exp_f32_e32 v119, v119
	v_exp_f32_e32 v120, v120
	v_exp_f32_e32 v121, v121
	v_pk_add_f32 v[126:127], v[126:127], 1.0 op_sel_hi:[1,0]
	v_pk_add_f32 v[128:129], v[128:129], 1.0 op_sel_hi:[1,0]
	v_pk_add_f32 v[118:119], v[118:119], 1.0 op_sel_hi:[1,0]
	v_pk_add_f32 v[120:121], v[120:121], 1.0 op_sel_hi:[1,0]
	v_rcp_f32_e32 v126, v126
	v_rcp_f32_e32 v127, v127
	v_rcp_f32_e32 v128, v128
	v_rcp_f32_e32 v129, v129
	v_rcp_f32_e32 v118, v118
	v_rcp_f32_e32 v119, v119
	v_rcp_f32_e32 v120, v120
	v_rcp_f32_e32 v121, v121
	v_pk_mul_f32 v[122:123], v[126:127], v[122:123]
	v_pk_mul_f32 v[124:125], v[128:129], v[124:125]
	v_pk_mul_f32 v[114:115], v[118:119], v[114:115]
	v_pk_mul_f32 v[116:117], v[120:121], v[116:117]
	v_cvt_pk_bf16_f32 v122, v122, v123
	v_cvt_pk_bf16_f32 v123, v124, v125
	v_cvt_pk_bf16_f32 v124, v114, v115
	v_cvt_pk_bf16_f32 v125, v116, v117
	global_store_dwordx4 v[158:159], v[122:125], off
	v_or_b32_e32 v114, 16, v156
	v_mad_i64_i32 v[114:115], s[0:1], v114, s73, v[148:149]
	v_lshl_add_u64 v[114:115], v[114:115], 0, v[146:147]
	v_pk_mul_f32 v[106:107], v[110:111], v[106:107]
	v_pk_mul_f32 v[108:109], v[112:113], v[108:109]
	v_pk_mul_f32 v[98:99], v[102:103], v[98:99]
	v_pk_mul_f32 v[100:101], v[104:105], v[100:101]
	v_pk_mul_f32 v[110:111], v[110:111], v[160:161] op_sel_hi:[1,0]
	v_pk_mul_f32 v[112:113], v[112:113], v[160:161] op_sel_hi:[1,0]
	v_pk_mul_f32 v[102:103], v[102:103], v[160:161] op_sel_hi:[1,0]
	v_pk_mul_f32 v[104:105], v[104:105], v[160:161] op_sel_hi:[1,0]
	v_exp_f32_e32 v110, v110
	v_exp_f32_e32 v111, v111
	v_exp_f32_e32 v112, v112
	v_exp_f32_e32 v113, v113
	v_exp_f32_e32 v102, v102
	v_exp_f32_e32 v103, v103
	v_exp_f32_e32 v104, v104
	v_exp_f32_e32 v105, v105
	v_pk_add_f32 v[110:111], v[110:111], 1.0 op_sel_hi:[1,0]
	v_pk_add_f32 v[112:113], v[112:113], 1.0 op_sel_hi:[1,0]
	v_pk_add_f32 v[102:103], v[102:103], 1.0 op_sel_hi:[1,0]
	v_pk_add_f32 v[104:105], v[104:105], 1.0 op_sel_hi:[1,0]
	v_rcp_f32_e32 v110, v110
	v_rcp_f32_e32 v111, v111
	v_rcp_f32_e32 v112, v112
	v_rcp_f32_e32 v113, v113
	v_rcp_f32_e32 v102, v102
	v_rcp_f32_e32 v103, v103
	v_rcp_f32_e32 v104, v104
	v_rcp_f32_e32 v105, v105
	v_pk_mul_f32 v[106:107], v[110:111], v[106:107]
	v_pk_mul_f32 v[108:109], v[112:113], v[108:109]
	v_pk_mul_f32 v[98:99], v[102:103], v[98:99]
	v_pk_mul_f32 v[100:101], v[104:105], v[100:101]
	v_cvt_pk_bf16_f32 v106, v106, v107
	v_cvt_pk_bf16_f32 v107, v108, v109
	v_cvt_pk_bf16_f32 v108, v98, v99
	v_cvt_pk_bf16_f32 v109, v100, v101
	global_store_dwordx4 v[114:115], v[106:109], off
	v_or_b32_e32 v98, 32, v156
	v_mad_i64_i32 v[98:99], s[0:1], v98, s73, v[148:149]
	v_lshl_add_u64 v[98:99], v[98:99], 0, v[146:147]
	v_pk_mul_f32 v[90:91], v[94:95], v[90:91]
	v_pk_mul_f32 v[92:93], v[96:97], v[92:93]
	v_pk_mul_f32 v[82:83], v[86:87], v[82:83]
	v_pk_mul_f32 v[84:85], v[88:89], v[84:85]
	v_pk_mul_f32 v[94:95], v[94:95], v[160:161] op_sel_hi:[1,0]
	v_pk_mul_f32 v[96:97], v[96:97], v[160:161] op_sel_hi:[1,0]
	v_pk_mul_f32 v[86:87], v[86:87], v[160:161] op_sel_hi:[1,0]
	v_pk_mul_f32 v[88:89], v[88:89], v[160:161] op_sel_hi:[1,0]
	v_exp_f32_e32 v94, v94
	v_exp_f32_e32 v95, v95
	v_exp_f32_e32 v96, v96
	v_exp_f32_e32 v97, v97
	v_exp_f32_e32 v86, v86
	v_exp_f32_e32 v87, v87
	v_exp_f32_e32 v88, v88
	v_exp_f32_e32 v89, v89
	v_pk_add_f32 v[94:95], v[94:95], 1.0 op_sel_hi:[1,0]
	v_pk_add_f32 v[96:97], v[96:97], 1.0 op_sel_hi:[1,0]
	v_pk_add_f32 v[86:87], v[86:87], 1.0 op_sel_hi:[1,0]
	v_pk_add_f32 v[88:89], v[88:89], 1.0 op_sel_hi:[1,0]
	v_rcp_f32_e32 v94, v94
	v_rcp_f32_e32 v95, v95
	v_rcp_f32_e32 v96, v96
	v_rcp_f32_e32 v97, v97
	v_rcp_f32_e32 v86, v86
	v_rcp_f32_e32 v87, v87
	v_rcp_f32_e32 v88, v88
	v_rcp_f32_e32 v89, v89
	v_pk_mul_f32 v[90:91], v[94:95], v[90:91]
	v_pk_mul_f32 v[92:93], v[96:97], v[92:93]
	v_pk_mul_f32 v[82:83], v[86:87], v[82:83]
	v_pk_mul_f32 v[84:85], v[88:89], v[84:85]
	v_cvt_pk_bf16_f32 v90, v90, v91
	v_cvt_pk_bf16_f32 v91, v92, v93
	v_cvt_pk_bf16_f32 v92, v82, v83
	v_cvt_pk_bf16_f32 v93, v84, v85
	global_store_dwordx4 v[98:99], v[90:93], off
	v_or_b32_e32 v82, 48, v156
	v_mad_i64_i32 v[82:83], s[0:1], v82, s73, v[148:149]
	v_lshl_add_u64 v[82:83], v[82:83], 0, v[146:147]
	v_pk_mul_f32 v[74:75], v[78:79], v[74:75]
	v_pk_mul_f32 v[76:77], v[80:81], v[76:77]
	v_pk_mul_f32 v[66:67], v[70:71], v[66:67]
	v_pk_mul_f32 v[68:69], v[72:73], v[68:69]
	v_pk_mul_f32 v[78:79], v[78:79], v[160:161] op_sel_hi:[1,0]
	v_pk_mul_f32 v[80:81], v[80:81], v[160:161] op_sel_hi:[1,0]
	v_pk_mul_f32 v[70:71], v[70:71], v[160:161] op_sel_hi:[1,0]
	v_pk_mul_f32 v[72:73], v[72:73], v[160:161] op_sel_hi:[1,0]
	v_exp_f32_e32 v78, v78
	v_exp_f32_e32 v79, v79
	v_exp_f32_e32 v80, v80
	v_exp_f32_e32 v81, v81
	v_exp_f32_e32 v70, v70
	v_exp_f32_e32 v71, v71
	v_exp_f32_e32 v72, v72
	v_exp_f32_e32 v73, v73
	v_pk_add_f32 v[78:79], v[78:79], 1.0 op_sel_hi:[1,0]
	v_pk_add_f32 v[80:81], v[80:81], 1.0 op_sel_hi:[1,0]
	v_pk_add_f32 v[70:71], v[70:71], 1.0 op_sel_hi:[1,0]
	v_pk_add_f32 v[72:73], v[72:73], 1.0 op_sel_hi:[1,0]
	v_rcp_f32_e32 v78, v78
	v_rcp_f32_e32 v79, v79
	v_rcp_f32_e32 v80, v80
	v_rcp_f32_e32 v81, v81
	v_rcp_f32_e32 v70, v70
	v_rcp_f32_e32 v71, v71
	v_rcp_f32_e32 v72, v72
	v_rcp_f32_e32 v73, v73
	v_pk_mul_f32 v[74:75], v[78:79], v[74:75]
	v_pk_mul_f32 v[76:77], v[80:81], v[76:77]
	v_pk_mul_f32 v[66:67], v[70:71], v[66:67]
	v_pk_mul_f32 v[68:69], v[72:73], v[68:69]
	v_cvt_pk_bf16_f32 v74, v74, v75
	v_cvt_pk_bf16_f32 v75, v76, v77
	v_cvt_pk_bf16_f32 v76, v66, v67
	v_cvt_pk_bf16_f32 v77, v68, v69
	global_store_dwordx4 v[82:83], v[74:77], off
	v_add_u32_e32 v66, 0x80, v156
	v_mad_i64_i32 v[66:67], s[0:1], v66, s73, v[148:149]
	v_lshl_add_u64 v[66:67], v[66:67], 0, v[146:147]
	v_pk_mul_f32 v[58:59], v[62:63], v[58:59]
	v_pk_mul_f32 v[60:61], v[64:65], v[60:61]
	v_pk_mul_f32 v[50:51], v[54:55], v[50:51]
	v_pk_mul_f32 v[52:53], v[56:57], v[52:53]
	v_pk_mul_f32 v[62:63], v[62:63], v[160:161] op_sel_hi:[1,0]
	v_pk_mul_f32 v[64:65], v[64:65], v[160:161] op_sel_hi:[1,0]
	v_pk_mul_f32 v[54:55], v[54:55], v[160:161] op_sel_hi:[1,0]
	v_pk_mul_f32 v[56:57], v[56:57], v[160:161] op_sel_hi:[1,0]
	v_exp_f32_e32 v62, v62
	v_exp_f32_e32 v63, v63
	v_exp_f32_e32 v64, v64
	v_exp_f32_e32 v65, v65
	v_exp_f32_e32 v54, v54
	v_exp_f32_e32 v55, v55
	v_exp_f32_e32 v56, v56
	v_exp_f32_e32 v57, v57
	v_pk_add_f32 v[62:63], v[62:63], 1.0 op_sel_hi:[1,0]
	v_pk_add_f32 v[64:65], v[64:65], 1.0 op_sel_hi:[1,0]
	v_pk_add_f32 v[54:55], v[54:55], 1.0 op_sel_hi:[1,0]
	v_pk_add_f32 v[56:57], v[56:57], 1.0 op_sel_hi:[1,0]
	v_rcp_f32_e32 v62, v62
	v_rcp_f32_e32 v63, v63
	v_rcp_f32_e32 v64, v64
	v_rcp_f32_e32 v65, v65
	v_rcp_f32_e32 v54, v54
	v_rcp_f32_e32 v55, v55
	v_rcp_f32_e32 v56, v56
	v_rcp_f32_e32 v57, v57
	v_pk_mul_f32 v[58:59], v[62:63], v[58:59]
	v_pk_mul_f32 v[60:61], v[64:65], v[60:61]
	v_pk_mul_f32 v[50:51], v[54:55], v[50:51]
	v_pk_mul_f32 v[52:53], v[56:57], v[52:53]
	v_cvt_pk_bf16_f32 v58, v58, v59
	v_cvt_pk_bf16_f32 v59, v60, v61
	v_cvt_pk_bf16_f32 v60, v50, v51
	v_cvt_pk_bf16_f32 v61, v52, v53
	global_store_dwordx4 v[66:67], v[58:61], off
	v_add_u32_e32 v50, 0x90, v156
	v_mad_i64_i32 v[50:51], s[0:1], v50, s73, v[148:149]
	v_lshl_add_u64 v[50:51], v[50:51], 0, v[146:147]
	v_pk_mul_f32 v[42:43], v[46:47], v[42:43]
	v_pk_mul_f32 v[44:45], v[48:49], v[44:45]
	v_pk_mul_f32 v[34:35], v[38:39], v[34:35]
	v_pk_mul_f32 v[36:37], v[40:41], v[36:37]
	v_pk_mul_f32 v[46:47], v[46:47], v[160:161] op_sel_hi:[1,0]
	v_pk_mul_f32 v[48:49], v[48:49], v[160:161] op_sel_hi:[1,0]
	v_pk_mul_f32 v[38:39], v[38:39], v[160:161] op_sel_hi:[1,0]
	v_pk_mul_f32 v[40:41], v[40:41], v[160:161] op_sel_hi:[1,0]
	v_exp_f32_e32 v46, v46
	v_exp_f32_e32 v47, v47
	v_exp_f32_e32 v48, v48
	v_exp_f32_e32 v49, v49
	v_exp_f32_e32 v38, v38
	v_exp_f32_e32 v39, v39
	v_exp_f32_e32 v40, v40
	v_exp_f32_e32 v41, v41
	v_pk_add_f32 v[46:47], v[46:47], 1.0 op_sel_hi:[1,0]
	v_pk_add_f32 v[48:49], v[48:49], 1.0 op_sel_hi:[1,0]
	v_pk_add_f32 v[38:39], v[38:39], 1.0 op_sel_hi:[1,0]
	v_pk_add_f32 v[40:41], v[40:41], 1.0 op_sel_hi:[1,0]
	v_rcp_f32_e32 v46, v46
	v_rcp_f32_e32 v47, v47
	v_rcp_f32_e32 v48, v48
	v_rcp_f32_e32 v49, v49
	v_rcp_f32_e32 v38, v38
	v_rcp_f32_e32 v39, v39
	v_rcp_f32_e32 v40, v40
	v_rcp_f32_e32 v41, v41
	v_pk_mul_f32 v[42:43], v[46:47], v[42:43]
	v_pk_mul_f32 v[44:45], v[48:49], v[44:45]
	v_pk_mul_f32 v[34:35], v[38:39], v[34:35]
	v_pk_mul_f32 v[36:37], v[40:41], v[36:37]
	v_cvt_pk_bf16_f32 v42, v42, v43
	v_cvt_pk_bf16_f32 v43, v44, v45
	v_cvt_pk_bf16_f32 v44, v34, v35
	v_cvt_pk_bf16_f32 v45, v36, v37
	global_store_dwordx4 v[50:51], v[42:45], off
	v_add_u32_e32 v34, 0xa0, v156
	v_mad_i64_i32 v[34:35], s[0:1], v34, s73, v[148:149]
	v_lshl_add_u64 v[34:35], v[34:35], 0, v[146:147]
	v_pk_mul_f32 v[26:27], v[30:31], v[26:27]
	v_pk_mul_f32 v[28:29], v[32:33], v[28:29]
	v_pk_mul_f32 v[18:19], v[22:23], v[18:19]
	v_pk_mul_f32 v[20:21], v[24:25], v[20:21]
	v_pk_mul_f32 v[30:31], v[30:31], v[160:161] op_sel_hi:[1,0]
	v_pk_mul_f32 v[32:33], v[32:33], v[160:161] op_sel_hi:[1,0]
	v_pk_mul_f32 v[22:23], v[22:23], v[160:161] op_sel_hi:[1,0]
	v_pk_mul_f32 v[24:25], v[24:25], v[160:161] op_sel_hi:[1,0]
	v_exp_f32_e32 v30, v30
	v_exp_f32_e32 v31, v31
	v_exp_f32_e32 v32, v32
	v_exp_f32_e32 v33, v33
	v_exp_f32_e32 v22, v22
	v_exp_f32_e32 v23, v23
	v_exp_f32_e32 v24, v24
	v_exp_f32_e32 v25, v25
	v_pk_add_f32 v[30:31], v[30:31], 1.0 op_sel_hi:[1,0]
	v_pk_add_f32 v[32:33], v[32:33], 1.0 op_sel_hi:[1,0]
	v_pk_add_f32 v[22:23], v[22:23], 1.0 op_sel_hi:[1,0]
	v_pk_add_f32 v[24:25], v[24:25], 1.0 op_sel_hi:[1,0]
	v_rcp_f32_e32 v30, v30
	v_rcp_f32_e32 v31, v31
	v_rcp_f32_e32 v32, v32
	v_rcp_f32_e32 v33, v33
	v_rcp_f32_e32 v22, v22
	v_rcp_f32_e32 v23, v23
	v_rcp_f32_e32 v24, v24
	v_rcp_f32_e32 v25, v25
	v_pk_mul_f32 v[26:27], v[30:31], v[26:27]
	v_pk_mul_f32 v[28:29], v[32:33], v[28:29]
	v_pk_mul_f32 v[18:19], v[22:23], v[18:19]
	v_pk_mul_f32 v[20:21], v[24:25], v[20:21]
	v_cvt_pk_bf16_f32 v26, v26, v27
	v_cvt_pk_bf16_f32 v27, v28, v29
	v_cvt_pk_bf16_f32 v28, v18, v19
	v_cvt_pk_bf16_f32 v29, v20, v21
	global_store_dwordx4 v[34:35], v[26:29], off
	v_add_u32_e32 v18, 0xb0, v156
	v_mad_i64_i32 v[18:19], s[0:1], v18, s73, v[148:149]
	v_lshl_add_u64 v[18:19], v[18:19], 0, v[146:147]
	s_andn2_b64 vcc, exec, s[2:3]
	s_mov_b64 s[0:1], -1
	v_pk_mul_f32 v[10:11], v[14:15], v[10:11]
	v_pk_mul_f32 v[12:13], v[16:17], v[12:13]
	v_pk_mul_f32 v[2:3], v[6:7], v[2:3]
	v_pk_mul_f32 v[4:5], v[8:9], v[4:5]
	v_pk_mul_f32 v[14:15], v[14:15], v[160:161] op_sel_hi:[1,0]
	v_pk_mul_f32 v[16:17], v[16:17], v[160:161] op_sel_hi:[1,0]
	v_pk_mul_f32 v[6:7], v[6:7], v[160:161] op_sel_hi:[1,0]
	v_pk_mul_f32 v[8:9], v[8:9], v[160:161] op_sel_hi:[1,0]
	v_exp_f32_e32 v14, v14
	v_exp_f32_e32 v15, v15
	v_exp_f32_e32 v16, v16
	v_exp_f32_e32 v17, v17
	v_exp_f32_e32 v6, v6
	v_exp_f32_e32 v7, v7
	v_exp_f32_e32 v8, v8
	v_exp_f32_e32 v9, v9
	v_pk_add_f32 v[14:15], v[14:15], 1.0 op_sel_hi:[1,0]
	v_pk_add_f32 v[16:17], v[16:17], 1.0 op_sel_hi:[1,0]
	v_pk_add_f32 v[6:7], v[6:7], 1.0 op_sel_hi:[1,0]
	v_pk_add_f32 v[8:9], v[8:9], 1.0 op_sel_hi:[1,0]
	v_rcp_f32_e32 v14, v14
	v_rcp_f32_e32 v15, v15
	v_rcp_f32_e32 v16, v16
	v_rcp_f32_e32 v17, v17
	v_rcp_f32_e32 v6, v6
	v_rcp_f32_e32 v7, v7
	v_rcp_f32_e32 v8, v8
	v_rcp_f32_e32 v9, v9
	v_pk_mul_f32 v[10:11], v[14:15], v[10:11]
	v_pk_mul_f32 v[12:13], v[16:17], v[12:13]
	v_pk_mul_f32 v[2:3], v[6:7], v[2:3]
	v_pk_mul_f32 v[4:5], v[8:9], v[4:5]
	v_cvt_pk_bf16_f32 v10, v10, v11
	v_cvt_pk_bf16_f32 v11, v12, v13
	v_cvt_pk_bf16_f32 v12, v2, v3
	v_cvt_pk_bf16_f32 v13, v4, v5
	global_store_dwordx4 v[18:19], v[10:13], off
	s_cbranch_vccnz .LBB0_2214
	s_andn2_b64 vcc, exec, s[6:7]
	s_cbranch_vccnz .LBB0_2213
	s_barrier
	s_branch .LBB0_2213

.LBB0_3067:
	ds_read_b128 v[146:149], v153
	ds_read_b128 v[156:159], v153 offset:1024
	ds_read_b128 v[160:163], v153 offset:2048
	ds_read_b128 v[164:167], v153 offset:3072
	ds_read_b128 v[168:171], v154
	ds_read_b128 v[172:175], v154 offset:1024
	ds_read_b128 v[176:179], v154 offset:2048
	ds_read_b128 v[180:183], v154 offset:3072
	s_add_u32 s34, s44, 0xfff80080
	s_addc_u32 s35, s45, -1
	s_cmp_eq_u32 s71, 28
	s_cselect_b32 s47, s0, s35
	s_cselect_b32 s46, s1, s34
	s_cselect_b32 s35, s27, s70
	s_cselect_b32 s34, s37, s69
	v_lshl_add_u64 v[218:219], s[44:45], 0, v[138:139]
	s_add_i32 m0, s43, 0xc000
	ds_read_b128 v[184:187], v155
	ds_read_b128 v[188:191], v155 offset:1024
	ds_read_b128 v[192:195], v155 offset:2048
	ds_read_b128 v[196:199], v155 offset:3072
	ds_read_b128 v[200:203], v155 offset:4096
	ds_read_b128 v[204:207], v155 offset:5120
	ds_read_b128 v[208:211], v155 offset:6144
	ds_read_b128 v[212:215], v155 offset:7168
	global_load_lds_dwordx4 v[218:219], off
	v_lshl_add_u64 v[218:219], s[44:45], 0, v[140:141]
	s_add_i32 m0, s43, 0xe000
	s_nop 0
	global_load_lds_dwordx4 v[218:219], off
	s_waitcnt vmcnt(8)
	s_waitcnt lgkmcnt(0)
	s_barrier
	s_setprio 1
	s_waitcnt lgkmcnt(0)
	v_mfma_f32_16x16x32_bf16 v[126:129], v[146:149], v[184:187], v[126:129]
	v_mfma_f32_16x16x32_bf16 v[118:121], v[160:163], v[184:187], v[118:121]
	v_mfma_f32_16x16x32_bf16 v[110:113], v[146:149], v[192:195], v[110:113]
	v_mfma_f32_16x16x32_bf16 v[102:105], v[160:163], v[192:195], v[102:105]
	v_mfma_f32_16x16x32_bf16 v[94:97], v[146:149], v[200:203], v[94:97]
	v_mfma_f32_16x16x32_bf16 v[86:89], v[160:163], v[200:203], v[86:89]
	v_mfma_f32_16x16x32_bf16 v[78:81], v[146:149], v[208:211], v[78:81]
	v_mfma_f32_16x16x32_bf16 v[70:73], v[160:163], v[208:211], v[70:73]
	v_mfma_f32_16x16x32_bf16 v[126:129], v[156:159], v[188:191], v[126:129]
	v_mfma_f32_16x16x32_bf16 v[118:121], v[164:167], v[188:191], v[118:121]
	v_mfma_f32_16x16x32_bf16 v[110:113], v[156:159], v[196:199], v[110:113]
	v_mfma_f32_16x16x32_bf16 v[102:105], v[164:167], v[196:199], v[102:105]
	v_mfma_f32_16x16x32_bf16 v[94:97], v[156:159], v[204:207], v[94:97]
	v_mfma_f32_16x16x32_bf16 v[86:89], v[164:167], v[204:207], v[86:89]
	v_mfma_f32_16x16x32_bf16 v[78:81], v[156:159], v[212:215], v[78:81]
	v_mfma_f32_16x16x32_bf16 v[70:73], v[164:167], v[212:215], v[70:73]
	s_setprio 0
	s_setprio 1
	v_mfma_f32_16x16x32_bf16 v[122:125], v[168:171], v[184:187], v[122:125]
	v_mfma_f32_16x16x32_bf16 v[114:117], v[176:179], v[184:187], v[114:117]
	v_mfma_f32_16x16x32_bf16 v[106:109], v[168:171], v[192:195], v[106:109]
	v_mfma_f32_16x16x32_bf16 v[98:101], v[176:179], v[192:195], v[98:101]
	v_mfma_f32_16x16x32_bf16 v[90:93], v[168:171], v[200:203], v[90:93]
	v_mfma_f32_16x16x32_bf16 v[82:85], v[176:179], v[200:203], v[82:85]
	v_mfma_f32_16x16x32_bf16 v[74:77], v[168:171], v[208:211], v[74:77]
	v_mfma_f32_16x16x32_bf16 v[66:69], v[176:179], v[208:211], v[66:69]
	v_mfma_f32_16x16x32_bf16 v[122:125], v[172:175], v[188:191], v[122:125]
	v_mfma_f32_16x16x32_bf16 v[114:117], v[180:183], v[188:191], v[114:117]
	v_mfma_f32_16x16x32_bf16 v[106:109], v[172:175], v[196:199], v[106:109]
	v_mfma_f32_16x16x32_bf16 v[98:101], v[180:183], v[196:199], v[98:101]
	v_mfma_f32_16x16x32_bf16 v[90:93], v[172:175], v[204:207], v[90:93]
	v_mfma_f32_16x16x32_bf16 v[82:85], v[180:183], v[204:207], v[82:85]
	v_mfma_f32_16x16x32_bf16 v[74:77], v[172:175], v[212:215], v[74:77]
	v_mfma_f32_16x16x32_bf16 v[66:69], v[180:183], v[212:215], v[66:69]
	s_setprio 0
	s_barrier
	s_add_i32 s62, s59, s30
	v_lshl_add_u64 v[218:219], s[34:35], 0, v[134:135]
	s_mov_b32 m0, s62
	ds_read_b128 v[184:187], v155 offset:16384
	ds_read_b128 v[188:191], v155 offset:17408
	ds_read_b128 v[192:195], v155 offset:18432
	ds_read_b128 v[196:199], v155 offset:19456
	ds_read_b128 v[200:203], v155 offset:20480
	ds_read_b128 v[204:207], v155 offset:21504
	ds_read_b128 v[208:211], v155 offset:22528
	ds_read_b128 v[212:215], v155 offset:23552
	global_load_lds_dwordx4 v[218:219], off
	s_add_i32 m0, s62, 0x2000
	s_add_u32 s62, s34, 0x80000
	v_lshl_add_u64 v[220:221], s[34:35], 0, v[130:131]
	s_addc_u32 s63, s35, 0
	s_add_i32 s66, s60, s30
	global_load_lds_dwordx4 v[220:221], off
	v_lshl_add_u64 v[222:223], s[62:63], 0, v[134:135]
	s_mov_b32 m0, s66
	v_lshl_add_u64 v[224:225], s[46:47], 0, v[132:133]
	global_load_lds_dwordx4 v[222:223], off
	v_lshl_add_u64 v[222:223], s[62:63], 0, v[130:131]
	s_add_i32 m0, s66, 0x2000
	s_nop 0
	global_load_lds_dwordx4 v[222:223], off
	v_lshl_add_u64 v[222:223], s[46:47], 0, v[136:137]
	s_mov_b32 m0, s43
	s_nop 0
	global_load_lds_dwordx4 v[222:223], off
	s_mov_b32 m0, s52
	s_nop 0
	global_load_lds_dwordx4 v[224:225], off
	s_waitcnt vmcnt(8)
	s_waitcnt lgkmcnt(0)
	s_barrier
	s_setprio 1
	s_waitcnt lgkmcnt(0)
	v_mfma_f32_16x16x32_bf16 v[62:65], v[146:149], v[184:187], v[62:65]
	v_mfma_f32_16x16x32_bf16 v[54:57], v[160:163], v[184:187], v[54:57]
	v_mfma_f32_16x16x32_bf16 v[46:49], v[146:149], v[192:195], v[46:49]
	v_mfma_f32_16x16x32_bf16 v[38:41], v[160:163], v[192:195], v[38:41]
	v_mfma_f32_16x16x32_bf16 v[30:33], v[146:149], v[200:203], v[30:33]
	v_mfma_f32_16x16x32_bf16 v[22:25], v[160:163], v[200:203], v[22:25]
	v_mfma_f32_16x16x32_bf16 v[14:17], v[146:149], v[208:211], v[14:17]
	v_mfma_f32_16x16x32_bf16 v[6:9], v[160:163], v[208:211], v[6:9]
	v_mfma_f32_16x16x32_bf16 v[62:65], v[156:159], v[188:191], v[62:65]
	v_mfma_f32_16x16x32_bf16 v[54:57], v[164:167], v[188:191], v[54:57]
	v_mfma_f32_16x16x32_bf16 v[46:49], v[156:159], v[196:199], v[46:49]
	v_mfma_f32_16x16x32_bf16 v[38:41], v[164:167], v[196:199], v[38:41]
	v_mfma_f32_16x16x32_bf16 v[30:33], v[156:159], v[204:207], v[30:33]
	v_mfma_f32_16x16x32_bf16 v[22:25], v[164:167], v[204:207], v[22:25]
	v_mfma_f32_16x16x32_bf16 v[14:17], v[156:159], v[212:215], v[14:17]
	v_mfma_f32_16x16x32_bf16 v[6:9], v[164:167], v[212:215], v[6:9]
	s_setprio 0
	s_setprio 1
	v_mfma_f32_16x16x32_bf16 v[58:61], v[168:171], v[184:187], v[58:61]
	v_mfma_f32_16x16x32_bf16 v[50:53], v[176:179], v[184:187], v[50:53]
	v_mfma_f32_16x16x32_bf16 v[42:45], v[168:171], v[192:195], v[42:45]
	v_mfma_f32_16x16x32_bf16 v[34:37], v[176:179], v[192:195], v[34:37]
	v_mfma_f32_16x16x32_bf16 v[26:29], v[168:171], v[200:203], v[26:29]
	v_mfma_f32_16x16x32_bf16 v[18:21], v[176:179], v[200:203], v[18:21]
	v_mfma_f32_16x16x32_bf16 v[10:13], v[168:171], v[208:211], v[10:13]
	v_mfma_f32_16x16x32_bf16 v[2:5], v[176:179], v[208:211], v[2:5]
	v_mfma_f32_16x16x32_bf16 v[58:61], v[172:175], v[188:191], v[58:61]
	v_mfma_f32_16x16x32_bf16 v[50:53], v[180:183], v[188:191], v[50:53]
	v_mfma_f32_16x16x32_bf16 v[42:45], v[172:175], v[196:199], v[42:45]
	v_mfma_f32_16x16x32_bf16 v[34:37], v[180:183], v[196:199], v[34:37]
	v_mfma_f32_16x16x32_bf16 v[26:29], v[172:175], v[204:207], v[26:29]
	v_mfma_f32_16x16x32_bf16 v[18:21], v[180:183], v[204:207], v[18:21]
	v_mfma_f32_16x16x32_bf16 v[10:13], v[172:175], v[212:215], v[10:13]
	v_mfma_f32_16x16x32_bf16 v[2:5], v[180:183], v[212:215], v[2:5]
	s_setprio 0
	s_barrier
	s_add_i32 s62, 0, 0x18000
	s_add_i32 s63, 0, 0x1c000
	v_add_u32_e32 v164, s62, v151
	v_add_u32_e32 v180, s63, v151
	ds_read_b128 v[146:149], v164
	ds_read_b128 v[156:159], v164 offset:1024
	ds_read_b128 v[160:163], v164 offset:2048
	ds_read_b128 v[164:167], v164 offset:3072
	ds_read_b128 v[168:171], v180
	ds_read_b128 v[172:175], v180 offset:1024
	ds_read_b128 v[176:179], v180 offset:2048
	ds_read_b128 v[180:183], v180 offset:3072
	s_add_u32 s46, s46, 0x80000
	s_addc_u32 s47, s47, 0
	s_mov_b32 m0, s53
	v_lshl_add_u64 v[226:227], s[46:47], 0, v[136:137]
	ds_read_b128 v[184:187], v155 offset:32768
	ds_read_b128 v[188:191], v155 offset:33792
	ds_read_b128 v[192:195], v155 offset:34816
	ds_read_b128 v[196:199], v155 offset:35840
	ds_read_b128 v[200:203], v155 offset:36864
	ds_read_b128 v[204:207], v155 offset:37888
	ds_read_b128 v[208:211], v155 offset:38912
	ds_read_b128 v[212:215], v155 offset:39936
	global_load_lds_dwordx4 v[226:227], off
	v_lshl_add_u64 v[226:227], s[46:47], 0, v[132:133]
	s_mov_b32 m0, s54
	s_nop 0
	global_load_lds_dwordx4 v[226:227], off
	s_waitcnt vmcnt(8)
	s_waitcnt lgkmcnt(0)
	s_barrier
	s_setprio 1
	s_waitcnt lgkmcnt(0)
	v_mfma_f32_16x16x32_bf16 v[126:129], v[146:149], v[184:187], v[126:129]
	v_mfma_f32_16x16x32_bf16 v[118:121], v[160:163], v[184:187], v[118:121]
	v_mfma_f32_16x16x32_bf16 v[110:113], v[146:149], v[192:195], v[110:113]
	v_mfma_f32_16x16x32_bf16 v[102:105], v[160:163], v[192:195], v[102:105]
	v_mfma_f32_16x16x32_bf16 v[94:97], v[146:149], v[200:203], v[94:97]
	v_mfma_f32_16x16x32_bf16 v[86:89], v[160:163], v[200:203], v[86:89]
	v_mfma_f32_16x16x32_bf16 v[78:81], v[146:149], v[208:211], v[78:81]
	v_mfma_f32_16x16x32_bf16 v[70:73], v[160:163], v[208:211], v[70:73]
	v_mfma_f32_16x16x32_bf16 v[126:129], v[156:159], v[188:191], v[126:129]
	v_mfma_f32_16x16x32_bf16 v[118:121], v[164:167], v[188:191], v[118:121]
	v_mfma_f32_16x16x32_bf16 v[110:113], v[156:159], v[196:199], v[110:113]
	v_mfma_f32_16x16x32_bf16 v[102:105], v[164:167], v[196:199], v[102:105]
	v_mfma_f32_16x16x32_bf16 v[94:97], v[156:159], v[204:207], v[94:97]
	v_mfma_f32_16x16x32_bf16 v[86:89], v[164:167], v[204:207], v[86:89]
	v_mfma_f32_16x16x32_bf16 v[78:81], v[156:159], v[212:215], v[78:81]
	v_mfma_f32_16x16x32_bf16 v[70:73], v[164:167], v[212:215], v[70:73]
	s_setprio 0
	s_setprio 1
	v_mfma_f32_16x16x32_bf16 v[122:125], v[168:171], v[184:187], v[122:125]
	v_mfma_f32_16x16x32_bf16 v[114:117], v[176:179], v[184:187], v[114:117]
	v_mfma_f32_16x16x32_bf16 v[106:109], v[168:171], v[192:195], v[106:109]
	v_mfma_f32_16x16x32_bf16 v[98:101], v[176:179], v[192:195], v[98:101]
	v_mfma_f32_16x16x32_bf16 v[90:93], v[168:171], v[200:203], v[90:93]
	v_mfma_f32_16x16x32_bf16 v[82:85], v[176:179], v[200:203], v[82:85]
	v_mfma_f32_16x16x32_bf16 v[74:77], v[168:171], v[208:211], v[74:77]
	v_mfma_f32_16x16x32_bf16 v[66:69], v[176:179], v[208:211], v[66:69]
	v_mfma_f32_16x16x32_bf16 v[122:125], v[172:175], v[188:191], v[122:125]
	v_mfma_f32_16x16x32_bf16 v[114:117], v[180:183], v[188:191], v[114:117]
	v_mfma_f32_16x16x32_bf16 v[106:109], v[172:175], v[196:199], v[106:109]
	v_mfma_f32_16x16x32_bf16 v[98:101], v[180:183], v[196:199], v[98:101]
	v_mfma_f32_16x16x32_bf16 v[90:93], v[172:175], v[204:207], v[90:93]
	v_mfma_f32_16x16x32_bf16 v[82:85], v[180:183], v[204:207], v[82:85]
	v_mfma_f32_16x16x32_bf16 v[74:77], v[172:175], v[212:215], v[74:77]
	v_mfma_f32_16x16x32_bf16 v[66:69], v[180:183], v[212:215], v[66:69]
	s_setprio 0
	s_barrier
	s_add_i32 s46, s62, s30
	v_lshl_add_u64 v[218:219], v[218:219], 0, s[8:9]
	s_mov_b32 m0, s46
	ds_read_b128 v[184:187], v155 offset:49152
	ds_read_b128 v[188:191], v155 offset:50176
	ds_read_b128 v[192:195], v155 offset:51200
	ds_read_b128 v[196:199], v155 offset:52224
	ds_read_b128 v[200:203], v155 offset:53248
	ds_read_b128 v[204:207], v155 offset:54272
	ds_read_b128 v[208:211], v155 offset:55296
	ds_read_b128 v[212:215], v155 offset:56320
	global_load_lds_dwordx4 v[218:219], off
	s_add_i32 m0, s46, 0x2000
	s_add_u32 s34, s34, 0x80080
	v_lshl_add_u64 v[218:219], v[220:221], 0, s[8:9]
	s_addc_u32 s35, s35, 0
	s_add_i32 s46, s63, s30
	global_load_lds_dwordx4 v[218:219], off
	v_lshl_add_u64 v[218:219], s[34:35], 0, v[134:135]
	s_mov_b32 m0, s46
	s_nop 0
	global_load_lds_dwordx4 v[218:219], off
	v_lshl_add_u64 v[218:219], s[34:35], 0, v[130:131]
	s_add_i32 m0, s46, 0x2000
	s_nop 0
	global_load_lds_dwordx4 v[218:219], off
	v_lshl_add_u64 v[218:219], v[222:223], 0, s[8:9]
	s_mov_b32 m0, s56
	s_nop 0
	global_load_lds_dwordx4 v[218:219], off
	v_lshl_add_u64 v[218:219], v[224:225], 0, s[8:9]
	s_mov_b32 m0, s57
	s_nop 0
	global_load_lds_dwordx4 v[218:219], off
	s_waitcnt vmcnt(8)
	s_waitcnt lgkmcnt(0)
	s_barrier
	s_setprio 1
	s_waitcnt lgkmcnt(0)
	v_mfma_f32_16x16x32_bf16 v[62:65], v[146:149], v[184:187], v[62:65]
	v_mfma_f32_16x16x32_bf16 v[54:57], v[160:163], v[184:187], v[54:57]
	v_mfma_f32_16x16x32_bf16 v[46:49], v[146:149], v[192:195], v[46:49]
	v_mfma_f32_16x16x32_bf16 v[38:41], v[160:163], v[192:195], v[38:41]
	v_mfma_f32_16x16x32_bf16 v[30:33], v[146:149], v[200:203], v[30:33]
	v_mfma_f32_16x16x32_bf16 v[22:25], v[160:163], v[200:203], v[22:25]
	v_mfma_f32_16x16x32_bf16 v[14:17], v[146:149], v[208:211], v[14:17]
	v_mfma_f32_16x16x32_bf16 v[6:9], v[160:163], v[208:211], v[6:9]
	v_mfma_f32_16x16x32_bf16 v[62:65], v[156:159], v[188:191], v[62:65]
	v_mfma_f32_16x16x32_bf16 v[54:57], v[164:167], v[188:191], v[54:57]
	v_mfma_f32_16x16x32_bf16 v[46:49], v[156:159], v[196:199], v[46:49]
	v_mfma_f32_16x16x32_bf16 v[38:41], v[164:167], v[196:199], v[38:41]
	v_mfma_f32_16x16x32_bf16 v[30:33], v[156:159], v[204:207], v[30:33]
	v_mfma_f32_16x16x32_bf16 v[22:25], v[164:167], v[204:207], v[22:25]
	v_mfma_f32_16x16x32_bf16 v[14:17], v[156:159], v[212:215], v[14:17]
	v_mfma_f32_16x16x32_bf16 v[6:9], v[164:167], v[212:215], v[6:9]
	s_setprio 0
	s_setprio 1
	v_mfma_f32_16x16x32_bf16 v[58:61], v[168:171], v[184:187], v[58:61]
	v_mfma_f32_16x16x32_bf16 v[50:53], v[176:179], v[184:187], v[50:53]
	v_mfma_f32_16x16x32_bf16 v[42:45], v[168:171], v[192:195], v[42:45]
	v_mfma_f32_16x16x32_bf16 v[34:37], v[176:179], v[192:195], v[34:37]
	v_mfma_f32_16x16x32_bf16 v[26:29], v[168:171], v[200:203], v[26:29]
	v_mfma_f32_16x16x32_bf16 v[18:21], v[176:179], v[200:203], v[18:21]
	v_mfma_f32_16x16x32_bf16 v[10:13], v[168:171], v[208:211], v[10:13]
	v_mfma_f32_16x16x32_bf16 v[2:5], v[176:179], v[208:211], v[2:5]
	v_mfma_f32_16x16x32_bf16 v[58:61], v[172:175], v[188:191], v[58:61]
	v_mfma_f32_16x16x32_bf16 v[50:53], v[180:183], v[188:191], v[50:53]
	v_mfma_f32_16x16x32_bf16 v[42:45], v[172:175], v[196:199], v[42:45]
	v_mfma_f32_16x16x32_bf16 v[34:37], v[180:183], v[196:199], v[34:37]
	v_mfma_f32_16x16x32_bf16 v[26:29], v[172:175], v[204:207], v[26:29]
	v_mfma_f32_16x16x32_bf16 v[18:21], v[180:183], v[204:207], v[18:21]
	v_mfma_f32_16x16x32_bf16 v[10:13], v[172:175], v[212:215], v[10:13]
	v_mfma_f32_16x16x32_bf16 v[2:5], v[180:183], v[212:215], v[2:5]
	s_setprio 0
	s_barrier
	s_add_i32 s71, s71, 2
	s_add_u32 s44, s44, 0x100
	s_addc_u32 s45, s45, 0
	s_add_u32 s69, s69, 0x100
	s_addc_u32 s70, s70, 0
	s_cmp_gt_u32 s71, 29
	s_cbranch_scc0 .LBB0_3067
	v_mov_b32_e32 v160, 0xbfb8aa3b
	s_and_b64 vcc, exec, s[24:25]
	s_cbranch_vccz .LBB0_3070
	s_barrier
.LBB0_3070:
	v_readlane_b32 s0, v247, 31
	v_lshl_or_b32 v146, s68, 7, v152
	v_readlane_b32 s1, v247, 32
	v_lshl_add_u32 v156, s42, 8, v1
	v_ashrrev_i32_e32 v147, 31, v146
	v_mov_b64_e32 v[148:149], s[0:1]
	v_mad_i64_i32 v[158:159], s[0:1], v156, s61, v[148:149]
	v_lshlrev_b64 v[146:147], 1, v[146:147]
	v_lshl_add_u64 v[158:159], v[158:159], 0, v[146:147]
	v_pk_mul_f32 v[122:123], v[126:127], v[122:123]
	v_pk_mul_f32 v[124:125], v[128:129], v[124:125]
	v_pk_mul_f32 v[114:115], v[118:119], v[114:115]
	v_pk_mul_f32 v[116:117], v[120:121], v[116:117]
	v_pk_mul_f32 v[126:127], v[126:127], v[160:161] op_sel_hi:[1,0]
	v_pk_mul_f32 v[128:129], v[128:129], v[160:161] op_sel_hi:[1,0]
	v_pk_mul_f32 v[118:119], v[118:119], v[160:161] op_sel_hi:[1,0]
	v_pk_mul_f32 v[120:121], v[120:121], v[160:161] op_sel_hi:[1,0]
	v_exp_f32_e32 v126, v126
	v_exp_f32_e32 v127, v127
	v_exp_f32_e32 v128, v128
	v_exp_f32_e32 v129, v129
	v_exp_f32_e32 v118, v118
	v_exp_f32_e32 v119, v119
	v_exp_f32_e32 v120, v120
	v_exp_f32_e32 v121, v121
	v_pk_add_f32 v[126:127], v[126:127], 1.0 op_sel_hi:[1,0]
	v_pk_add_f32 v[128:129], v[128:129], 1.0 op_sel_hi:[1,0]
	v_pk_add_f32 v[118:119], v[118:119], 1.0 op_sel_hi:[1,0]
	v_pk_add_f32 v[120:121], v[120:121], 1.0 op_sel_hi:[1,0]
	v_rcp_f32_e32 v126, v126
	v_rcp_f32_e32 v127, v127
	v_rcp_f32_e32 v128, v128
	v_rcp_f32_e32 v129, v129
	v_rcp_f32_e32 v118, v118
	v_rcp_f32_e32 v119, v119
	v_rcp_f32_e32 v120, v120
	v_rcp_f32_e32 v121, v121
	v_pk_mul_f32 v[122:123], v[126:127], v[122:123]
	v_pk_mul_f32 v[124:125], v[128:129], v[124:125]
	v_pk_mul_f32 v[114:115], v[118:119], v[114:115]
	v_pk_mul_f32 v[116:117], v[120:121], v[116:117]
	v_cvt_pk_bf16_f32 v122, v122, v123
	v_cvt_pk_bf16_f32 v123, v124, v125
	v_cvt_pk_bf16_f32 v124, v114, v115
	v_cvt_pk_bf16_f32 v125, v116, v117
	global_store_dwordx4 v[158:159], v[122:125], off
	v_or_b32_e32 v114, 16, v156
	v_mad_i64_i32 v[114:115], s[0:1], v114, s61, v[148:149]
	v_lshl_add_u64 v[114:115], v[114:115], 0, v[146:147]
	v_pk_mul_f32 v[106:107], v[110:111], v[106:107]
	v_pk_mul_f32 v[108:109], v[112:113], v[108:109]
	v_pk_mul_f32 v[98:99], v[102:103], v[98:99]
	v_pk_mul_f32 v[100:101], v[104:105], v[100:101]
	v_pk_mul_f32 v[110:111], v[110:111], v[160:161] op_sel_hi:[1,0]
	v_pk_mul_f32 v[112:113], v[112:113], v[160:161] op_sel_hi:[1,0]
	v_pk_mul_f32 v[102:103], v[102:103], v[160:161] op_sel_hi:[1,0]
	v_pk_mul_f32 v[104:105], v[104:105], v[160:161] op_sel_hi:[1,0]
	v_exp_f32_e32 v110, v110
	v_exp_f32_e32 v111, v111
	v_exp_f32_e32 v112, v112
	v_exp_f32_e32 v113, v113
	v_exp_f32_e32 v102, v102
	v_exp_f32_e32 v103, v103
	v_exp_f32_e32 v104, v104
	v_exp_f32_e32 v105, v105
	v_pk_add_f32 v[110:111], v[110:111], 1.0 op_sel_hi:[1,0]
	v_pk_add_f32 v[112:113], v[112:113], 1.0 op_sel_hi:[1,0]
	v_pk_add_f32 v[102:103], v[102:103], 1.0 op_sel_hi:[1,0]
	v_pk_add_f32 v[104:105], v[104:105], 1.0 op_sel_hi:[1,0]
	v_rcp_f32_e32 v110, v110
	v_rcp_f32_e32 v111, v111
	v_rcp_f32_e32 v112, v112
	v_rcp_f32_e32 v113, v113
	v_rcp_f32_e32 v102, v102
	v_rcp_f32_e32 v103, v103
	v_rcp_f32_e32 v104, v104
	v_rcp_f32_e32 v105, v105
	v_pk_mul_f32 v[106:107], v[110:111], v[106:107]
	v_pk_mul_f32 v[108:109], v[112:113], v[108:109]
	v_pk_mul_f32 v[98:99], v[102:103], v[98:99]
	v_pk_mul_f32 v[100:101], v[104:105], v[100:101]
	v_cvt_pk_bf16_f32 v106, v106, v107
	v_cvt_pk_bf16_f32 v107, v108, v109
	v_cvt_pk_bf16_f32 v108, v98, v99
	v_cvt_pk_bf16_f32 v109, v100, v101
	global_store_dwordx4 v[114:115], v[106:109], off
	v_or_b32_e32 v98, 32, v156
	v_mad_i64_i32 v[98:99], s[0:1], v98, s61, v[148:149]
	v_lshl_add_u64 v[98:99], v[98:99], 0, v[146:147]
	v_pk_mul_f32 v[90:91], v[94:95], v[90:91]
	v_pk_mul_f32 v[92:93], v[96:97], v[92:93]
	v_pk_mul_f32 v[82:83], v[86:87], v[82:83]
	v_pk_mul_f32 v[84:85], v[88:89], v[84:85]
	v_pk_mul_f32 v[94:95], v[94:95], v[160:161] op_sel_hi:[1,0]
	v_pk_mul_f32 v[96:97], v[96:97], v[160:161] op_sel_hi:[1,0]
	v_pk_mul_f32 v[86:87], v[86:87], v[160:161] op_sel_hi:[1,0]
	v_pk_mul_f32 v[88:89], v[88:89], v[160:161] op_sel_hi:[1,0]
	v_exp_f32_e32 v94, v94
	v_exp_f32_e32 v95, v95
	v_exp_f32_e32 v96, v96
	v_exp_f32_e32 v97, v97
	v_exp_f32_e32 v86, v86
	v_exp_f32_e32 v87, v87
	v_exp_f32_e32 v88, v88
	v_exp_f32_e32 v89, v89
	v_pk_add_f32 v[94:95], v[94:95], 1.0 op_sel_hi:[1,0]
	v_pk_add_f32 v[96:97], v[96:97], 1.0 op_sel_hi:[1,0]
	v_pk_add_f32 v[86:87], v[86:87], 1.0 op_sel_hi:[1,0]
	v_pk_add_f32 v[88:89], v[88:89], 1.0 op_sel_hi:[1,0]
	v_rcp_f32_e32 v94, v94
	v_rcp_f32_e32 v95, v95
	v_rcp_f32_e32 v96, v96
	v_rcp_f32_e32 v97, v97
	v_rcp_f32_e32 v86, v86
	v_rcp_f32_e32 v87, v87
	v_rcp_f32_e32 v88, v88
	v_rcp_f32_e32 v89, v89
	v_pk_mul_f32 v[90:91], v[94:95], v[90:91]
	v_pk_mul_f32 v[92:93], v[96:97], v[92:93]
	v_pk_mul_f32 v[82:83], v[86:87], v[82:83]
	v_pk_mul_f32 v[84:85], v[88:89], v[84:85]
	v_cvt_pk_bf16_f32 v90, v90, v91
	v_cvt_pk_bf16_f32 v91, v92, v93
	v_cvt_pk_bf16_f32 v92, v82, v83
	v_cvt_pk_bf16_f32 v93, v84, v85
	global_store_dwordx4 v[98:99], v[90:93], off
	v_or_b32_e32 v82, 48, v156
	v_mad_i64_i32 v[82:83], s[0:1], v82, s61, v[148:149]
	v_lshl_add_u64 v[82:83], v[82:83], 0, v[146:147]
	v_pk_mul_f32 v[74:75], v[78:79], v[74:75]
	v_pk_mul_f32 v[76:77], v[80:81], v[76:77]
	v_pk_mul_f32 v[66:67], v[70:71], v[66:67]
	v_pk_mul_f32 v[68:69], v[72:73], v[68:69]
	v_pk_mul_f32 v[78:79], v[78:79], v[160:161] op_sel_hi:[1,0]
	v_pk_mul_f32 v[80:81], v[80:81], v[160:161] op_sel_hi:[1,0]
	v_pk_mul_f32 v[70:71], v[70:71], v[160:161] op_sel_hi:[1,0]
	v_pk_mul_f32 v[72:73], v[72:73], v[160:161] op_sel_hi:[1,0]
	v_exp_f32_e32 v78, v78
	v_exp_f32_e32 v79, v79
	v_exp_f32_e32 v80, v80
	v_exp_f32_e32 v81, v81
	v_exp_f32_e32 v70, v70
	v_exp_f32_e32 v71, v71
	v_exp_f32_e32 v72, v72
	v_exp_f32_e32 v73, v73
	v_pk_add_f32 v[78:79], v[78:79], 1.0 op_sel_hi:[1,0]
	v_pk_add_f32 v[80:81], v[80:81], 1.0 op_sel_hi:[1,0]
	v_pk_add_f32 v[70:71], v[70:71], 1.0 op_sel_hi:[1,0]
	v_pk_add_f32 v[72:73], v[72:73], 1.0 op_sel_hi:[1,0]
	v_rcp_f32_e32 v78, v78
	v_rcp_f32_e32 v79, v79
	v_rcp_f32_e32 v80, v80
	v_rcp_f32_e32 v81, v81
	v_rcp_f32_e32 v70, v70
	v_rcp_f32_e32 v71, v71
	v_rcp_f32_e32 v72, v72
	v_rcp_f32_e32 v73, v73
	v_pk_mul_f32 v[74:75], v[78:79], v[74:75]
	v_pk_mul_f32 v[76:77], v[80:81], v[76:77]
	v_pk_mul_f32 v[66:67], v[70:71], v[66:67]
	v_pk_mul_f32 v[68:69], v[72:73], v[68:69]
	v_cvt_pk_bf16_f32 v74, v74, v75
	v_cvt_pk_bf16_f32 v75, v76, v77
	v_cvt_pk_bf16_f32 v76, v66, v67
	v_cvt_pk_bf16_f32 v77, v68, v69
	global_store_dwordx4 v[82:83], v[74:77], off
	v_add_u32_e32 v66, 0x80, v156
	v_mad_i64_i32 v[66:67], s[0:1], v66, s61, v[148:149]
	v_lshl_add_u64 v[66:67], v[66:67], 0, v[146:147]
	v_pk_mul_f32 v[58:59], v[62:63], v[58:59]
	v_pk_mul_f32 v[60:61], v[64:65], v[60:61]
	v_pk_mul_f32 v[50:51], v[54:55], v[50:51]
	v_pk_mul_f32 v[52:53], v[56:57], v[52:53]
	v_pk_mul_f32 v[62:63], v[62:63], v[160:161] op_sel_hi:[1,0]
	v_pk_mul_f32 v[64:65], v[64:65], v[160:161] op_sel_hi:[1,0]
	v_pk_mul_f32 v[54:55], v[54:55], v[160:161] op_sel_hi:[1,0]
	v_pk_mul_f32 v[56:57], v[56:57], v[160:161] op_sel_hi:[1,0]
	v_exp_f32_e32 v62, v62
	v_exp_f32_e32 v63, v63
	v_exp_f32_e32 v64, v64
	v_exp_f32_e32 v65, v65
	v_exp_f32_e32 v54, v54
	v_exp_f32_e32 v55, v55
	v_exp_f32_e32 v56, v56
	v_exp_f32_e32 v57, v57
	v_pk_add_f32 v[62:63], v[62:63], 1.0 op_sel_hi:[1,0]
	v_pk_add_f32 v[64:65], v[64:65], 1.0 op_sel_hi:[1,0]
	v_pk_add_f32 v[54:55], v[54:55], 1.0 op_sel_hi:[1,0]
	v_pk_add_f32 v[56:57], v[56:57], 1.0 op_sel_hi:[1,0]
	v_rcp_f32_e32 v62, v62
	v_rcp_f32_e32 v63, v63
	v_rcp_f32_e32 v64, v64
	v_rcp_f32_e32 v65, v65
	v_rcp_f32_e32 v54, v54
	v_rcp_f32_e32 v55, v55
	v_rcp_f32_e32 v56, v56
	v_rcp_f32_e32 v57, v57
	v_pk_mul_f32 v[58:59], v[62:63], v[58:59]
	v_pk_mul_f32 v[60:61], v[64:65], v[60:61]
	v_pk_mul_f32 v[50:51], v[54:55], v[50:51]
	v_pk_mul_f32 v[52:53], v[56:57], v[52:53]
	v_cvt_pk_bf16_f32 v58, v58, v59
	v_cvt_pk_bf16_f32 v59, v60, v61
	v_cvt_pk_bf16_f32 v60, v50, v51
	v_cvt_pk_bf16_f32 v61, v52, v53
	global_store_dwordx4 v[66:67], v[58:61], off
	v_add_u32_e32 v50, 0x90, v156
	v_mad_i64_i32 v[50:51], s[0:1], v50, s61, v[148:149]
	v_lshl_add_u64 v[50:51], v[50:51], 0, v[146:147]
	v_pk_mul_f32 v[42:43], v[46:47], v[42:43]
	v_pk_mul_f32 v[44:45], v[48:49], v[44:45]
	v_pk_mul_f32 v[34:35], v[38:39], v[34:35]
	v_pk_mul_f32 v[36:37], v[40:41], v[36:37]
	v_pk_mul_f32 v[46:47], v[46:47], v[160:161] op_sel_hi:[1,0]
	v_pk_mul_f32 v[48:49], v[48:49], v[160:161] op_sel_hi:[1,0]
	v_pk_mul_f32 v[38:39], v[38:39], v[160:161] op_sel_hi:[1,0]
	v_pk_mul_f32 v[40:41], v[40:41], v[160:161] op_sel_hi:[1,0]
	v_exp_f32_e32 v46, v46
	v_exp_f32_e32 v47, v47
	v_exp_f32_e32 v48, v48
	v_exp_f32_e32 v49, v49
	v_exp_f32_e32 v38, v38
	v_exp_f32_e32 v39, v39
	v_exp_f32_e32 v40, v40
	v_exp_f32_e32 v41, v41
	v_pk_add_f32 v[46:47], v[46:47], 1.0 op_sel_hi:[1,0]
	v_pk_add_f32 v[48:49], v[48:49], 1.0 op_sel_hi:[1,0]
	v_pk_add_f32 v[38:39], v[38:39], 1.0 op_sel_hi:[1,0]
	v_pk_add_f32 v[40:41], v[40:41], 1.0 op_sel_hi:[1,0]
	v_rcp_f32_e32 v46, v46
	v_rcp_f32_e32 v47, v47
	v_rcp_f32_e32 v48, v48
	v_rcp_f32_e32 v49, v49
	v_rcp_f32_e32 v38, v38
	v_rcp_f32_e32 v39, v39
	v_rcp_f32_e32 v40, v40
	v_rcp_f32_e32 v41, v41
	v_pk_mul_f32 v[42:43], v[46:47], v[42:43]
	v_pk_mul_f32 v[44:45], v[48:49], v[44:45]
	v_pk_mul_f32 v[34:35], v[38:39], v[34:35]
	v_pk_mul_f32 v[36:37], v[40:41], v[36:37]
	v_cvt_pk_bf16_f32 v42, v42, v43
	v_cvt_pk_bf16_f32 v43, v44, v45
	v_cvt_pk_bf16_f32 v44, v34, v35
	v_cvt_pk_bf16_f32 v45, v36, v37
	global_store_dwordx4 v[50:51], v[42:45], off
	v_add_u32_e32 v34, 0xa0, v156
	v_mad_i64_i32 v[34:35], s[0:1], v34, s61, v[148:149]
	v_lshl_add_u64 v[34:35], v[34:35], 0, v[146:147]
	v_pk_mul_f32 v[26:27], v[30:31], v[26:27]
	v_pk_mul_f32 v[28:29], v[32:33], v[28:29]
	v_pk_mul_f32 v[18:19], v[22:23], v[18:19]
	v_pk_mul_f32 v[20:21], v[24:25], v[20:21]
	v_pk_mul_f32 v[30:31], v[30:31], v[160:161] op_sel_hi:[1,0]
	v_pk_mul_f32 v[32:33], v[32:33], v[160:161] op_sel_hi:[1,0]
	v_pk_mul_f32 v[22:23], v[22:23], v[160:161] op_sel_hi:[1,0]
	v_pk_mul_f32 v[24:25], v[24:25], v[160:161] op_sel_hi:[1,0]
	v_exp_f32_e32 v30, v30
	v_exp_f32_e32 v31, v31
	v_exp_f32_e32 v32, v32
	v_exp_f32_e32 v33, v33
	v_exp_f32_e32 v22, v22
	v_exp_f32_e32 v23, v23
	v_exp_f32_e32 v24, v24
	v_exp_f32_e32 v25, v25
	v_pk_add_f32 v[30:31], v[30:31], 1.0 op_sel_hi:[1,0]
	v_pk_add_f32 v[32:33], v[32:33], 1.0 op_sel_hi:[1,0]
	v_pk_add_f32 v[22:23], v[22:23], 1.0 op_sel_hi:[1,0]
	v_pk_add_f32 v[24:25], v[24:25], 1.0 op_sel_hi:[1,0]
	v_rcp_f32_e32 v30, v30
	v_rcp_f32_e32 v31, v31
	v_rcp_f32_e32 v32, v32
	v_rcp_f32_e32 v33, v33
	v_rcp_f32_e32 v22, v22
	v_rcp_f32_e32 v23, v23
	v_rcp_f32_e32 v24, v24
	v_rcp_f32_e32 v25, v25
	v_pk_mul_f32 v[26:27], v[30:31], v[26:27]
	v_pk_mul_f32 v[28:29], v[32:33], v[28:29]
	v_pk_mul_f32 v[18:19], v[22:23], v[18:19]
	v_pk_mul_f32 v[20:21], v[24:25], v[20:21]
	v_cvt_pk_bf16_f32 v26, v26, v27
	v_cvt_pk_bf16_f32 v27, v28, v29
	v_cvt_pk_bf16_f32 v28, v18, v19
	v_cvt_pk_bf16_f32 v29, v20, v21
	global_store_dwordx4 v[34:35], v[26:29], off
	v_add_u32_e32 v18, 0xb0, v156
	v_mad_i64_i32 v[18:19], s[0:1], v18, s61, v[148:149]
	v_lshl_add_u64 v[18:19], v[18:19], 0, v[146:147]
	s_andn2_b64 vcc, exec, s[2:3]
	s_mov_b64 s[0:1], -1
	v_pk_mul_f32 v[10:11], v[14:15], v[10:11]
	v_pk_mul_f32 v[12:13], v[16:17], v[12:13]
	v_pk_mul_f32 v[2:3], v[6:7], v[2:3]
	v_pk_mul_f32 v[4:5], v[8:9], v[4:5]
	v_pk_mul_f32 v[14:15], v[14:15], v[160:161] op_sel_hi:[1,0]
	v_pk_mul_f32 v[16:17], v[16:17], v[160:161] op_sel_hi:[1,0]
	v_pk_mul_f32 v[6:7], v[6:7], v[160:161] op_sel_hi:[1,0]
	v_pk_mul_f32 v[8:9], v[8:9], v[160:161] op_sel_hi:[1,0]
	v_exp_f32_e32 v14, v14
	v_exp_f32_e32 v15, v15
	v_exp_f32_e32 v16, v16
	v_exp_f32_e32 v17, v17
	v_exp_f32_e32 v6, v6
	v_exp_f32_e32 v7, v7
	v_exp_f32_e32 v8, v8
	v_exp_f32_e32 v9, v9
	v_pk_add_f32 v[14:15], v[14:15], 1.0 op_sel_hi:[1,0]
	v_pk_add_f32 v[16:17], v[16:17], 1.0 op_sel_hi:[1,0]
	v_pk_add_f32 v[6:7], v[6:7], 1.0 op_sel_hi:[1,0]
	v_pk_add_f32 v[8:9], v[8:9], 1.0 op_sel_hi:[1,0]
	v_rcp_f32_e32 v14, v14
	v_rcp_f32_e32 v15, v15
	v_rcp_f32_e32 v16, v16
	v_rcp_f32_e32 v17, v17
	v_rcp_f32_e32 v6, v6
	v_rcp_f32_e32 v7, v7
	v_rcp_f32_e32 v8, v8
	v_rcp_f32_e32 v9, v9
	v_pk_mul_f32 v[10:11], v[14:15], v[10:11]
	v_pk_mul_f32 v[12:13], v[16:17], v[12:13]
	v_pk_mul_f32 v[2:3], v[6:7], v[2:3]
	v_pk_mul_f32 v[4:5], v[8:9], v[4:5]
	v_cvt_pk_bf16_f32 v10, v10, v11
	v_cvt_pk_bf16_f32 v11, v12, v13
	v_cvt_pk_bf16_f32 v12, v2, v3
	v_cvt_pk_bf16_f32 v13, v4, v5
	global_store_dwordx4 v[18:19], v[10:13], off
	s_cbranch_vccnz .LBB0_3063
	s_andn2_b64 vcc, exec, s[6:7]
	s_cbranch_vccnz .LBB0_3062
	s_barrier
	s_branch .LBB0_3062

.LBB0_3309:
	ds_read_b128 v[146:149], v153
	ds_read_b128 v[156:159], v153 offset:1024
	ds_read_b128 v[160:163], v153 offset:2048
	ds_read_b128 v[164:167], v153 offset:3072
	ds_read_b128 v[168:171], v154
	ds_read_b128 v[172:175], v154 offset:1024
	ds_read_b128 v[176:179], v154 offset:2048
	ds_read_b128 v[180:183], v154 offset:3072
	s_add_u32 s34, s44, 0xfff80080
	s_addc_u32 s35, s45, -1
	s_cmp_eq_u32 s69, 28
	s_cselect_b32 s47, s0, s35
	s_cselect_b32 s46, s1, s34
	s_cselect_b32 s35, s27, s68
	s_cselect_b32 s34, s37, s61
	v_lshl_add_u64 v[218:219], s[44:45], 0, v[138:139]
	s_add_i32 m0, s43, 0xc000
	ds_read_b128 v[184:187], v155
	ds_read_b128 v[188:191], v155 offset:1024
	ds_read_b128 v[192:195], v155 offset:2048
	ds_read_b128 v[196:199], v155 offset:3072
	ds_read_b128 v[200:203], v155 offset:4096
	ds_read_b128 v[204:207], v155 offset:5120
	ds_read_b128 v[208:211], v155 offset:6144
	ds_read_b128 v[212:215], v155 offset:7168
	global_load_lds_dwordx4 v[218:219], off
	v_lshl_add_u64 v[218:219], s[44:45], 0, v[140:141]
	s_add_i32 m0, s43, 0xe000
	s_nop 0
	global_load_lds_dwordx4 v[218:219], off
	s_waitcnt vmcnt(8)
	s_waitcnt lgkmcnt(0)
	s_barrier
	s_setprio 1
	s_waitcnt lgkmcnt(0)
	v_mfma_f32_16x16x32_bf16 v[126:129], v[146:149], v[184:187], v[126:129]
	v_mfma_f32_16x16x32_bf16 v[118:121], v[160:163], v[184:187], v[118:121]
	v_mfma_f32_16x16x32_bf16 v[110:113], v[146:149], v[192:195], v[110:113]
	v_mfma_f32_16x16x32_bf16 v[102:105], v[160:163], v[192:195], v[102:105]
	v_mfma_f32_16x16x32_bf16 v[94:97], v[146:149], v[200:203], v[94:97]
	v_mfma_f32_16x16x32_bf16 v[86:89], v[160:163], v[200:203], v[86:89]
	v_mfma_f32_16x16x32_bf16 v[78:81], v[146:149], v[208:211], v[78:81]
	v_mfma_f32_16x16x32_bf16 v[70:73], v[160:163], v[208:211], v[70:73]
	v_mfma_f32_16x16x32_bf16 v[126:129], v[156:159], v[188:191], v[126:129]
	v_mfma_f32_16x16x32_bf16 v[118:121], v[164:167], v[188:191], v[118:121]
	v_mfma_f32_16x16x32_bf16 v[110:113], v[156:159], v[196:199], v[110:113]
	v_mfma_f32_16x16x32_bf16 v[102:105], v[164:167], v[196:199], v[102:105]
	v_mfma_f32_16x16x32_bf16 v[94:97], v[156:159], v[204:207], v[94:97]
	v_mfma_f32_16x16x32_bf16 v[86:89], v[164:167], v[204:207], v[86:89]
	v_mfma_f32_16x16x32_bf16 v[78:81], v[156:159], v[212:215], v[78:81]
	v_mfma_f32_16x16x32_bf16 v[70:73], v[164:167], v[212:215], v[70:73]
	s_setprio 0
	s_setprio 1
	v_mfma_f32_16x16x32_bf16 v[122:125], v[168:171], v[184:187], v[122:125]
	v_mfma_f32_16x16x32_bf16 v[114:117], v[176:179], v[184:187], v[114:117]
	v_mfma_f32_16x16x32_bf16 v[106:109], v[168:171], v[192:195], v[106:109]
	v_mfma_f32_16x16x32_bf16 v[98:101], v[176:179], v[192:195], v[98:101]
	v_mfma_f32_16x16x32_bf16 v[90:93], v[168:171], v[200:203], v[90:93]
	v_mfma_f32_16x16x32_bf16 v[82:85], v[176:179], v[200:203], v[82:85]
	v_mfma_f32_16x16x32_bf16 v[74:77], v[168:171], v[208:211], v[74:77]
	v_mfma_f32_16x16x32_bf16 v[66:69], v[176:179], v[208:211], v[66:69]
	v_mfma_f32_16x16x32_bf16 v[122:125], v[172:175], v[188:191], v[122:125]
	v_mfma_f32_16x16x32_bf16 v[114:117], v[180:183], v[188:191], v[114:117]
	v_mfma_f32_16x16x32_bf16 v[106:109], v[172:175], v[196:199], v[106:109]
	v_mfma_f32_16x16x32_bf16 v[98:101], v[180:183], v[196:199], v[98:101]
	v_mfma_f32_16x16x32_bf16 v[90:93], v[172:175], v[204:207], v[90:93]
	v_mfma_f32_16x16x32_bf16 v[82:85], v[180:183], v[204:207], v[82:85]
	v_mfma_f32_16x16x32_bf16 v[74:77], v[172:175], v[212:215], v[74:77]
	v_mfma_f32_16x16x32_bf16 v[66:69], v[180:183], v[212:215], v[66:69]
	s_setprio 0
	s_barrier
	s_add_i32 s62, s57, s30
	v_lshl_add_u64 v[218:219], s[34:35], 0, v[134:135]
	s_mov_b32 m0, s62
	ds_read_b128 v[184:187], v155 offset:16384
	ds_read_b128 v[188:191], v155 offset:17408
	ds_read_b128 v[192:195], v155 offset:18432
	ds_read_b128 v[196:199], v155 offset:19456
	ds_read_b128 v[200:203], v155 offset:20480
	ds_read_b128 v[204:207], v155 offset:21504
	ds_read_b128 v[208:211], v155 offset:22528
	ds_read_b128 v[212:215], v155 offset:23552
	global_load_lds_dwordx4 v[218:219], off
	s_add_i32 m0, s62, 0x2000
	s_add_u32 s62, s34, 0x80000
	v_lshl_add_u64 v[220:221], s[34:35], 0, v[130:131]
	s_addc_u32 s63, s35, 0
	s_add_i32 s66, s58, s30
	global_load_lds_dwordx4 v[220:221], off
	v_lshl_add_u64 v[222:223], s[62:63], 0, v[134:135]
	s_mov_b32 m0, s66
	v_lshl_add_u64 v[224:225], s[46:47], 0, v[132:133]
	global_load_lds_dwordx4 v[222:223], off
	v_lshl_add_u64 v[222:223], s[62:63], 0, v[130:131]
	s_add_i32 m0, s66, 0x2000
	s_nop 0
	global_load_lds_dwordx4 v[222:223], off
	v_lshl_add_u64 v[222:223], s[46:47], 0, v[136:137]
	s_mov_b32 m0, s43
	s_nop 0
	global_load_lds_dwordx4 v[222:223], off
	s_mov_b32 m0, s48
	s_nop 0
	global_load_lds_dwordx4 v[224:225], off
	s_waitcnt vmcnt(8)
	s_waitcnt lgkmcnt(0)
	s_barrier
	s_setprio 1
	s_waitcnt lgkmcnt(0)
	v_mfma_f32_16x16x32_bf16 v[62:65], v[146:149], v[184:187], v[62:65]
	v_mfma_f32_16x16x32_bf16 v[54:57], v[160:163], v[184:187], v[54:57]
	v_mfma_f32_16x16x32_bf16 v[46:49], v[146:149], v[192:195], v[46:49]
	v_mfma_f32_16x16x32_bf16 v[38:41], v[160:163], v[192:195], v[38:41]
	v_mfma_f32_16x16x32_bf16 v[30:33], v[146:149], v[200:203], v[30:33]
	v_mfma_f32_16x16x32_bf16 v[22:25], v[160:163], v[200:203], v[22:25]
	v_mfma_f32_16x16x32_bf16 v[14:17], v[146:149], v[208:211], v[14:17]
	v_mfma_f32_16x16x32_bf16 v[6:9], v[160:163], v[208:211], v[6:9]
	v_mfma_f32_16x16x32_bf16 v[62:65], v[156:159], v[188:191], v[62:65]
	v_mfma_f32_16x16x32_bf16 v[54:57], v[164:167], v[188:191], v[54:57]
	v_mfma_f32_16x16x32_bf16 v[46:49], v[156:159], v[196:199], v[46:49]
	v_mfma_f32_16x16x32_bf16 v[38:41], v[164:167], v[196:199], v[38:41]
	v_mfma_f32_16x16x32_bf16 v[30:33], v[156:159], v[204:207], v[30:33]
	v_mfma_f32_16x16x32_bf16 v[22:25], v[164:167], v[204:207], v[22:25]
	v_mfma_f32_16x16x32_bf16 v[14:17], v[156:159], v[212:215], v[14:17]
	v_mfma_f32_16x16x32_bf16 v[6:9], v[164:167], v[212:215], v[6:9]
	s_setprio 0
	s_setprio 1
	v_mfma_f32_16x16x32_bf16 v[58:61], v[168:171], v[184:187], v[58:61]
	v_mfma_f32_16x16x32_bf16 v[50:53], v[176:179], v[184:187], v[50:53]
	v_mfma_f32_16x16x32_bf16 v[42:45], v[168:171], v[192:195], v[42:45]
	v_mfma_f32_16x16x32_bf16 v[34:37], v[176:179], v[192:195], v[34:37]
	v_mfma_f32_16x16x32_bf16 v[26:29], v[168:171], v[200:203], v[26:29]
	v_mfma_f32_16x16x32_bf16 v[18:21], v[176:179], v[200:203], v[18:21]
	v_mfma_f32_16x16x32_bf16 v[10:13], v[168:171], v[208:211], v[10:13]
	v_mfma_f32_16x16x32_bf16 v[2:5], v[176:179], v[208:211], v[2:5]
	v_mfma_f32_16x16x32_bf16 v[58:61], v[172:175], v[188:191], v[58:61]
	v_mfma_f32_16x16x32_bf16 v[50:53], v[180:183], v[188:191], v[50:53]
	v_mfma_f32_16x16x32_bf16 v[42:45], v[172:175], v[196:199], v[42:45]
	v_mfma_f32_16x16x32_bf16 v[34:37], v[180:183], v[196:199], v[34:37]
	v_mfma_f32_16x16x32_bf16 v[26:29], v[172:175], v[204:207], v[26:29]
	v_mfma_f32_16x16x32_bf16 v[18:21], v[180:183], v[204:207], v[18:21]
	v_mfma_f32_16x16x32_bf16 v[10:13], v[172:175], v[212:215], v[10:13]
	v_mfma_f32_16x16x32_bf16 v[2:5], v[180:183], v[212:215], v[2:5]
	s_setprio 0
	s_barrier
	s_add_i32 s62, 0, 0x18000
	s_add_i32 s63, 0, 0x1c000
	v_add_u32_e32 v164, s62, v151
	v_add_u32_e32 v180, s63, v151
	ds_read_b128 v[146:149], v164
	ds_read_b128 v[156:159], v164 offset:1024
	ds_read_b128 v[160:163], v164 offset:2048
	ds_read_b128 v[164:167], v164 offset:3072
	ds_read_b128 v[168:171], v180
	ds_read_b128 v[172:175], v180 offset:1024
	ds_read_b128 v[176:179], v180 offset:2048
	ds_read_b128 v[180:183], v180 offset:3072
	s_add_u32 s46, s46, 0x80000
	s_addc_u32 s47, s47, 0
	s_mov_b32 m0, s49
	v_lshl_add_u64 v[226:227], s[46:47], 0, v[136:137]
	ds_read_b128 v[184:187], v155 offset:32768
	ds_read_b128 v[188:191], v155 offset:33792
	ds_read_b128 v[192:195], v155 offset:34816
	ds_read_b128 v[196:199], v155 offset:35840
	ds_read_b128 v[200:203], v155 offset:36864
	ds_read_b128 v[204:207], v155 offset:37888
	ds_read_b128 v[208:211], v155 offset:38912
	ds_read_b128 v[212:215], v155 offset:39936
	global_load_lds_dwordx4 v[226:227], off
	v_lshl_add_u64 v[226:227], s[46:47], 0, v[132:133]
	s_mov_b32 m0, s52
	s_nop 0
	global_load_lds_dwordx4 v[226:227], off
	s_waitcnt vmcnt(8)
	s_waitcnt lgkmcnt(0)
	s_barrier
	s_setprio 1
	s_waitcnt lgkmcnt(0)
	v_mfma_f32_16x16x32_bf16 v[126:129], v[146:149], v[184:187], v[126:129]
	v_mfma_f32_16x16x32_bf16 v[118:121], v[160:163], v[184:187], v[118:121]
	v_mfma_f32_16x16x32_bf16 v[110:113], v[146:149], v[192:195], v[110:113]
	v_mfma_f32_16x16x32_bf16 v[102:105], v[160:163], v[192:195], v[102:105]
	v_mfma_f32_16x16x32_bf16 v[94:97], v[146:149], v[200:203], v[94:97]
	v_mfma_f32_16x16x32_bf16 v[86:89], v[160:163], v[200:203], v[86:89]
	v_mfma_f32_16x16x32_bf16 v[78:81], v[146:149], v[208:211], v[78:81]
	v_mfma_f32_16x16x32_bf16 v[70:73], v[160:163], v[208:211], v[70:73]
	v_mfma_f32_16x16x32_bf16 v[126:129], v[156:159], v[188:191], v[126:129]
	v_mfma_f32_16x16x32_bf16 v[118:121], v[164:167], v[188:191], v[118:121]
	v_mfma_f32_16x16x32_bf16 v[110:113], v[156:159], v[196:199], v[110:113]
	v_mfma_f32_16x16x32_bf16 v[102:105], v[164:167], v[196:199], v[102:105]
	v_mfma_f32_16x16x32_bf16 v[94:97], v[156:159], v[204:207], v[94:97]
	v_mfma_f32_16x16x32_bf16 v[86:89], v[164:167], v[204:207], v[86:89]
	v_mfma_f32_16x16x32_bf16 v[78:81], v[156:159], v[212:215], v[78:81]
	v_mfma_f32_16x16x32_bf16 v[70:73], v[164:167], v[212:215], v[70:73]
	s_setprio 0
	s_setprio 1
	v_mfma_f32_16x16x32_bf16 v[122:125], v[168:171], v[184:187], v[122:125]
	v_mfma_f32_16x16x32_bf16 v[114:117], v[176:179], v[184:187], v[114:117]
	v_mfma_f32_16x16x32_bf16 v[106:109], v[168:171], v[192:195], v[106:109]
	v_mfma_f32_16x16x32_bf16 v[98:101], v[176:179], v[192:195], v[98:101]
	v_mfma_f32_16x16x32_bf16 v[90:93], v[168:171], v[200:203], v[90:93]
	v_mfma_f32_16x16x32_bf16 v[82:85], v[176:179], v[200:203], v[82:85]
	v_mfma_f32_16x16x32_bf16 v[74:77], v[168:171], v[208:211], v[74:77]
	v_mfma_f32_16x16x32_bf16 v[66:69], v[176:179], v[208:211], v[66:69]
	v_mfma_f32_16x16x32_bf16 v[122:125], v[172:175], v[188:191], v[122:125]
	v_mfma_f32_16x16x32_bf16 v[114:117], v[180:183], v[188:191], v[114:117]
	v_mfma_f32_16x16x32_bf16 v[106:109], v[172:175], v[196:199], v[106:109]
	v_mfma_f32_16x16x32_bf16 v[98:101], v[180:183], v[196:199], v[98:101]
	v_mfma_f32_16x16x32_bf16 v[90:93], v[172:175], v[204:207], v[90:93]
	v_mfma_f32_16x16x32_bf16 v[82:85], v[180:183], v[204:207], v[82:85]
	v_mfma_f32_16x16x32_bf16 v[74:77], v[172:175], v[212:215], v[74:77]
	v_mfma_f32_16x16x32_bf16 v[66:69], v[180:183], v[212:215], v[66:69]
	s_setprio 0
	s_barrier
	s_add_i32 s46, s62, s30
	v_lshl_add_u64 v[218:219], v[218:219], 0, s[8:9]
	s_mov_b32 m0, s46
	ds_read_b128 v[184:187], v155 offset:49152
	ds_read_b128 v[188:191], v155 offset:50176
	ds_read_b128 v[192:195], v155 offset:51200
	ds_read_b128 v[196:199], v155 offset:52224
	ds_read_b128 v[200:203], v155 offset:53248
	ds_read_b128 v[204:207], v155 offset:54272
	ds_read_b128 v[208:211], v155 offset:55296
	ds_read_b128 v[212:215], v155 offset:56320
	global_load_lds_dwordx4 v[218:219], off
	s_add_i32 m0, s46, 0x2000
	s_add_u32 s34, s34, 0x80080
	v_lshl_add_u64 v[218:219], v[220:221], 0, s[8:9]
	s_addc_u32 s35, s35, 0
	s_add_i32 s46, s63, s30
	global_load_lds_dwordx4 v[218:219], off
	v_lshl_add_u64 v[218:219], s[34:35], 0, v[134:135]
	s_mov_b32 m0, s46
	s_nop 0
	global_load_lds_dwordx4 v[218:219], off
	v_lshl_add_u64 v[218:219], s[34:35], 0, v[130:131]
	s_add_i32 m0, s46, 0x2000
	s_nop 0
	global_load_lds_dwordx4 v[218:219], off
	v_lshl_add_u64 v[218:219], v[222:223], 0, s[8:9]
	s_mov_b32 m0, s54
	s_nop 0
	global_load_lds_dwordx4 v[218:219], off
	v_lshl_add_u64 v[218:219], v[224:225], 0, s[8:9]
	s_mov_b32 m0, s55
	s_nop 0
	global_load_lds_dwordx4 v[218:219], off
	s_waitcnt vmcnt(8)
	s_waitcnt lgkmcnt(0)
	s_barrier
	s_setprio 1
	s_waitcnt lgkmcnt(0)
	v_mfma_f32_16x16x32_bf16 v[62:65], v[146:149], v[184:187], v[62:65]
	v_mfma_f32_16x16x32_bf16 v[54:57], v[160:163], v[184:187], v[54:57]
	v_mfma_f32_16x16x32_bf16 v[46:49], v[146:149], v[192:195], v[46:49]
	v_mfma_f32_16x16x32_bf16 v[38:41], v[160:163], v[192:195], v[38:41]
	v_mfma_f32_16x16x32_bf16 v[30:33], v[146:149], v[200:203], v[30:33]
	v_mfma_f32_16x16x32_bf16 v[22:25], v[160:163], v[200:203], v[22:25]
	v_mfma_f32_16x16x32_bf16 v[14:17], v[146:149], v[208:211], v[14:17]
	v_mfma_f32_16x16x32_bf16 v[6:9], v[160:163], v[208:211], v[6:9]
	v_mfma_f32_16x16x32_bf16 v[62:65], v[156:159], v[188:191], v[62:65]
	v_mfma_f32_16x16x32_bf16 v[54:57], v[164:167], v[188:191], v[54:57]
	v_mfma_f32_16x16x32_bf16 v[46:49], v[156:159], v[196:199], v[46:49]
	v_mfma_f32_16x16x32_bf16 v[38:41], v[164:167], v[196:199], v[38:41]
	v_mfma_f32_16x16x32_bf16 v[30:33], v[156:159], v[204:207], v[30:33]
	v_mfma_f32_16x16x32_bf16 v[22:25], v[164:167], v[204:207], v[22:25]
	v_mfma_f32_16x16x32_bf16 v[14:17], v[156:159], v[212:215], v[14:17]
	v_mfma_f32_16x16x32_bf16 v[6:9], v[164:167], v[212:215], v[6:9]
	s_setprio 0
	s_setprio 1
	v_mfma_f32_16x16x32_bf16 v[58:61], v[168:171], v[184:187], v[58:61]
	v_mfma_f32_16x16x32_bf16 v[50:53], v[176:179], v[184:187], v[50:53]
	v_mfma_f32_16x16x32_bf16 v[42:45], v[168:171], v[192:195], v[42:45]
	v_mfma_f32_16x16x32_bf16 v[34:37], v[176:179], v[192:195], v[34:37]
	v_mfma_f32_16x16x32_bf16 v[26:29], v[168:171], v[200:203], v[26:29]
	v_mfma_f32_16x16x32_bf16 v[18:21], v[176:179], v[200:203], v[18:21]
	v_mfma_f32_16x16x32_bf16 v[10:13], v[168:171], v[208:211], v[10:13]
	v_mfma_f32_16x16x32_bf16 v[2:5], v[176:179], v[208:211], v[2:5]
	v_mfma_f32_16x16x32_bf16 v[58:61], v[172:175], v[188:191], v[58:61]
	v_mfma_f32_16x16x32_bf16 v[50:53], v[180:183], v[188:191], v[50:53]
	v_mfma_f32_16x16x32_bf16 v[42:45], v[172:175], v[196:199], v[42:45]
	v_mfma_f32_16x16x32_bf16 v[34:37], v[180:183], v[196:199], v[34:37]
	v_mfma_f32_16x16x32_bf16 v[26:29], v[172:175], v[204:207], v[26:29]
	v_mfma_f32_16x16x32_bf16 v[18:21], v[180:183], v[204:207], v[18:21]
	v_mfma_f32_16x16x32_bf16 v[10:13], v[172:175], v[212:215], v[10:13]
	v_mfma_f32_16x16x32_bf16 v[2:5], v[180:183], v[212:215], v[2:5]
	s_setprio 0
	s_barrier
	s_add_i32 s69, s69, 2
	s_add_u32 s44, s44, 0x100
	s_addc_u32 s45, s45, 0
	s_add_u32 s61, s61, 0x100
	s_addc_u32 s68, s68, 0
	s_cmp_gt_u32 s69, 29
	s_cbranch_scc0 .LBB0_3309
	v_mov_b32_e32 v160, 0xbfb8aa3b
	s_and_b64 vcc, exec, s[24:25]
	s_cbranch_vccz .LBB0_3312
	s_barrier
.LBB0_3312:
	v_readlane_b32 s0, v247, 31
	v_lshl_or_b32 v146, s60, 7, v152
	v_readlane_b32 s1, v247, 32
	v_lshl_add_u32 v156, s42, 8, v150
	v_ashrrev_i32_e32 v147, 31, v146
	v_mov_b64_e32 v[148:149], s[0:1]
	v_mad_i64_i32 v[158:159], s[0:1], v156, s59, v[148:149]
	v_lshlrev_b64 v[146:147], 1, v[146:147]
	v_lshl_add_u64 v[158:159], v[158:159], 0, v[146:147]
	v_pk_mul_f32 v[122:123], v[126:127], v[122:123]
	v_pk_mul_f32 v[124:125], v[128:129], v[124:125]
	v_pk_mul_f32 v[114:115], v[118:119], v[114:115]
	v_pk_mul_f32 v[116:117], v[120:121], v[116:117]
	v_pk_mul_f32 v[126:127], v[126:127], v[160:161] op_sel_hi:[1,0]
	v_pk_mul_f32 v[128:129], v[128:129], v[160:161] op_sel_hi:[1,0]
	v_pk_mul_f32 v[118:119], v[118:119], v[160:161] op_sel_hi:[1,0]
	v_pk_mul_f32 v[120:121], v[120:121], v[160:161] op_sel_hi:[1,0]
	v_exp_f32_e32 v126, v126
	v_exp_f32_e32 v127, v127
	v_exp_f32_e32 v128, v128
	v_exp_f32_e32 v129, v129
	v_exp_f32_e32 v118, v118
	v_exp_f32_e32 v119, v119
	v_exp_f32_e32 v120, v120
	v_exp_f32_e32 v121, v121
	v_pk_add_f32 v[126:127], v[126:127], 1.0 op_sel_hi:[1,0]
	v_pk_add_f32 v[128:129], v[128:129], 1.0 op_sel_hi:[1,0]
	v_pk_add_f32 v[118:119], v[118:119], 1.0 op_sel_hi:[1,0]
	v_pk_add_f32 v[120:121], v[120:121], 1.0 op_sel_hi:[1,0]
	v_rcp_f32_e32 v126, v126
	v_rcp_f32_e32 v127, v127
	v_rcp_f32_e32 v128, v128
	v_rcp_f32_e32 v129, v129
	v_rcp_f32_e32 v118, v118
	v_rcp_f32_e32 v119, v119
	v_rcp_f32_e32 v120, v120
	v_rcp_f32_e32 v121, v121
	v_pk_mul_f32 v[122:123], v[126:127], v[122:123]
	v_pk_mul_f32 v[124:125], v[128:129], v[124:125]
	v_pk_mul_f32 v[114:115], v[118:119], v[114:115]
	v_pk_mul_f32 v[116:117], v[120:121], v[116:117]
	v_cvt_pk_bf16_f32 v122, v122, v123
	v_cvt_pk_bf16_f32 v123, v124, v125
	v_cvt_pk_bf16_f32 v124, v114, v115
	v_cvt_pk_bf16_f32 v125, v116, v117
	global_store_dwordx4 v[158:159], v[122:125], off
	v_or_b32_e32 v114, 16, v156
	v_mad_i64_i32 v[114:115], s[0:1], v114, s59, v[148:149]
	v_lshl_add_u64 v[114:115], v[114:115], 0, v[146:147]
	v_pk_mul_f32 v[106:107], v[110:111], v[106:107]
	v_pk_mul_f32 v[108:109], v[112:113], v[108:109]
	v_pk_mul_f32 v[98:99], v[102:103], v[98:99]
	v_pk_mul_f32 v[100:101], v[104:105], v[100:101]
	v_pk_mul_f32 v[110:111], v[110:111], v[160:161] op_sel_hi:[1,0]
	v_pk_mul_f32 v[112:113], v[112:113], v[160:161] op_sel_hi:[1,0]
	v_pk_mul_f32 v[102:103], v[102:103], v[160:161] op_sel_hi:[1,0]
	v_pk_mul_f32 v[104:105], v[104:105], v[160:161] op_sel_hi:[1,0]
	v_exp_f32_e32 v110, v110
	v_exp_f32_e32 v111, v111
	v_exp_f32_e32 v112, v112
	v_exp_f32_e32 v113, v113
	v_exp_f32_e32 v102, v102
	v_exp_f32_e32 v103, v103
	v_exp_f32_e32 v104, v104
	v_exp_f32_e32 v105, v105
	v_pk_add_f32 v[110:111], v[110:111], 1.0 op_sel_hi:[1,0]
	v_pk_add_f32 v[112:113], v[112:113], 1.0 op_sel_hi:[1,0]
	v_pk_add_f32 v[102:103], v[102:103], 1.0 op_sel_hi:[1,0]
	v_pk_add_f32 v[104:105], v[104:105], 1.0 op_sel_hi:[1,0]
	v_rcp_f32_e32 v110, v110
	v_rcp_f32_e32 v111, v111
	v_rcp_f32_e32 v112, v112
	v_rcp_f32_e32 v113, v113
	v_rcp_f32_e32 v102, v102
	v_rcp_f32_e32 v103, v103
	v_rcp_f32_e32 v104, v104
	v_rcp_f32_e32 v105, v105
	v_pk_mul_f32 v[106:107], v[110:111], v[106:107]
	v_pk_mul_f32 v[108:109], v[112:113], v[108:109]
	v_pk_mul_f32 v[98:99], v[102:103], v[98:99]
	v_pk_mul_f32 v[100:101], v[104:105], v[100:101]
	v_cvt_pk_bf16_f32 v106, v106, v107
	v_cvt_pk_bf16_f32 v107, v108, v109
	v_cvt_pk_bf16_f32 v108, v98, v99
	v_cvt_pk_bf16_f32 v109, v100, v101
	global_store_dwordx4 v[114:115], v[106:109], off
	v_or_b32_e32 v98, 32, v156
	v_mad_i64_i32 v[98:99], s[0:1], v98, s59, v[148:149]
	v_lshl_add_u64 v[98:99], v[98:99], 0, v[146:147]
	v_pk_mul_f32 v[90:91], v[94:95], v[90:91]
	v_pk_mul_f32 v[92:93], v[96:97], v[92:93]
	v_pk_mul_f32 v[82:83], v[86:87], v[82:83]
	v_pk_mul_f32 v[84:85], v[88:89], v[84:85]
	v_pk_mul_f32 v[94:95], v[94:95], v[160:161] op_sel_hi:[1,0]
	v_pk_mul_f32 v[96:97], v[96:97], v[160:161] op_sel_hi:[1,0]
	v_pk_mul_f32 v[86:87], v[86:87], v[160:161] op_sel_hi:[1,0]
	v_pk_mul_f32 v[88:89], v[88:89], v[160:161] op_sel_hi:[1,0]
	v_exp_f32_e32 v94, v94
	v_exp_f32_e32 v95, v95
	v_exp_f32_e32 v96, v96
	v_exp_f32_e32 v97, v97
	v_exp_f32_e32 v86, v86
	v_exp_f32_e32 v87, v87
	v_exp_f32_e32 v88, v88
	v_exp_f32_e32 v89, v89
	v_pk_add_f32 v[94:95], v[94:95], 1.0 op_sel_hi:[1,0]
	v_pk_add_f32 v[96:97], v[96:97], 1.0 op_sel_hi:[1,0]
	v_pk_add_f32 v[86:87], v[86:87], 1.0 op_sel_hi:[1,0]
	v_pk_add_f32 v[88:89], v[88:89], 1.0 op_sel_hi:[1,0]
	v_rcp_f32_e32 v94, v94
	v_rcp_f32_e32 v95, v95
	v_rcp_f32_e32 v96, v96
	v_rcp_f32_e32 v97, v97
	v_rcp_f32_e32 v86, v86
	v_rcp_f32_e32 v87, v87
	v_rcp_f32_e32 v88, v88
	v_rcp_f32_e32 v89, v89
	v_pk_mul_f32 v[90:91], v[94:95], v[90:91]
	v_pk_mul_f32 v[92:93], v[96:97], v[92:93]
	v_pk_mul_f32 v[82:83], v[86:87], v[82:83]
	v_pk_mul_f32 v[84:85], v[88:89], v[84:85]
	v_cvt_pk_bf16_f32 v90, v90, v91
	v_cvt_pk_bf16_f32 v91, v92, v93
	v_cvt_pk_bf16_f32 v92, v82, v83
	v_cvt_pk_bf16_f32 v93, v84, v85
	global_store_dwordx4 v[98:99], v[90:93], off
	v_or_b32_e32 v82, 48, v156
	v_mad_i64_i32 v[82:83], s[0:1], v82, s59, v[148:149]
	v_lshl_add_u64 v[82:83], v[82:83], 0, v[146:147]
	v_pk_mul_f32 v[74:75], v[78:79], v[74:75]
	v_pk_mul_f32 v[76:77], v[80:81], v[76:77]
	v_pk_mul_f32 v[66:67], v[70:71], v[66:67]
	v_pk_mul_f32 v[68:69], v[72:73], v[68:69]
	v_pk_mul_f32 v[78:79], v[78:79], v[160:161] op_sel_hi:[1,0]
	v_pk_mul_f32 v[80:81], v[80:81], v[160:161] op_sel_hi:[1,0]
	v_pk_mul_f32 v[70:71], v[70:71], v[160:161] op_sel_hi:[1,0]
	v_pk_mul_f32 v[72:73], v[72:73], v[160:161] op_sel_hi:[1,0]
	v_exp_f32_e32 v78, v78
	v_exp_f32_e32 v79, v79
	v_exp_f32_e32 v80, v80
	v_exp_f32_e32 v81, v81
	v_exp_f32_e32 v70, v70
	v_exp_f32_e32 v71, v71
	v_exp_f32_e32 v72, v72
	v_exp_f32_e32 v73, v73
	v_pk_add_f32 v[78:79], v[78:79], 1.0 op_sel_hi:[1,0]
	v_pk_add_f32 v[80:81], v[80:81], 1.0 op_sel_hi:[1,0]
	v_pk_add_f32 v[70:71], v[70:71], 1.0 op_sel_hi:[1,0]
	v_pk_add_f32 v[72:73], v[72:73], 1.0 op_sel_hi:[1,0]
	v_rcp_f32_e32 v78, v78
	v_rcp_f32_e32 v79, v79
	v_rcp_f32_e32 v80, v80
	v_rcp_f32_e32 v81, v81
	v_rcp_f32_e32 v70, v70
	v_rcp_f32_e32 v71, v71
	v_rcp_f32_e32 v72, v72
	v_rcp_f32_e32 v73, v73
	v_pk_mul_f32 v[74:75], v[78:79], v[74:75]
	v_pk_mul_f32 v[76:77], v[80:81], v[76:77]
	v_pk_mul_f32 v[66:67], v[70:71], v[66:67]
	v_pk_mul_f32 v[68:69], v[72:73], v[68:69]
	v_cvt_pk_bf16_f32 v74, v74, v75
	v_cvt_pk_bf16_f32 v75, v76, v77
	v_cvt_pk_bf16_f32 v76, v66, v67
	v_cvt_pk_bf16_f32 v77, v68, v69
	global_store_dwordx4 v[82:83], v[74:77], off
	v_add_u32_e32 v66, 0x80, v156
	v_mad_i64_i32 v[66:67], s[0:1], v66, s59, v[148:149]
	v_lshl_add_u64 v[66:67], v[66:67], 0, v[146:147]
	v_pk_mul_f32 v[58:59], v[62:63], v[58:59]
	v_pk_mul_f32 v[60:61], v[64:65], v[60:61]
	v_pk_mul_f32 v[50:51], v[54:55], v[50:51]
	v_pk_mul_f32 v[52:53], v[56:57], v[52:53]
	v_pk_mul_f32 v[62:63], v[62:63], v[160:161] op_sel_hi:[1,0]
	v_pk_mul_f32 v[64:65], v[64:65], v[160:161] op_sel_hi:[1,0]
	v_pk_mul_f32 v[54:55], v[54:55], v[160:161] op_sel_hi:[1,0]
	v_pk_mul_f32 v[56:57], v[56:57], v[160:161] op_sel_hi:[1,0]
	v_exp_f32_e32 v62, v62
	v_exp_f32_e32 v63, v63
	v_exp_f32_e32 v64, v64
	v_exp_f32_e32 v65, v65
	v_exp_f32_e32 v54, v54
	v_exp_f32_e32 v55, v55
	v_exp_f32_e32 v56, v56
	v_exp_f32_e32 v57, v57
	v_pk_add_f32 v[62:63], v[62:63], 1.0 op_sel_hi:[1,0]
	v_pk_add_f32 v[64:65], v[64:65], 1.0 op_sel_hi:[1,0]
	v_pk_add_f32 v[54:55], v[54:55], 1.0 op_sel_hi:[1,0]
	v_pk_add_f32 v[56:57], v[56:57], 1.0 op_sel_hi:[1,0]
	v_rcp_f32_e32 v62, v62
	v_rcp_f32_e32 v63, v63
	v_rcp_f32_e32 v64, v64
	v_rcp_f32_e32 v65, v65
	v_rcp_f32_e32 v54, v54
	v_rcp_f32_e32 v55, v55
	v_rcp_f32_e32 v56, v56
	v_rcp_f32_e32 v57, v57
	v_pk_mul_f32 v[58:59], v[62:63], v[58:59]
	v_pk_mul_f32 v[60:61], v[64:65], v[60:61]
	v_pk_mul_f32 v[50:51], v[54:55], v[50:51]
	v_pk_mul_f32 v[52:53], v[56:57], v[52:53]
	v_cvt_pk_bf16_f32 v58, v58, v59
	v_cvt_pk_bf16_f32 v59, v60, v61
	v_cvt_pk_bf16_f32 v60, v50, v51
	v_cvt_pk_bf16_f32 v61, v52, v53
	global_store_dwordx4 v[66:67], v[58:61], off
	v_add_u32_e32 v50, 0x90, v156
	v_mad_i64_i32 v[50:51], s[0:1], v50, s59, v[148:149]
	v_lshl_add_u64 v[50:51], v[50:51], 0, v[146:147]
	v_pk_mul_f32 v[42:43], v[46:47], v[42:43]
	v_pk_mul_f32 v[44:45], v[48:49], v[44:45]
	v_pk_mul_f32 v[34:35], v[38:39], v[34:35]
	v_pk_mul_f32 v[36:37], v[40:41], v[36:37]
	v_pk_mul_f32 v[46:47], v[46:47], v[160:161] op_sel_hi:[1,0]
	v_pk_mul_f32 v[48:49], v[48:49], v[160:161] op_sel_hi:[1,0]
	v_pk_mul_f32 v[38:39], v[38:39], v[160:161] op_sel_hi:[1,0]
	v_pk_mul_f32 v[40:41], v[40:41], v[160:161] op_sel_hi:[1,0]
	v_exp_f32_e32 v46, v46
	v_exp_f32_e32 v47, v47
	v_exp_f32_e32 v48, v48
	v_exp_f32_e32 v49, v49
	v_exp_f32_e32 v38, v38
	v_exp_f32_e32 v39, v39
	v_exp_f32_e32 v40, v40
	v_exp_f32_e32 v41, v41
	v_pk_add_f32 v[46:47], v[46:47], 1.0 op_sel_hi:[1,0]
	v_pk_add_f32 v[48:49], v[48:49], 1.0 op_sel_hi:[1,0]
	v_pk_add_f32 v[38:39], v[38:39], 1.0 op_sel_hi:[1,0]
	v_pk_add_f32 v[40:41], v[40:41], 1.0 op_sel_hi:[1,0]
	v_rcp_f32_e32 v46, v46
	v_rcp_f32_e32 v47, v47
	v_rcp_f32_e32 v48, v48
	v_rcp_f32_e32 v49, v49
	v_rcp_f32_e32 v38, v38
	v_rcp_f32_e32 v39, v39
	v_rcp_f32_e32 v40, v40
	v_rcp_f32_e32 v41, v41
	v_pk_mul_f32 v[42:43], v[46:47], v[42:43]
	v_pk_mul_f32 v[44:45], v[48:49], v[44:45]
	v_pk_mul_f32 v[34:35], v[38:39], v[34:35]
	v_pk_mul_f32 v[36:37], v[40:41], v[36:37]
	v_cvt_pk_bf16_f32 v42, v42, v43
	v_cvt_pk_bf16_f32 v43, v44, v45
	v_cvt_pk_bf16_f32 v44, v34, v35
	v_cvt_pk_bf16_f32 v45, v36, v37
	global_store_dwordx4 v[50:51], v[42:45], off
	v_add_u32_e32 v34, 0xa0, v156
	v_mad_i64_i32 v[34:35], s[0:1], v34, s59, v[148:149]
	v_lshl_add_u64 v[34:35], v[34:35], 0, v[146:147]
	v_pk_mul_f32 v[26:27], v[30:31], v[26:27]
	v_pk_mul_f32 v[28:29], v[32:33], v[28:29]
	v_pk_mul_f32 v[18:19], v[22:23], v[18:19]
	v_pk_mul_f32 v[20:21], v[24:25], v[20:21]
	v_pk_mul_f32 v[30:31], v[30:31], v[160:161] op_sel_hi:[1,0]
	v_pk_mul_f32 v[32:33], v[32:33], v[160:161] op_sel_hi:[1,0]
	v_pk_mul_f32 v[22:23], v[22:23], v[160:161] op_sel_hi:[1,0]
	v_pk_mul_f32 v[24:25], v[24:25], v[160:161] op_sel_hi:[1,0]
	v_exp_f32_e32 v30, v30
	v_exp_f32_e32 v31, v31
	v_exp_f32_e32 v32, v32
	v_exp_f32_e32 v33, v33
	v_exp_f32_e32 v22, v22
	v_exp_f32_e32 v23, v23
	v_exp_f32_e32 v24, v24
	v_exp_f32_e32 v25, v25
	v_pk_add_f32 v[30:31], v[30:31], 1.0 op_sel_hi:[1,0]
	v_pk_add_f32 v[32:33], v[32:33], 1.0 op_sel_hi:[1,0]
	v_pk_add_f32 v[22:23], v[22:23], 1.0 op_sel_hi:[1,0]
	v_pk_add_f32 v[24:25], v[24:25], 1.0 op_sel_hi:[1,0]
	v_rcp_f32_e32 v30, v30
	v_rcp_f32_e32 v31, v31
	v_rcp_f32_e32 v32, v32
	v_rcp_f32_e32 v33, v33
	v_rcp_f32_e32 v22, v22
	v_rcp_f32_e32 v23, v23
	v_rcp_f32_e32 v24, v24
	v_rcp_f32_e32 v25, v25
	v_pk_mul_f32 v[26:27], v[30:31], v[26:27]
	v_pk_mul_f32 v[28:29], v[32:33], v[28:29]
	v_pk_mul_f32 v[18:19], v[22:23], v[18:19]
	v_pk_mul_f32 v[20:21], v[24:25], v[20:21]
	v_cvt_pk_bf16_f32 v26, v26, v27
	v_cvt_pk_bf16_f32 v27, v28, v29
	v_cvt_pk_bf16_f32 v28, v18, v19
	v_cvt_pk_bf16_f32 v29, v20, v21
	global_store_dwordx4 v[34:35], v[26:29], off
	v_add_u32_e32 v18, 0xb0, v156
	v_mad_i64_i32 v[18:19], s[0:1], v18, s59, v[148:149]
	v_lshl_add_u64 v[18:19], v[18:19], 0, v[146:147]
	s_andn2_b64 vcc, exec, s[2:3]
	s_mov_b64 s[0:1], -1
	v_pk_mul_f32 v[10:11], v[14:15], v[10:11]
	v_pk_mul_f32 v[12:13], v[16:17], v[12:13]
	v_pk_mul_f32 v[2:3], v[6:7], v[2:3]
	v_pk_mul_f32 v[4:5], v[8:9], v[4:5]
	v_pk_mul_f32 v[14:15], v[14:15], v[160:161] op_sel_hi:[1,0]
	v_pk_mul_f32 v[16:17], v[16:17], v[160:161] op_sel_hi:[1,0]
	v_pk_mul_f32 v[6:7], v[6:7], v[160:161] op_sel_hi:[1,0]
	v_pk_mul_f32 v[8:9], v[8:9], v[160:161] op_sel_hi:[1,0]
	v_exp_f32_e32 v14, v14
	v_exp_f32_e32 v15, v15
	v_exp_f32_e32 v16, v16
	v_exp_f32_e32 v17, v17
	v_exp_f32_e32 v6, v6
	v_exp_f32_e32 v7, v7
	v_exp_f32_e32 v8, v8
	v_exp_f32_e32 v9, v9
	v_pk_add_f32 v[14:15], v[14:15], 1.0 op_sel_hi:[1,0]
	v_pk_add_f32 v[16:17], v[16:17], 1.0 op_sel_hi:[1,0]
	v_pk_add_f32 v[6:7], v[6:7], 1.0 op_sel_hi:[1,0]
	v_pk_add_f32 v[8:9], v[8:9], 1.0 op_sel_hi:[1,0]
	v_rcp_f32_e32 v14, v14
	v_rcp_f32_e32 v15, v15
	v_rcp_f32_e32 v16, v16
	v_rcp_f32_e32 v17, v17
	v_rcp_f32_e32 v6, v6
	v_rcp_f32_e32 v7, v7
	v_rcp_f32_e32 v8, v8
	v_rcp_f32_e32 v9, v9
	v_pk_mul_f32 v[10:11], v[14:15], v[10:11]
	v_pk_mul_f32 v[12:13], v[16:17], v[12:13]
	v_pk_mul_f32 v[2:3], v[6:7], v[2:3]
	v_pk_mul_f32 v[4:5], v[8:9], v[4:5]
	v_cvt_pk_bf16_f32 v10, v10, v11
	v_cvt_pk_bf16_f32 v11, v12, v13
	v_cvt_pk_bf16_f32 v12, v2, v3
	v_cvt_pk_bf16_f32 v13, v4, v5
	global_store_dwordx4 v[18:19], v[10:13], off
	s_cbranch_vccnz .LBB0_3305
	s_andn2_b64 vcc, exec, s[6:7]
	s_cbranch_vccnz .LBB0_3304
	s_barrier
	s_branch .LBB0_3304

.LBB0_3835:
	ds_read_b128 v[146:149], v153
	ds_read_b128 v[156:159], v153 offset:1024
	ds_read_b128 v[160:163], v153 offset:2048
	ds_read_b128 v[164:167], v153 offset:3072
	ds_read_b128 v[168:171], v154
	ds_read_b128 v[172:175], v154 offset:1024
	ds_read_b128 v[176:179], v154 offset:2048
	ds_read_b128 v[180:183], v154 offset:3072
	s_add_u32 s34, s38, 0xfff80080
	s_addc_u32 s35, s39, -1
	s_cmp_eq_u32 s57, 28
	s_cselect_b32 s41, s0, s35
	s_cselect_b32 s40, s1, s34
	s_cselect_b32 s35, s15, s56
	s_cselect_b32 s34, s17, s55
	v_lshl_add_u64 v[218:219], s[38:39], 0, v[138:139]
	s_add_i32 m0, s37, 0xc000
	ds_read_b128 v[184:187], v155
	ds_read_b128 v[188:191], v155 offset:1024
	ds_read_b128 v[192:195], v155 offset:2048
	ds_read_b128 v[196:199], v155 offset:3072
	ds_read_b128 v[200:203], v155 offset:4096
	ds_read_b128 v[204:207], v155 offset:5120
	ds_read_b128 v[208:211], v155 offset:6144
	ds_read_b128 v[212:215], v155 offset:7168
	global_load_lds_dwordx4 v[218:219], off
	v_lshl_add_u64 v[218:219], s[38:39], 0, v[140:141]
	s_add_i32 m0, s37, 0xe000
	s_nop 0
	global_load_lds_dwordx4 v[218:219], off
	s_waitcnt vmcnt(8)
	s_waitcnt lgkmcnt(0)
	s_barrier
	s_setprio 1
	s_waitcnt lgkmcnt(0)
	v_mfma_f32_16x16x32_bf16 v[126:129], v[146:149], v[184:187], v[126:129]
	v_mfma_f32_16x16x32_bf16 v[118:121], v[160:163], v[184:187], v[118:121]
	v_mfma_f32_16x16x32_bf16 v[110:113], v[146:149], v[192:195], v[110:113]
	v_mfma_f32_16x16x32_bf16 v[102:105], v[160:163], v[192:195], v[102:105]
	v_mfma_f32_16x16x32_bf16 v[94:97], v[146:149], v[200:203], v[94:97]
	v_mfma_f32_16x16x32_bf16 v[86:89], v[160:163], v[200:203], v[86:89]
	v_mfma_f32_16x16x32_bf16 v[78:81], v[146:149], v[208:211], v[78:81]
	v_mfma_f32_16x16x32_bf16 v[70:73], v[160:163], v[208:211], v[70:73]
	v_mfma_f32_16x16x32_bf16 v[126:129], v[156:159], v[188:191], v[126:129]
	v_mfma_f32_16x16x32_bf16 v[118:121], v[164:167], v[188:191], v[118:121]
	v_mfma_f32_16x16x32_bf16 v[110:113], v[156:159], v[196:199], v[110:113]
	v_mfma_f32_16x16x32_bf16 v[102:105], v[164:167], v[196:199], v[102:105]
	v_mfma_f32_16x16x32_bf16 v[94:97], v[156:159], v[204:207], v[94:97]
	v_mfma_f32_16x16x32_bf16 v[86:89], v[164:167], v[204:207], v[86:89]
	v_mfma_f32_16x16x32_bf16 v[78:81], v[156:159], v[212:215], v[78:81]
	v_mfma_f32_16x16x32_bf16 v[70:73], v[164:167], v[212:215], v[70:73]
	s_setprio 0
	s_setprio 1
	v_mfma_f32_16x16x32_bf16 v[122:125], v[168:171], v[184:187], v[122:125]
	v_mfma_f32_16x16x32_bf16 v[114:117], v[176:179], v[184:187], v[114:117]
	v_mfma_f32_16x16x32_bf16 v[106:109], v[168:171], v[192:195], v[106:109]
	v_mfma_f32_16x16x32_bf16 v[98:101], v[176:179], v[192:195], v[98:101]
	v_mfma_f32_16x16x32_bf16 v[90:93], v[168:171], v[200:203], v[90:93]
	v_mfma_f32_16x16x32_bf16 v[82:85], v[176:179], v[200:203], v[82:85]
	v_mfma_f32_16x16x32_bf16 v[74:77], v[168:171], v[208:211], v[74:77]
	v_mfma_f32_16x16x32_bf16 v[66:69], v[176:179], v[208:211], v[66:69]
	v_mfma_f32_16x16x32_bf16 v[122:125], v[172:175], v[188:191], v[122:125]
	v_mfma_f32_16x16x32_bf16 v[114:117], v[180:183], v[188:191], v[114:117]
	v_mfma_f32_16x16x32_bf16 v[106:109], v[172:175], v[196:199], v[106:109]
	v_mfma_f32_16x16x32_bf16 v[98:101], v[180:183], v[196:199], v[98:101]
	v_mfma_f32_16x16x32_bf16 v[90:93], v[172:175], v[204:207], v[90:93]
	v_mfma_f32_16x16x32_bf16 v[82:85], v[180:183], v[204:207], v[82:85]
	v_mfma_f32_16x16x32_bf16 v[74:77], v[172:175], v[212:215], v[74:77]
	v_mfma_f32_16x16x32_bf16 v[66:69], v[180:183], v[212:215], v[66:69]
	s_setprio 0
	s_barrier
	s_add_i32 s58, s51, s33
	v_lshl_add_u64 v[218:219], s[34:35], 0, v[134:135]
	s_mov_b32 m0, s58
	ds_read_b128 v[184:187], v155 offset:16384
	ds_read_b128 v[188:191], v155 offset:17408
	ds_read_b128 v[192:195], v155 offset:18432
	ds_read_b128 v[196:199], v155 offset:19456
	ds_read_b128 v[200:203], v155 offset:20480
	ds_read_b128 v[204:207], v155 offset:21504
	ds_read_b128 v[208:211], v155 offset:22528
	ds_read_b128 v[212:215], v155 offset:23552
	global_load_lds_dwordx4 v[218:219], off
	s_add_i32 m0, s58, 0x2000
	s_add_u32 s58, s34, 0x80000
	v_lshl_add_u64 v[220:221], s[34:35], 0, v[130:131]
	s_addc_u32 s59, s35, 0
	s_add_i32 s60, s52, s33
	global_load_lds_dwordx4 v[220:221], off
	v_lshl_add_u64 v[222:223], s[58:59], 0, v[134:135]
	s_mov_b32 m0, s60
	v_lshl_add_u64 v[224:225], s[40:41], 0, v[132:133]
	global_load_lds_dwordx4 v[222:223], off
	v_lshl_add_u64 v[222:223], s[58:59], 0, v[130:131]
	s_add_i32 m0, s60, 0x2000
	s_nop 0
	global_load_lds_dwordx4 v[222:223], off
	v_lshl_add_u64 v[222:223], s[40:41], 0, v[136:137]
	s_mov_b32 m0, s37
	s_nop 0
	global_load_lds_dwordx4 v[222:223], off
	s_mov_b32 m0, s44
	s_nop 0
	global_load_lds_dwordx4 v[224:225], off
	s_waitcnt vmcnt(8)
	s_waitcnt lgkmcnt(0)
	s_barrier
	s_setprio 1
	s_waitcnt lgkmcnt(0)
	v_mfma_f32_16x16x32_bf16 v[62:65], v[146:149], v[184:187], v[62:65]
	v_mfma_f32_16x16x32_bf16 v[54:57], v[160:163], v[184:187], v[54:57]
	v_mfma_f32_16x16x32_bf16 v[46:49], v[146:149], v[192:195], v[46:49]
	v_mfma_f32_16x16x32_bf16 v[38:41], v[160:163], v[192:195], v[38:41]
	v_mfma_f32_16x16x32_bf16 v[30:33], v[146:149], v[200:203], v[30:33]
	v_mfma_f32_16x16x32_bf16 v[22:25], v[160:163], v[200:203], v[22:25]
	v_mfma_f32_16x16x32_bf16 v[14:17], v[146:149], v[208:211], v[14:17]
	v_mfma_f32_16x16x32_bf16 v[6:9], v[160:163], v[208:211], v[6:9]
	v_mfma_f32_16x16x32_bf16 v[62:65], v[156:159], v[188:191], v[62:65]
	v_mfma_f32_16x16x32_bf16 v[54:57], v[164:167], v[188:191], v[54:57]
	v_mfma_f32_16x16x32_bf16 v[46:49], v[156:159], v[196:199], v[46:49]
	v_mfma_f32_16x16x32_bf16 v[38:41], v[164:167], v[196:199], v[38:41]
	v_mfma_f32_16x16x32_bf16 v[30:33], v[156:159], v[204:207], v[30:33]
	v_mfma_f32_16x16x32_bf16 v[22:25], v[164:167], v[204:207], v[22:25]
	v_mfma_f32_16x16x32_bf16 v[14:17], v[156:159], v[212:215], v[14:17]
	v_mfma_f32_16x16x32_bf16 v[6:9], v[164:167], v[212:215], v[6:9]
	s_setprio 0
	s_setprio 1
	v_mfma_f32_16x16x32_bf16 v[58:61], v[168:171], v[184:187], v[58:61]
	v_mfma_f32_16x16x32_bf16 v[50:53], v[176:179], v[184:187], v[50:53]
	v_mfma_f32_16x16x32_bf16 v[42:45], v[168:171], v[192:195], v[42:45]
	v_mfma_f32_16x16x32_bf16 v[34:37], v[176:179], v[192:195], v[34:37]
	v_mfma_f32_16x16x32_bf16 v[26:29], v[168:171], v[200:203], v[26:29]
	v_mfma_f32_16x16x32_bf16 v[18:21], v[176:179], v[200:203], v[18:21]
	v_mfma_f32_16x16x32_bf16 v[10:13], v[168:171], v[208:211], v[10:13]
	v_mfma_f32_16x16x32_bf16 v[2:5], v[176:179], v[208:211], v[2:5]
	v_mfma_f32_16x16x32_bf16 v[58:61], v[172:175], v[188:191], v[58:61]
	v_mfma_f32_16x16x32_bf16 v[50:53], v[180:183], v[188:191], v[50:53]
	v_mfma_f32_16x16x32_bf16 v[42:45], v[172:175], v[196:199], v[42:45]
	v_mfma_f32_16x16x32_bf16 v[34:37], v[180:183], v[196:199], v[34:37]
	v_mfma_f32_16x16x32_bf16 v[26:29], v[172:175], v[204:207], v[26:29]
	v_mfma_f32_16x16x32_bf16 v[18:21], v[180:183], v[204:207], v[18:21]
	v_mfma_f32_16x16x32_bf16 v[10:13], v[172:175], v[212:215], v[10:13]
	v_mfma_f32_16x16x32_bf16 v[2:5], v[180:183], v[212:215], v[2:5]
	s_setprio 0
	s_barrier
	s_add_i32 s58, 0, 0x18000
	s_add_i32 s59, 0, 0x1c000
	v_add_u32_e32 v164, s58, v151
	v_add_u32_e32 v180, s59, v151
	ds_read_b128 v[146:149], v164
	ds_read_b128 v[156:159], v164 offset:1024
	ds_read_b128 v[160:163], v164 offset:2048
	ds_read_b128 v[164:167], v164 offset:3072
	ds_read_b128 v[168:171], v180
	ds_read_b128 v[172:175], v180 offset:1024
	ds_read_b128 v[176:179], v180 offset:2048
	ds_read_b128 v[180:183], v180 offset:3072
	s_add_u32 s40, s40, 0x80000
	s_addc_u32 s41, s41, 0
	s_mov_b32 m0, s45
	v_lshl_add_u64 v[226:227], s[40:41], 0, v[136:137]
	ds_read_b128 v[184:187], v155 offset:32768
	ds_read_b128 v[188:191], v155 offset:33792
	ds_read_b128 v[192:195], v155 offset:34816
	ds_read_b128 v[196:199], v155 offset:35840
	ds_read_b128 v[200:203], v155 offset:36864
	ds_read_b128 v[204:207], v155 offset:37888
	ds_read_b128 v[208:211], v155 offset:38912
	ds_read_b128 v[212:215], v155 offset:39936
	global_load_lds_dwordx4 v[226:227], off
	v_lshl_add_u64 v[226:227], s[40:41], 0, v[132:133]
	s_mov_b32 m0, s46
	s_nop 0
	global_load_lds_dwordx4 v[226:227], off
	s_waitcnt vmcnt(8)
	s_waitcnt lgkmcnt(0)
	s_barrier
	s_setprio 1
	s_waitcnt lgkmcnt(0)
	v_mfma_f32_16x16x32_bf16 v[126:129], v[146:149], v[184:187], v[126:129]
	v_mfma_f32_16x16x32_bf16 v[118:121], v[160:163], v[184:187], v[118:121]
	v_mfma_f32_16x16x32_bf16 v[110:113], v[146:149], v[192:195], v[110:113]
	v_mfma_f32_16x16x32_bf16 v[102:105], v[160:163], v[192:195], v[102:105]
	v_mfma_f32_16x16x32_bf16 v[94:97], v[146:149], v[200:203], v[94:97]
	v_mfma_f32_16x16x32_bf16 v[86:89], v[160:163], v[200:203], v[86:89]
	v_mfma_f32_16x16x32_bf16 v[78:81], v[146:149], v[208:211], v[78:81]
	v_mfma_f32_16x16x32_bf16 v[70:73], v[160:163], v[208:211], v[70:73]
	v_mfma_f32_16x16x32_bf16 v[126:129], v[156:159], v[188:191], v[126:129]
	v_mfma_f32_16x16x32_bf16 v[118:121], v[164:167], v[188:191], v[118:121]
	v_mfma_f32_16x16x32_bf16 v[110:113], v[156:159], v[196:199], v[110:113]
	v_mfma_f32_16x16x32_bf16 v[102:105], v[164:167], v[196:199], v[102:105]
	v_mfma_f32_16x16x32_bf16 v[94:97], v[156:159], v[204:207], v[94:97]
	v_mfma_f32_16x16x32_bf16 v[86:89], v[164:167], v[204:207], v[86:89]
	v_mfma_f32_16x16x32_bf16 v[78:81], v[156:159], v[212:215], v[78:81]
	v_mfma_f32_16x16x32_bf16 v[70:73], v[164:167], v[212:215], v[70:73]
	s_setprio 0
	s_setprio 1
	v_mfma_f32_16x16x32_bf16 v[122:125], v[168:171], v[184:187], v[122:125]
	v_mfma_f32_16x16x32_bf16 v[114:117], v[176:179], v[184:187], v[114:117]
	v_mfma_f32_16x16x32_bf16 v[106:109], v[168:171], v[192:195], v[106:109]
	v_mfma_f32_16x16x32_bf16 v[98:101], v[176:179], v[192:195], v[98:101]
	v_mfma_f32_16x16x32_bf16 v[90:93], v[168:171], v[200:203], v[90:93]
	v_mfma_f32_16x16x32_bf16 v[82:85], v[176:179], v[200:203], v[82:85]
	v_mfma_f32_16x16x32_bf16 v[74:77], v[168:171], v[208:211], v[74:77]
	v_mfma_f32_16x16x32_bf16 v[66:69], v[176:179], v[208:211], v[66:69]
	v_mfma_f32_16x16x32_bf16 v[122:125], v[172:175], v[188:191], v[122:125]
	v_mfma_f32_16x16x32_bf16 v[114:117], v[180:183], v[188:191], v[114:117]
	v_mfma_f32_16x16x32_bf16 v[106:109], v[172:175], v[196:199], v[106:109]
	v_mfma_f32_16x16x32_bf16 v[98:101], v[180:183], v[196:199], v[98:101]
	v_mfma_f32_16x16x32_bf16 v[90:93], v[172:175], v[204:207], v[90:93]
	v_mfma_f32_16x16x32_bf16 v[82:85], v[180:183], v[204:207], v[82:85]
	v_mfma_f32_16x16x32_bf16 v[74:77], v[172:175], v[212:215], v[74:77]
	v_mfma_f32_16x16x32_bf16 v[66:69], v[180:183], v[212:215], v[66:69]
	s_setprio 0
	s_barrier
	s_add_i32 s40, s58, s33
	v_lshl_add_u64 v[218:219], v[218:219], 0, s[8:9]
	s_mov_b32 m0, s40
	ds_read_b128 v[184:187], v155 offset:49152
	ds_read_b128 v[188:191], v155 offset:50176
	ds_read_b128 v[192:195], v155 offset:51200
	ds_read_b128 v[196:199], v155 offset:52224
	ds_read_b128 v[200:203], v155 offset:53248
	ds_read_b128 v[204:207], v155 offset:54272
	ds_read_b128 v[208:211], v155 offset:55296
	ds_read_b128 v[212:215], v155 offset:56320
	global_load_lds_dwordx4 v[218:219], off
	s_add_i32 m0, s40, 0x2000
	s_add_u32 s34, s34, 0x80080
	v_lshl_add_u64 v[218:219], v[220:221], 0, s[8:9]
	s_addc_u32 s35, s35, 0
	s_add_i32 s40, s59, s33
	global_load_lds_dwordx4 v[218:219], off
	v_lshl_add_u64 v[218:219], s[34:35], 0, v[134:135]
	s_mov_b32 m0, s40
	s_nop 0
	global_load_lds_dwordx4 v[218:219], off
	v_lshl_add_u64 v[218:219], s[34:35], 0, v[130:131]
	s_add_i32 m0, s40, 0x2000
	s_nop 0
	global_load_lds_dwordx4 v[218:219], off
	v_lshl_add_u64 v[218:219], v[222:223], 0, s[8:9]
	s_mov_b32 m0, s48
	s_nop 0
	global_load_lds_dwordx4 v[218:219], off
	v_lshl_add_u64 v[218:219], v[224:225], 0, s[8:9]
	s_mov_b32 m0, s49
	s_nop 0
	global_load_lds_dwordx4 v[218:219], off
	s_waitcnt vmcnt(8)
	s_waitcnt lgkmcnt(0)
	s_barrier
	s_setprio 1
	s_waitcnt lgkmcnt(0)
	v_mfma_f32_16x16x32_bf16 v[62:65], v[146:149], v[184:187], v[62:65]
	v_mfma_f32_16x16x32_bf16 v[54:57], v[160:163], v[184:187], v[54:57]
	v_mfma_f32_16x16x32_bf16 v[46:49], v[146:149], v[192:195], v[46:49]
	v_mfma_f32_16x16x32_bf16 v[38:41], v[160:163], v[192:195], v[38:41]
	v_mfma_f32_16x16x32_bf16 v[30:33], v[146:149], v[200:203], v[30:33]
	v_mfma_f32_16x16x32_bf16 v[22:25], v[160:163], v[200:203], v[22:25]
	v_mfma_f32_16x16x32_bf16 v[14:17], v[146:149], v[208:211], v[14:17]
	v_mfma_f32_16x16x32_bf16 v[6:9], v[160:163], v[208:211], v[6:9]
	v_mfma_f32_16x16x32_bf16 v[62:65], v[156:159], v[188:191], v[62:65]
	v_mfma_f32_16x16x32_bf16 v[54:57], v[164:167], v[188:191], v[54:57]
	v_mfma_f32_16x16x32_bf16 v[46:49], v[156:159], v[196:199], v[46:49]
	v_mfma_f32_16x16x32_bf16 v[38:41], v[164:167], v[196:199], v[38:41]
	v_mfma_f32_16x16x32_bf16 v[30:33], v[156:159], v[204:207], v[30:33]
	v_mfma_f32_16x16x32_bf16 v[22:25], v[164:167], v[204:207], v[22:25]
	v_mfma_f32_16x16x32_bf16 v[14:17], v[156:159], v[212:215], v[14:17]
	v_mfma_f32_16x16x32_bf16 v[6:9], v[164:167], v[212:215], v[6:9]
	s_setprio 0
	s_setprio 1
	v_mfma_f32_16x16x32_bf16 v[58:61], v[168:171], v[184:187], v[58:61]
	v_mfma_f32_16x16x32_bf16 v[50:53], v[176:179], v[184:187], v[50:53]
	v_mfma_f32_16x16x32_bf16 v[42:45], v[168:171], v[192:195], v[42:45]
	v_mfma_f32_16x16x32_bf16 v[34:37], v[176:179], v[192:195], v[34:37]
	v_mfma_f32_16x16x32_bf16 v[26:29], v[168:171], v[200:203], v[26:29]
	v_mfma_f32_16x16x32_bf16 v[18:21], v[176:179], v[200:203], v[18:21]
	v_mfma_f32_16x16x32_bf16 v[10:13], v[168:171], v[208:211], v[10:13]
	v_mfma_f32_16x16x32_bf16 v[2:5], v[176:179], v[208:211], v[2:5]
	v_mfma_f32_16x16x32_bf16 v[58:61], v[172:175], v[188:191], v[58:61]
	v_mfma_f32_16x16x32_bf16 v[50:53], v[180:183], v[188:191], v[50:53]
	v_mfma_f32_16x16x32_bf16 v[42:45], v[172:175], v[196:199], v[42:45]
	v_mfma_f32_16x16x32_bf16 v[34:37], v[180:183], v[196:199], v[34:37]
	v_mfma_f32_16x16x32_bf16 v[26:29], v[172:175], v[204:207], v[26:29]
	v_mfma_f32_16x16x32_bf16 v[18:21], v[180:183], v[204:207], v[18:21]
	v_mfma_f32_16x16x32_bf16 v[10:13], v[172:175], v[212:215], v[10:13]
	v_mfma_f32_16x16x32_bf16 v[2:5], v[180:183], v[212:215], v[2:5]
	s_setprio 0
	s_barrier
	s_add_i32 s57, s57, 2
	s_add_u32 s38, s38, 0x100
	s_addc_u32 s39, s39, 0
	s_add_u32 s55, s55, 0x100
	s_addc_u32 s56, s56, 0
	s_cmp_gt_u32 s57, 29
	s_cbranch_scc0 .LBB0_3835
	v_mov_b32_e32 v160, 0xbfb8aa3b
	s_and_b64 vcc, exec, s[12:13]
	s_cbranch_vccz .LBB0_3838
	s_barrier
.LBB0_3838:
	v_readlane_b32 s0, v247, 31
	v_lshl_or_b32 v146, s54, 7, v152
	v_readlane_b32 s1, v247, 32
	v_lshl_add_u32 v156, s36, 8, v150
	v_ashrrev_i32_e32 v147, 31, v146
	v_mov_b64_e32 v[148:149], s[0:1]
	v_mad_i64_i32 v[158:159], s[0:1], v156, s53, v[148:149]
	v_lshlrev_b64 v[146:147], 1, v[146:147]
	v_lshl_add_u64 v[158:159], v[158:159], 0, v[146:147]
	v_pk_mul_f32 v[122:123], v[126:127], v[122:123]
	v_pk_mul_f32 v[124:125], v[128:129], v[124:125]
	v_pk_mul_f32 v[114:115], v[118:119], v[114:115]
	v_pk_mul_f32 v[116:117], v[120:121], v[116:117]
	v_pk_mul_f32 v[126:127], v[126:127], v[160:161] op_sel_hi:[1,0]
	v_pk_mul_f32 v[128:129], v[128:129], v[160:161] op_sel_hi:[1,0]
	v_pk_mul_f32 v[118:119], v[118:119], v[160:161] op_sel_hi:[1,0]
	v_pk_mul_f32 v[120:121], v[120:121], v[160:161] op_sel_hi:[1,0]
	v_exp_f32_e32 v126, v126
	v_exp_f32_e32 v127, v127
	v_exp_f32_e32 v128, v128
	v_exp_f32_e32 v129, v129
	v_exp_f32_e32 v118, v118
	v_exp_f32_e32 v119, v119
	v_exp_f32_e32 v120, v120
	v_exp_f32_e32 v121, v121
	v_pk_add_f32 v[126:127], v[126:127], 1.0 op_sel_hi:[1,0]
	v_pk_add_f32 v[128:129], v[128:129], 1.0 op_sel_hi:[1,0]
	v_pk_add_f32 v[118:119], v[118:119], 1.0 op_sel_hi:[1,0]
	v_pk_add_f32 v[120:121], v[120:121], 1.0 op_sel_hi:[1,0]
	v_rcp_f32_e32 v126, v126
	v_rcp_f32_e32 v127, v127
	v_rcp_f32_e32 v128, v128
	v_rcp_f32_e32 v129, v129
	v_rcp_f32_e32 v118, v118
	v_rcp_f32_e32 v119, v119
	v_rcp_f32_e32 v120, v120
	v_rcp_f32_e32 v121, v121
	v_pk_mul_f32 v[122:123], v[126:127], v[122:123]
	v_pk_mul_f32 v[124:125], v[128:129], v[124:125]
	v_pk_mul_f32 v[114:115], v[118:119], v[114:115]
	v_pk_mul_f32 v[116:117], v[120:121], v[116:117]
	v_cvt_pk_bf16_f32 v122, v122, v123
	v_cvt_pk_bf16_f32 v123, v124, v125
	v_cvt_pk_bf16_f32 v124, v114, v115
	v_cvt_pk_bf16_f32 v125, v116, v117
	global_store_dwordx4 v[158:159], v[122:125], off
	v_or_b32_e32 v114, 16, v156
	v_mad_i64_i32 v[114:115], s[0:1], v114, s53, v[148:149]
	v_lshl_add_u64 v[114:115], v[114:115], 0, v[146:147]
	v_pk_mul_f32 v[106:107], v[110:111], v[106:107]
	v_pk_mul_f32 v[108:109], v[112:113], v[108:109]
	v_pk_mul_f32 v[98:99], v[102:103], v[98:99]
	v_pk_mul_f32 v[100:101], v[104:105], v[100:101]
	v_pk_mul_f32 v[110:111], v[110:111], v[160:161] op_sel_hi:[1,0]
	v_pk_mul_f32 v[112:113], v[112:113], v[160:161] op_sel_hi:[1,0]
	v_pk_mul_f32 v[102:103], v[102:103], v[160:161] op_sel_hi:[1,0]
	v_pk_mul_f32 v[104:105], v[104:105], v[160:161] op_sel_hi:[1,0]
	v_exp_f32_e32 v110, v110
	v_exp_f32_e32 v111, v111
	v_exp_f32_e32 v112, v112
	v_exp_f32_e32 v113, v113
	v_exp_f32_e32 v102, v102
	v_exp_f32_e32 v103, v103
	v_exp_f32_e32 v104, v104
	v_exp_f32_e32 v105, v105
	v_pk_add_f32 v[110:111], v[110:111], 1.0 op_sel_hi:[1,0]
	v_pk_add_f32 v[112:113], v[112:113], 1.0 op_sel_hi:[1,0]
	v_pk_add_f32 v[102:103], v[102:103], 1.0 op_sel_hi:[1,0]
	v_pk_add_f32 v[104:105], v[104:105], 1.0 op_sel_hi:[1,0]
	v_rcp_f32_e32 v110, v110
	v_rcp_f32_e32 v111, v111
	v_rcp_f32_e32 v112, v112
	v_rcp_f32_e32 v113, v113
	v_rcp_f32_e32 v102, v102
	v_rcp_f32_e32 v103, v103
	v_rcp_f32_e32 v104, v104
	v_rcp_f32_e32 v105, v105
	v_pk_mul_f32 v[106:107], v[110:111], v[106:107]
	v_pk_mul_f32 v[108:109], v[112:113], v[108:109]
	v_pk_mul_f32 v[98:99], v[102:103], v[98:99]
	v_pk_mul_f32 v[100:101], v[104:105], v[100:101]
	v_cvt_pk_bf16_f32 v106, v106, v107
	v_cvt_pk_bf16_f32 v107, v108, v109
	v_cvt_pk_bf16_f32 v108, v98, v99
	v_cvt_pk_bf16_f32 v109, v100, v101
	global_store_dwordx4 v[114:115], v[106:109], off
	v_or_b32_e32 v98, 32, v156
	v_mad_i64_i32 v[98:99], s[0:1], v98, s53, v[148:149]
	v_lshl_add_u64 v[98:99], v[98:99], 0, v[146:147]
	v_pk_mul_f32 v[90:91], v[94:95], v[90:91]
	v_pk_mul_f32 v[92:93], v[96:97], v[92:93]
	v_pk_mul_f32 v[82:83], v[86:87], v[82:83]
	v_pk_mul_f32 v[84:85], v[88:89], v[84:85]
	v_pk_mul_f32 v[94:95], v[94:95], v[160:161] op_sel_hi:[1,0]
	v_pk_mul_f32 v[96:97], v[96:97], v[160:161] op_sel_hi:[1,0]
	v_pk_mul_f32 v[86:87], v[86:87], v[160:161] op_sel_hi:[1,0]
	v_pk_mul_f32 v[88:89], v[88:89], v[160:161] op_sel_hi:[1,0]
	v_exp_f32_e32 v94, v94
	v_exp_f32_e32 v95, v95
	v_exp_f32_e32 v96, v96
	v_exp_f32_e32 v97, v97
	v_exp_f32_e32 v86, v86
	v_exp_f32_e32 v87, v87
	v_exp_f32_e32 v88, v88
	v_exp_f32_e32 v89, v89
	v_pk_add_f32 v[94:95], v[94:95], 1.0 op_sel_hi:[1,0]
	v_pk_add_f32 v[96:97], v[96:97], 1.0 op_sel_hi:[1,0]
	v_pk_add_f32 v[86:87], v[86:87], 1.0 op_sel_hi:[1,0]
	v_pk_add_f32 v[88:89], v[88:89], 1.0 op_sel_hi:[1,0]
	v_rcp_f32_e32 v94, v94
	v_rcp_f32_e32 v95, v95
	v_rcp_f32_e32 v96, v96
	v_rcp_f32_e32 v97, v97
	v_rcp_f32_e32 v86, v86
	v_rcp_f32_e32 v87, v87
	v_rcp_f32_e32 v88, v88
	v_rcp_f32_e32 v89, v89
	v_pk_mul_f32 v[90:91], v[94:95], v[90:91]
	v_pk_mul_f32 v[92:93], v[96:97], v[92:93]
	v_pk_mul_f32 v[82:83], v[86:87], v[82:83]
	v_pk_mul_f32 v[84:85], v[88:89], v[84:85]
	v_cvt_pk_bf16_f32 v90, v90, v91
	v_cvt_pk_bf16_f32 v91, v92, v93
	v_cvt_pk_bf16_f32 v92, v82, v83
	v_cvt_pk_bf16_f32 v93, v84, v85
	global_store_dwordx4 v[98:99], v[90:93], off
	v_or_b32_e32 v82, 48, v156
	v_mad_i64_i32 v[82:83], s[0:1], v82, s53, v[148:149]
	v_lshl_add_u64 v[82:83], v[82:83], 0, v[146:147]
	v_pk_mul_f32 v[74:75], v[78:79], v[74:75]
	v_pk_mul_f32 v[76:77], v[80:81], v[76:77]
	v_pk_mul_f32 v[66:67], v[70:71], v[66:67]
	v_pk_mul_f32 v[68:69], v[72:73], v[68:69]
	v_pk_mul_f32 v[78:79], v[78:79], v[160:161] op_sel_hi:[1,0]
	v_pk_mul_f32 v[80:81], v[80:81], v[160:161] op_sel_hi:[1,0]
	v_pk_mul_f32 v[70:71], v[70:71], v[160:161] op_sel_hi:[1,0]
	v_pk_mul_f32 v[72:73], v[72:73], v[160:161] op_sel_hi:[1,0]
	v_exp_f32_e32 v78, v78
	v_exp_f32_e32 v79, v79
	v_exp_f32_e32 v80, v80
	v_exp_f32_e32 v81, v81
	v_exp_f32_e32 v70, v70
	v_exp_f32_e32 v71, v71
	v_exp_f32_e32 v72, v72
	v_exp_f32_e32 v73, v73
	v_pk_add_f32 v[78:79], v[78:79], 1.0 op_sel_hi:[1,0]
	v_pk_add_f32 v[80:81], v[80:81], 1.0 op_sel_hi:[1,0]
	v_pk_add_f32 v[70:71], v[70:71], 1.0 op_sel_hi:[1,0]
	v_pk_add_f32 v[72:73], v[72:73], 1.0 op_sel_hi:[1,0]
	v_rcp_f32_e32 v78, v78
	v_rcp_f32_e32 v79, v79
	v_rcp_f32_e32 v80, v80
	v_rcp_f32_e32 v81, v81
	v_rcp_f32_e32 v70, v70
	v_rcp_f32_e32 v71, v71
	v_rcp_f32_e32 v72, v72
	v_rcp_f32_e32 v73, v73
	v_pk_mul_f32 v[74:75], v[78:79], v[74:75]
	v_pk_mul_f32 v[76:77], v[80:81], v[76:77]
	v_pk_mul_f32 v[66:67], v[70:71], v[66:67]
	v_pk_mul_f32 v[68:69], v[72:73], v[68:69]
	v_cvt_pk_bf16_f32 v74, v74, v75
	v_cvt_pk_bf16_f32 v75, v76, v77
	v_cvt_pk_bf16_f32 v76, v66, v67
	v_cvt_pk_bf16_f32 v77, v68, v69
	global_store_dwordx4 v[82:83], v[74:77], off
	v_add_u32_e32 v66, 0x80, v156
	v_mad_i64_i32 v[66:67], s[0:1], v66, s53, v[148:149]
	v_lshl_add_u64 v[66:67], v[66:67], 0, v[146:147]
	v_pk_mul_f32 v[58:59], v[62:63], v[58:59]
	v_pk_mul_f32 v[60:61], v[64:65], v[60:61]
	v_pk_mul_f32 v[50:51], v[54:55], v[50:51]
	v_pk_mul_f32 v[52:53], v[56:57], v[52:53]
	v_pk_mul_f32 v[62:63], v[62:63], v[160:161] op_sel_hi:[1,0]
	v_pk_mul_f32 v[64:65], v[64:65], v[160:161] op_sel_hi:[1,0]
	v_pk_mul_f32 v[54:55], v[54:55], v[160:161] op_sel_hi:[1,0]
	v_pk_mul_f32 v[56:57], v[56:57], v[160:161] op_sel_hi:[1,0]
	v_exp_f32_e32 v62, v62
	v_exp_f32_e32 v63, v63
	v_exp_f32_e32 v64, v64
	v_exp_f32_e32 v65, v65
	v_exp_f32_e32 v54, v54
	v_exp_f32_e32 v55, v55
	v_exp_f32_e32 v56, v56
	v_exp_f32_e32 v57, v57
	v_pk_add_f32 v[62:63], v[62:63], 1.0 op_sel_hi:[1,0]
	v_pk_add_f32 v[64:65], v[64:65], 1.0 op_sel_hi:[1,0]
	v_pk_add_f32 v[54:55], v[54:55], 1.0 op_sel_hi:[1,0]
	v_pk_add_f32 v[56:57], v[56:57], 1.0 op_sel_hi:[1,0]
	v_rcp_f32_e32 v62, v62
	v_rcp_f32_e32 v63, v63
	v_rcp_f32_e32 v64, v64
	v_rcp_f32_e32 v65, v65
	v_rcp_f32_e32 v54, v54
	v_rcp_f32_e32 v55, v55
	v_rcp_f32_e32 v56, v56
	v_rcp_f32_e32 v57, v57
	v_pk_mul_f32 v[58:59], v[62:63], v[58:59]
	v_pk_mul_f32 v[60:61], v[64:65], v[60:61]
	v_pk_mul_f32 v[50:51], v[54:55], v[50:51]
	v_pk_mul_f32 v[52:53], v[56:57], v[52:53]
	v_cvt_pk_bf16_f32 v58, v58, v59
	v_cvt_pk_bf16_f32 v59, v60, v61
	v_cvt_pk_bf16_f32 v60, v50, v51
	v_cvt_pk_bf16_f32 v61, v52, v53
	global_store_dwordx4 v[66:67], v[58:61], off
	v_add_u32_e32 v50, 0x90, v156
	v_mad_i64_i32 v[50:51], s[0:1], v50, s53, v[148:149]
	v_lshl_add_u64 v[50:51], v[50:51], 0, v[146:147]
	v_pk_mul_f32 v[42:43], v[46:47], v[42:43]
	v_pk_mul_f32 v[44:45], v[48:49], v[44:45]
	v_pk_mul_f32 v[34:35], v[38:39], v[34:35]
	v_pk_mul_f32 v[36:37], v[40:41], v[36:37]
	v_pk_mul_f32 v[46:47], v[46:47], v[160:161] op_sel_hi:[1,0]
	v_pk_mul_f32 v[48:49], v[48:49], v[160:161] op_sel_hi:[1,0]
	v_pk_mul_f32 v[38:39], v[38:39], v[160:161] op_sel_hi:[1,0]
	v_pk_mul_f32 v[40:41], v[40:41], v[160:161] op_sel_hi:[1,0]
	v_exp_f32_e32 v46, v46
	v_exp_f32_e32 v47, v47
	v_exp_f32_e32 v48, v48
	v_exp_f32_e32 v49, v49
	v_exp_f32_e32 v38, v38
	v_exp_f32_e32 v39, v39
	v_exp_f32_e32 v40, v40
	v_exp_f32_e32 v41, v41
	v_pk_add_f32 v[46:47], v[46:47], 1.0 op_sel_hi:[1,0]
	v_pk_add_f32 v[48:49], v[48:49], 1.0 op_sel_hi:[1,0]
	v_pk_add_f32 v[38:39], v[38:39], 1.0 op_sel_hi:[1,0]
	v_pk_add_f32 v[40:41], v[40:41], 1.0 op_sel_hi:[1,0]
	v_rcp_f32_e32 v46, v46
	v_rcp_f32_e32 v47, v47
	v_rcp_f32_e32 v48, v48
	v_rcp_f32_e32 v49, v49
	v_rcp_f32_e32 v38, v38
	v_rcp_f32_e32 v39, v39
	v_rcp_f32_e32 v40, v40
	v_rcp_f32_e32 v41, v41
	v_pk_mul_f32 v[42:43], v[46:47], v[42:43]
	v_pk_mul_f32 v[44:45], v[48:49], v[44:45]
	v_pk_mul_f32 v[34:35], v[38:39], v[34:35]
	v_pk_mul_f32 v[36:37], v[40:41], v[36:37]
	v_cvt_pk_bf16_f32 v42, v42, v43
	v_cvt_pk_bf16_f32 v43, v44, v45
	v_cvt_pk_bf16_f32 v44, v34, v35
	v_cvt_pk_bf16_f32 v45, v36, v37
	global_store_dwordx4 v[50:51], v[42:45], off
	v_add_u32_e32 v34, 0xa0, v156
	v_mad_i64_i32 v[34:35], s[0:1], v34, s53, v[148:149]
	v_lshl_add_u64 v[34:35], v[34:35], 0, v[146:147]
	v_pk_mul_f32 v[26:27], v[30:31], v[26:27]
	v_pk_mul_f32 v[28:29], v[32:33], v[28:29]
	v_pk_mul_f32 v[18:19], v[22:23], v[18:19]
	v_pk_mul_f32 v[20:21], v[24:25], v[20:21]
	v_pk_mul_f32 v[30:31], v[30:31], v[160:161] op_sel_hi:[1,0]
	v_pk_mul_f32 v[32:33], v[32:33], v[160:161] op_sel_hi:[1,0]
	v_pk_mul_f32 v[22:23], v[22:23], v[160:161] op_sel_hi:[1,0]
	v_pk_mul_f32 v[24:25], v[24:25], v[160:161] op_sel_hi:[1,0]
	v_exp_f32_e32 v30, v30
	v_exp_f32_e32 v31, v31
	v_exp_f32_e32 v32, v32
	v_exp_f32_e32 v33, v33
	v_exp_f32_e32 v22, v22
	v_exp_f32_e32 v23, v23
	v_exp_f32_e32 v24, v24
	v_exp_f32_e32 v25, v25
	v_pk_add_f32 v[30:31], v[30:31], 1.0 op_sel_hi:[1,0]
	v_pk_add_f32 v[32:33], v[32:33], 1.0 op_sel_hi:[1,0]
	v_pk_add_f32 v[22:23], v[22:23], 1.0 op_sel_hi:[1,0]
	v_pk_add_f32 v[24:25], v[24:25], 1.0 op_sel_hi:[1,0]
	v_rcp_f32_e32 v30, v30
	v_rcp_f32_e32 v31, v31
	v_rcp_f32_e32 v32, v32
	v_rcp_f32_e32 v33, v33
	v_rcp_f32_e32 v22, v22
	v_rcp_f32_e32 v23, v23
	v_rcp_f32_e32 v24, v24
	v_rcp_f32_e32 v25, v25
	v_pk_mul_f32 v[26:27], v[30:31], v[26:27]
	v_pk_mul_f32 v[28:29], v[32:33], v[28:29]
	v_pk_mul_f32 v[18:19], v[22:23], v[18:19]
	v_pk_mul_f32 v[20:21], v[24:25], v[20:21]
	v_cvt_pk_bf16_f32 v26, v26, v27
	v_cvt_pk_bf16_f32 v27, v28, v29
	v_cvt_pk_bf16_f32 v28, v18, v19
	v_cvt_pk_bf16_f32 v29, v20, v21
	global_store_dwordx4 v[34:35], v[26:29], off
	v_add_u32_e32 v18, 0xb0, v156
	v_mad_i64_i32 v[18:19], s[0:1], v18, s53, v[148:149]
	v_lshl_add_u64 v[18:19], v[18:19], 0, v[146:147]
	s_andn2_b64 vcc, exec, s[2:3]
	s_mov_b64 s[0:1], -1
	v_pk_mul_f32 v[10:11], v[14:15], v[10:11]
	v_pk_mul_f32 v[12:13], v[16:17], v[12:13]
	v_pk_mul_f32 v[2:3], v[6:7], v[2:3]
	v_pk_mul_f32 v[4:5], v[8:9], v[4:5]
	v_pk_mul_f32 v[14:15], v[14:15], v[160:161] op_sel_hi:[1,0]
	v_pk_mul_f32 v[16:17], v[16:17], v[160:161] op_sel_hi:[1,0]
	v_pk_mul_f32 v[6:7], v[6:7], v[160:161] op_sel_hi:[1,0]
	v_pk_mul_f32 v[8:9], v[8:9], v[160:161] op_sel_hi:[1,0]
	v_exp_f32_e32 v14, v14
	v_exp_f32_e32 v15, v15
	v_exp_f32_e32 v16, v16
	v_exp_f32_e32 v17, v17
	v_exp_f32_e32 v6, v6
	v_exp_f32_e32 v7, v7
	v_exp_f32_e32 v8, v8
	v_exp_f32_e32 v9, v9
	v_pk_add_f32 v[14:15], v[14:15], 1.0 op_sel_hi:[1,0]
	v_pk_add_f32 v[16:17], v[16:17], 1.0 op_sel_hi:[1,0]
	v_pk_add_f32 v[6:7], v[6:7], 1.0 op_sel_hi:[1,0]
	v_pk_add_f32 v[8:9], v[8:9], 1.0 op_sel_hi:[1,0]
	v_rcp_f32_e32 v14, v14
	v_rcp_f32_e32 v15, v15
	v_rcp_f32_e32 v16, v16
	v_rcp_f32_e32 v17, v17
	v_rcp_f32_e32 v6, v6
	v_rcp_f32_e32 v7, v7
	v_rcp_f32_e32 v8, v8
	v_rcp_f32_e32 v9, v9
	v_pk_mul_f32 v[10:11], v[14:15], v[10:11]
	v_pk_mul_f32 v[12:13], v[16:17], v[12:13]
	v_pk_mul_f32 v[2:3], v[6:7], v[2:3]
	v_pk_mul_f32 v[4:5], v[8:9], v[4:5]
	v_cvt_pk_bf16_f32 v10, v10, v11
	v_cvt_pk_bf16_f32 v11, v12, v13
	v_cvt_pk_bf16_f32 v12, v2, v3
	v_cvt_pk_bf16_f32 v13, v4, v5
	global_store_dwordx4 v[18:19], v[10:13], off
	s_cbranch_vccnz .LBB0_3831
	s_andn2_b64 vcc, exec, s[6:7]
	s_cbranch_vccnz .LBB0_3830
	s_barrier
	s_branch .LBB0_3830
